# K loops: LDS-DMA loads rebalanced 2/6/2/6 -> 4/4/4/4 per segment (A(1,0) piece moved to next segment A, A(0,0) piece to segment C), counted waits re-derived (6 where two fewer loads precede)
# speedup vs baseline: 1.0105x; 1.0105x over previous
; #define PG8_STAGE(bufoff, gbase, voff) do { _Pragma("unroll") for (int _i = 0; _i < 2; ++_i) \
;         __builtin_amdgcn_global_load_lds((const unsigned*)((const char*)(gbase) + (voff)[_i]), (LAS unsigned*)(lds + (bufoff) + ldsw + _i * 8192), 16, 0, ((voff) == voffA ? AUXA : 0)); } while (0)
; #define PG8_LDA(dst, b, h) do { _Pragma("unroll") for (int m = 0; m < 4; ++m) _Pragma("unroll") for (int k = 0; k < 2; ++k) dst[m][k] = *(const LAS bf16x8*)(lds + PG8_SA(b, h) + aoff + m * 2048 + k * 1024); } while (0)
; #define PG8_LDB(dst, b, h) do { _Pragma("unroll") for (int n = 0; n < 2; ++n) _Pragma("unroll") for (int k = 0; k < 2; ++k) dst[n][k] = *(const LAS bf16x8*)(lds + PG8_SB(b, h) + boff + n * 2048 + k * 1024); } while (0)
; #define PG8_MMA(ai, bj, At, Bt) do { __builtin_amdgcn_s_setprio(1); _Pragma("unroll") for (int m = 0; m < 4; ++m) _Pragma("unroll") for (int n = 0; n < 2; ++n) _Pragma("unroll") for (int k = 0; k < 2; ++k) \
;         acc[ai][bj][m][n] = __builtin_amdgcn_mfma_f32_16x16x32_bf16(Bt[n][k], At[m][k], acc[ai][bj][m][n], 0, 0, 0); __builtin_amdgcn_s_setprio(0); } while (0)
; #define PG8_WAIT_V(n) asm volatile("s_waitcnt vmcnt(" #n ")" ::: "memory")
; #define PG8_WAIT_L(n) asm volatile("s_waitcnt lgkmcnt(" #n ")" ::: "memory")
; #define PG8_BAR __builtin_amdgcn_s_barrier()
; #define PG8_SCHED __builtin_amdgcn_sched_barrier(0)
;     ...
;             PG8_LDA(At, 0, 1); PG8_STAGE(PG8_SB(0, 0), b2, voffB); PG8_STAGE(PG8_SB(0, 1), b2 + hsB, voffB); PG8_STAGE(PG8_SA(0, 0), a2, voffA);
;             if (Epi::NPRE != 0 && last) { PG8_WAIT_V(16); } else { PG8_WAIT_V(8); }
;             PG8_WAIT_L(0); PG8_BAR; PG8_MMA(1, 0, At, B0); PG8_MMA(1, 1, At, B1); PG8_BAR; PG8_SCHED;
;             PG8_LDB(B0, 1, 0); PG8_LDB(B1, 1, 1); PG8_SCHED; PG8_LDA(At, 1, 0); PG8_STAGE(PG8_SA(0, 1), a2 + hsA, voffA);
;             PG8_WAIT_V(8); PG8_WAIT_L(0); PG8_BAR; PG8_MMA(0, 0, At, B0); PG8_MMA(0, 1, At, B1); PG8_BAR; PG8_SCHED;
.LBB0_148:
	s_waitcnt lgkmcnt(0)
	s_add_i32 s61, s61, 2
	s_setprio 1
	s_barrier
	v_mfma_f32_16x16x32_bf16 v[60:63], v[144:147], v[184:187], v[60:63]
	v_mfma_f32_16x16x32_bf16 v[52:55], v[152:155], v[184:187], v[52:55]
	v_mfma_f32_16x16x32_bf16 v[44:47], v[144:147], v[176:179], v[44:47]
	v_mfma_f32_16x16x32_bf16 v[36:39], v[152:155], v[176:179], v[36:39]
	v_mfma_f32_16x16x32_bf16 v[28:31], v[144:147], v[168:171], v[28:31]
	v_mfma_f32_16x16x32_bf16 v[20:23], v[152:155], v[168:171], v[20:23]
	v_mfma_f32_16x16x32_bf16 v[12:15], v[144:147], v[160:163], v[12:15]
	v_mfma_f32_16x16x32_bf16 v[4:7], v[152:155], v[160:163], v[4:7]
	v_mfma_f32_16x16x32_bf16 v[60:63], v[148:151], v[188:191], v[60:63]
	v_mfma_f32_16x16x32_bf16 v[52:55], v[156:159], v[188:191], v[52:55]
	v_mfma_f32_16x16x32_bf16 v[44:47], v[148:151], v[180:183], v[44:47]
	v_mfma_f32_16x16x32_bf16 v[36:39], v[156:159], v[180:183], v[36:39]
	v_mfma_f32_16x16x32_bf16 v[28:31], v[148:151], v[172:175], v[28:31]
	v_mfma_f32_16x16x32_bf16 v[20:23], v[156:159], v[172:175], v[20:23]
	v_mfma_f32_16x16x32_bf16 v[12:15], v[148:151], v[164:167], v[12:15]
	v_mfma_f32_16x16x32_bf16 v[4:7], v[156:159], v[164:167], v[4:7]
	v_mfma_f32_16x16x32_bf16 v[56:59], v[128:131], v[184:187], v[56:59]
	v_mfma_f32_16x16x32_bf16 v[48:51], v[136:139], v[184:187], v[48:51]
	v_mfma_f32_16x16x32_bf16 v[40:43], v[128:131], v[176:179], v[40:43]
	v_mfma_f32_16x16x32_bf16 v[32:35], v[136:139], v[176:179], v[32:35]
	v_mfma_f32_16x16x32_bf16 v[24:27], v[128:131], v[168:171], v[24:27]
	v_mfma_f32_16x16x32_bf16 v[16:19], v[136:139], v[168:171], v[16:19]
	v_mfma_f32_16x16x32_bf16 v[8:11], v[128:131], v[160:163], v[8:11]
	v_mfma_f32_16x16x32_bf16 v[0:3], v[136:139], v[160:163], v[0:3]
	v_mfma_f32_16x16x32_bf16 v[56:59], v[132:135], v[188:191], v[56:59]
	v_mfma_f32_16x16x32_bf16 v[48:51], v[140:143], v[188:191], v[48:51]
	v_mfma_f32_16x16x32_bf16 v[40:43], v[132:135], v[180:183], v[40:43]
	v_mfma_f32_16x16x32_bf16 v[32:35], v[140:143], v[180:183], v[32:35]
	v_mfma_f32_16x16x32_bf16 v[24:27], v[132:135], v[172:175], v[24:27]
	v_mfma_f32_16x16x32_bf16 v[16:19], v[140:143], v[172:175], v[16:19]
	v_mfma_f32_16x16x32_bf16 v[8:11], v[132:135], v[164:167], v[8:11]
	v_mfma_f32_16x16x32_bf16 v[0:3], v[140:143], v[164:167], v[0:3]
	s_barrier
	s_mov_b32 m0, s40
	s_nop 0
	global_load_lds_dwordx4 v200, s[34:35]
	s_mov_b32 m0, s45
	s_nop 0
	global_load_lds_dwordx4 v196, s[34:35]
	s_setprio 0
	s_add_i32 s36, 0, 0x18000
	s_add_i32 s37, 0, 0x1c000
	v_add_u32_e32 v140, s36, v222
	v_add_u32_e32 v156, s37, v222
	ds_read_b128 v[128:131], v140
	ds_read_b128 v[132:135], v140 offset:1024
	ds_read_b128 v[136:139], v140 offset:2048
	ds_read_b128 v[140:143], v140 offset:3072
	ds_read_b128 v[144:147], v156
	ds_read_b128 v[148:151], v156 offset:1024
	ds_read_b128 v[152:155], v156 offset:2048
	ds_read_b128 v[156:159], v156 offset:3072
	s_add_u32 s34, s34, 0x80000
	s_addc_u32 s35, s35, 0
	s_mov_b32 m0, s46
	ds_read_b128 v[160:163], v226 offset:32768
	ds_read_b128 v[164:167], v226 offset:33792
	ds_read_b128 v[168:171], v226 offset:34816
	ds_read_b128 v[172:175], v226 offset:35840
	ds_read_b128 v[176:179], v226 offset:36864
	ds_read_b128 v[180:183], v226 offset:37888
	ds_read_b128 v[184:187], v226 offset:38912
	ds_read_b128 v[188:191], v226 offset:39936
	global_load_lds_dwordx4 v200, s[34:35]
	s_mov_b32 m0, s47
	s_nop 0
	global_load_lds_dwordx4 v196, s[34:35]
	s_waitcnt vmcnt(8)
	s_waitcnt lgkmcnt(0)
	s_setprio 1
	s_barrier
	v_mfma_f32_16x16x32_bf16 v[124:127], v[128:131], v[160:163], v[124:127]
	v_mfma_f32_16x16x32_bf16 v[116:119], v[136:139], v[160:163], v[116:119]
	v_mfma_f32_16x16x32_bf16 v[108:111], v[128:131], v[168:171], v[108:111]
	v_mfma_f32_16x16x32_bf16 v[100:103], v[136:139], v[168:171], v[100:103]
	v_mfma_f32_16x16x32_bf16 v[92:95], v[128:131], v[176:179], v[92:95]
	v_mfma_f32_16x16x32_bf16 v[84:87], v[136:139], v[176:179], v[84:87]
	v_mfma_f32_16x16x32_bf16 v[76:79], v[128:131], v[184:187], v[76:79]
	v_mfma_f32_16x16x32_bf16 v[68:71], v[136:139], v[184:187], v[68:71]
	v_mfma_f32_16x16x32_bf16 v[124:127], v[132:135], v[164:167], v[124:127]
	v_mfma_f32_16x16x32_bf16 v[116:119], v[140:143], v[164:167], v[116:119]
	v_mfma_f32_16x16x32_bf16 v[108:111], v[132:135], v[172:175], v[108:111]
	v_mfma_f32_16x16x32_bf16 v[100:103], v[140:143], v[172:175], v[100:103]
	v_mfma_f32_16x16x32_bf16 v[92:95], v[132:135], v[180:183], v[92:95]
	v_mfma_f32_16x16x32_bf16 v[84:87], v[140:143], v[180:183], v[84:87]
	v_mfma_f32_16x16x32_bf16 v[76:79], v[132:135], v[188:191], v[76:79]
	v_mfma_f32_16x16x32_bf16 v[68:71], v[140:143], v[188:191], v[68:71]
	v_mfma_f32_16x16x32_bf16 v[120:123], v[144:147], v[160:163], v[120:123]
	v_mfma_f32_16x16x32_bf16 v[112:115], v[152:155], v[160:163], v[112:115]
	v_mfma_f32_16x16x32_bf16 v[104:107], v[144:147], v[168:171], v[104:107]
	v_mfma_f32_16x16x32_bf16 v[96:99], v[152:155], v[168:171], v[96:99]
	v_mfma_f32_16x16x32_bf16 v[88:91], v[144:147], v[176:179], v[88:91]
	v_mfma_f32_16x16x32_bf16 v[80:83], v[152:155], v[176:179], v[80:83]
	v_mfma_f32_16x16x32_bf16 v[72:75], v[144:147], v[184:187], v[72:75]
	v_mfma_f32_16x16x32_bf16 v[64:67], v[152:155], v[184:187], v[64:67]
	v_mfma_f32_16x16x32_bf16 v[120:123], v[148:151], v[164:167], v[120:123]
	v_mfma_f32_16x16x32_bf16 v[112:115], v[156:159], v[164:167], v[112:115]
	v_mfma_f32_16x16x32_bf16 v[104:107], v[148:151], v[172:175], v[104:107]
	v_mfma_f32_16x16x32_bf16 v[96:99], v[156:159], v[172:175], v[96:99]
	v_mfma_f32_16x16x32_bf16 v[88:91], v[148:151], v[180:183], v[88:91]
	v_mfma_f32_16x16x32_bf16 v[80:83], v[156:159], v[180:183], v[80:83]
	v_mfma_f32_16x16x32_bf16 v[72:75], v[148:151], v[188:191], v[72:75]
	v_mfma_f32_16x16x32_bf16 v[64:67], v[156:159], v[188:191], v[64:67]
	s_barrier
; #define PG8_STAGE(bufoff, gbase, voff) do { _Pragma("unroll") for (int _i = 0; _i < 2; ++_i) \
;         __builtin_amdgcn_global_load_lds((const unsigned*)((const char*)(gbase) + (voff)[_i]), (LAS unsigned*)(lds + (bufoff) + ldsw + _i * 8192), 16, 0, ((voff) == voffA ? AUXA : 0)); } while (0)
; #define PG8_LDA(dst, b, h) do { _Pragma("unroll") for (int m = 0; m < 4; ++m) _Pragma("unroll") for (int k = 0; k < 2; ++k) dst[m][k] = *(const LAS bf16x8*)(lds + PG8_SA(b, h) + aoff + m * 2048 + k * 1024); } while (0)
; #define PG8_LDB(dst, b, h) do { _Pragma("unroll") for (int n = 0; n < 2; ++n) _Pragma("unroll") for (int k = 0; k < 2; ++k) dst[n][k] = *(const LAS bf16x8*)(lds + PG8_SB(b, h) + boff + n * 2048 + k * 1024); } while (0)
; #define PG8_MMA(ai, bj, At, Bt) do { __builtin_amdgcn_s_setprio(1); _Pragma("unroll") for (int m = 0; m < 4; ++m) _Pragma("unroll") for (int n = 0; n < 2; ++n) _Pragma("unroll") for (int k = 0; k < 2; ++k) \
;         acc[ai][bj][m][n] = __builtin_amdgcn_mfma_f32_16x16x32_bf16(Bt[n][k], At[m][k], acc[ai][bj][m][n], 0, 0, 0); __builtin_amdgcn_s_setprio(0); } while (0)
; #define PG8_WAIT_V(n) asm volatile("s_waitcnt vmcnt(" #n ")" ::: "memory")
; #define PG8_WAIT_L(n) asm volatile("s_waitcnt lgkmcnt(" #n ")" ::: "memory")
; #define PG8_BAR __builtin_amdgcn_s_barrier()
; #define PG8_SCHED __builtin_amdgcn_sched_barrier(0)
;     ...
;             PG8_LDB(B0, 0, 0); PG8_LDB(B1, 0, 1); PG8_SCHED; PG8_LDA(At, 0, 0); PG8_STAGE(PG8_SA(1, 1), a1 + hsA, voffA);
;             if (Epi::NPRE != 0 && last) { E.pre(sv, cur, wr, fr); PG8_WAIT_V(16); } else { PG8_WAIT_V(8); }
;     ...
;             PG8_LDA(At, 1, 1); PG8_STAGE(PG8_SB(1, 0), b3, voffB); PG8_STAGE(PG8_SB(1, 1), b3 + hsB, voffB); PG8_STAGE(PG8_SA(1, 0), a3, voffA);
;             PG8_WAIT_V(8); PG8_WAIT_L(0); PG8_BAR; PG8_MMA(1, 0, At, B0); PG8_MMA(1, 1, At, B1); PG8_BAR; PG8_SCHED;
	s_setprio 0
	s_add_i32 s34, s36, s3
	s_mov_b32 m0, s34
	ds_read_b128 v[160:163], v226 offset:49152
	ds_read_b128 v[164:167], v226 offset:50176
	ds_read_b128 v[168:171], v226 offset:51200
	ds_read_b128 v[172:175], v226 offset:52224
	ds_read_b128 v[176:179], v226 offset:53248
	ds_read_b128 v[180:183], v226 offset:54272
	ds_read_b128 v[184:187], v226 offset:55296
	ds_read_b128 v[188:191], v226 offset:56320
	global_load_lds_dwordx4 v198, s[98:99]
	s_add_i32 m0, s34, 0x2000
	s_add_u32 s30, s30, 0x80080
	s_addc_u32 s31, s31, 0
	s_add_i32 s34, s37, s3
	global_load_lds_dwordx4 v194, s[98:99]
	s_mov_b32 m0, s34
	s_nop 0
	global_load_lds_dwordx4 v198, s[30:31]
	s_add_i32 m0, s34, 0x2000
	s_nop 0
	global_load_lds_dwordx4 v194, s[30:31]
	s_waitcnt vmcnt(6)
	s_waitcnt lgkmcnt(0)
	s_setprio 1
	s_barrier
	v_mfma_f32_16x16x32_bf16 v[60:63], v[128:131], v[160:163], v[60:63]
	v_mfma_f32_16x16x32_bf16 v[52:55], v[136:139], v[160:163], v[52:55]
	v_mfma_f32_16x16x32_bf16 v[44:47], v[128:131], v[168:171], v[44:47]
	v_mfma_f32_16x16x32_bf16 v[36:39], v[136:139], v[168:171], v[36:39]
	v_mfma_f32_16x16x32_bf16 v[28:31], v[128:131], v[176:179], v[28:31]
	v_mfma_f32_16x16x32_bf16 v[20:23], v[136:139], v[176:179], v[20:23]
	v_mfma_f32_16x16x32_bf16 v[12:15], v[128:131], v[184:187], v[12:15]
	v_mfma_f32_16x16x32_bf16 v[4:7], v[136:139], v[184:187], v[4:7]
	v_mfma_f32_16x16x32_bf16 v[60:63], v[132:135], v[164:167], v[60:63]
	v_mfma_f32_16x16x32_bf16 v[52:55], v[140:143], v[164:167], v[52:55]
	v_mfma_f32_16x16x32_bf16 v[44:47], v[132:135], v[172:175], v[44:47]
	v_mfma_f32_16x16x32_bf16 v[36:39], v[140:143], v[172:175], v[36:39]
	v_mfma_f32_16x16x32_bf16 v[28:31], v[132:135], v[180:183], v[28:31]
	v_mfma_f32_16x16x32_bf16 v[20:23], v[140:143], v[180:183], v[20:23]
	v_mfma_f32_16x16x32_bf16 v[12:15], v[132:135], v[188:191], v[12:15]
	v_mfma_f32_16x16x32_bf16 v[4:7], v[140:143], v[188:191], v[4:7]
	v_mfma_f32_16x16x32_bf16 v[56:59], v[144:147], v[160:163], v[56:59]
	v_mfma_f32_16x16x32_bf16 v[48:51], v[152:155], v[160:163], v[48:51]
	v_mfma_f32_16x16x32_bf16 v[40:43], v[144:147], v[168:171], v[40:43]
	v_mfma_f32_16x16x32_bf16 v[32:35], v[152:155], v[168:171], v[32:35]
	v_mfma_f32_16x16x32_bf16 v[24:27], v[144:147], v[176:179], v[24:27]
	v_mfma_f32_16x16x32_bf16 v[16:19], v[152:155], v[176:179], v[16:19]
	v_mfma_f32_16x16x32_bf16 v[8:11], v[144:147], v[184:187], v[8:11]
	v_mfma_f32_16x16x32_bf16 v[0:3], v[152:155], v[184:187], v[0:3]
	v_mfma_f32_16x16x32_bf16 v[56:59], v[148:151], v[164:167], v[56:59]
	v_mfma_f32_16x16x32_bf16 v[48:51], v[156:159], v[164:167], v[48:51]
	v_mfma_f32_16x16x32_bf16 v[40:43], v[148:151], v[172:175], v[40:43]
	v_mfma_f32_16x16x32_bf16 v[32:35], v[156:159], v[172:175], v[32:35]
	v_mfma_f32_16x16x32_bf16 v[24:27], v[148:151], v[180:183], v[24:27]
	v_mfma_f32_16x16x32_bf16 v[16:19], v[156:159], v[180:183], v[16:19]
	v_mfma_f32_16x16x32_bf16 v[8:11], v[148:151], v[188:191], v[8:11]
	v_mfma_f32_16x16x32_bf16 v[0:3], v[156:159], v[188:191], v[0:3]
	s_barrier
	s_setprio 0
	s_add_u32 s28, s28, 0x100
	s_addc_u32 s29, s29, 0
	s_add_u32 s59, s59, 0x100
	s_addc_u32 s60, s60, 0
	s_cmp_ge_i32 s61, s49
	s_cbranch_scc1 .LBB0_158
.LBB0_149:
	s_add_u32 s98, s28, 0xfff80000
	s_addc_u32 s99, s29, -1
	s_mov_b32 m0, s50
	s_nop 0
	global_load_lds_dwordx4 v200, s[98:99]
	s_mov_b32 m0, s51
	s_nop 0
	global_load_lds_dwordx4 v196, s[98:99]
	ds_read_b128 v[144:147], v224
	ds_read_b128 v[148:151], v224 offset:1024
	ds_read_b128 v[152:155], v224 offset:2048
	ds_read_b128 v[156:159], v224 offset:3072
	ds_read_b128 v[128:131], v225
	ds_read_b128 v[132:135], v225 offset:1024
	ds_read_b128 v[136:139], v225 offset:2048
	ds_read_b128 v[140:143], v225 offset:3072
	s_cmp_eq_u32 s52, s61
	s_cselect_b64 s[30:31], -1, 0
	s_cmp_lg_u32 s52, s61
	s_cselect_b64 s[36:37], -1, 0
	s_add_i32 m0, s40, 0xc000
	ds_read_b128 v[184:187], v226
	ds_read_b128 v[188:191], v226 offset:1024
	ds_read_b128 v[176:179], v226 offset:2048
	ds_read_b128 v[180:183], v226 offset:3072
	ds_read_b128 v[168:171], v226 offset:4096
	ds_read_b128 v[172:175], v226 offset:5120
	ds_read_b128 v[160:163], v226 offset:6144
	ds_read_b128 v[164:167], v226 offset:7168
	global_load_lds_dwordx4 v202, s[28:29]
	s_add_i32 m0, s40, 0xe000
	s_mov_b64 s[34:35], -1
	global_load_lds_dwordx4 v204, s[28:29]
	s_and_b64 vcc, exec, s[36:37]
	s_cbranch_vccz .LBB0_151
	s_waitcnt vmcnt(8)
	s_mov_b64 s[34:35], 0

; #define PG8_STAGE(bufoff, gbase, voff) do { _Pragma("unroll") for (int _i = 0; _i < 2; ++_i) \
;         __builtin_amdgcn_global_load_lds((const unsigned*)((const char*)(gbase) + (voff)[_i]), (LAS unsigned*)(lds + (bufoff) + ldsw + _i * 8192), 16, 0, ((voff) == voffA ? AUXA : 0)); } while (0)
; #define PG8_LDA(dst, b, h) do { _Pragma("unroll") for (int m = 0; m < 4; ++m) _Pragma("unroll") for (int k = 0; k < 2; ++k) dst[m][k] = *(const LAS bf16x8*)(lds + PG8_SA(b, h) + aoff + m * 2048 + k * 1024); } while (0)
; #define PG8_LDB(dst, b, h) do { _Pragma("unroll") for (int n = 0; n < 2; ++n) _Pragma("unroll") for (int k = 0; k < 2; ++k) dst[n][k] = *(const LAS bf16x8*)(lds + PG8_SB(b, h) + boff + n * 2048 + k * 1024); } while (0)
; #define PG8_MMA(ai, bj, At, Bt) do { __builtin_amdgcn_s_setprio(1); _Pragma("unroll") for (int m = 0; m < 4; ++m) _Pragma("unroll") for (int n = 0; n < 2; ++n) _Pragma("unroll") for (int k = 0; k < 2; ++k) \
;         acc[ai][bj][m][n] = __builtin_amdgcn_mfma_f32_16x16x32_bf16(Bt[n][k], At[m][k], acc[ai][bj][m][n], 0, 0, 0); __builtin_amdgcn_s_setprio(0); } while (0)
; #define PG8_WAIT_V(n) asm volatile("s_waitcnt vmcnt(" #n ")" ::: "memory")
; #define PG8_WAIT_L(n) asm volatile("s_waitcnt lgkmcnt(" #n ")" ::: "memory")
; #define PG8_BAR __builtin_amdgcn_s_barrier()
; #define PG8_SCHED __builtin_amdgcn_sched_barrier(0)
;     ...
;             const char* a2 = last ? nA : cA + (size_t)(t + 2) * kstep; const char* b2 = last ? nB : cB + (size_t)(t + 2) * kstep;
;             const char* a3 = a2 + kstep; const char* b3 = b2 + kstep;
;             PG8_LDB(B0, 0, 0); PG8_LDB(B1, 0, 1); PG8_SCHED; PG8_LDA(At, 0, 0); PG8_STAGE(PG8_SA(1, 1), a1 + hsA, voffA);
;             if (Epi::NPRE != 0 && last) { E.pre(sv, cur, wr, fr); PG8_WAIT_V(16); } else { PG8_WAIT_V(8); }
;             PG8_WAIT_L(0); PG8_BAR; PG8_MMA(0, 0, At, B0); PG8_MMA(0, 1, At, B1); PG8_BAR; PG8_SCHED;
;             PG8_LDA(At, 0, 1); PG8_STAGE(PG8_SB(0, 0), b2, voffB); PG8_STAGE(PG8_SB(0, 1), b2 + hsB, voffB); PG8_STAGE(PG8_SA(0, 0), a2, voffA);
;             if (Epi::NPRE != 0 && last) { PG8_WAIT_V(16); } else { PG8_WAIT_V(8); }
.LBB0_153:
	s_add_u32 s34, s28, 0xfff80080
	s_addc_u32 s35, s29, -1
	s_waitcnt lgkmcnt(0)
	s_and_b64 s[30:31], s[30:31], exec
	s_cselect_b32 s35, s21, s35
	s_cselect_b32 s34, s23, s34
	s_cselect_b32 s31, s57, s60
	s_cselect_b32 s30, s58, s59
	s_setprio 1
	s_barrier
	v_mfma_f32_16x16x32_bf16 v[124:127], v[144:147], v[184:187], v[124:127]
	v_mfma_f32_16x16x32_bf16 v[116:119], v[152:155], v[184:187], v[116:119]
	v_mfma_f32_16x16x32_bf16 v[108:111], v[144:147], v[176:179], v[108:111]
	v_mfma_f32_16x16x32_bf16 v[100:103], v[152:155], v[176:179], v[100:103]
	v_mfma_f32_16x16x32_bf16 v[92:95], v[144:147], v[168:171], v[92:95]
	v_mfma_f32_16x16x32_bf16 v[84:87], v[152:155], v[168:171], v[84:87]
	v_mfma_f32_16x16x32_bf16 v[76:79], v[144:147], v[160:163], v[76:79]
	v_mfma_f32_16x16x32_bf16 v[68:71], v[152:155], v[160:163], v[68:71]
	v_mfma_f32_16x16x32_bf16 v[124:127], v[148:151], v[188:191], v[124:127]
	v_mfma_f32_16x16x32_bf16 v[116:119], v[156:159], v[188:191], v[116:119]
	v_mfma_f32_16x16x32_bf16 v[108:111], v[148:151], v[180:183], v[108:111]
	v_mfma_f32_16x16x32_bf16 v[100:103], v[156:159], v[180:183], v[100:103]
	v_mfma_f32_16x16x32_bf16 v[92:95], v[148:151], v[172:175], v[92:95]
	v_mfma_f32_16x16x32_bf16 v[84:87], v[156:159], v[172:175], v[84:87]
	v_mfma_f32_16x16x32_bf16 v[76:79], v[148:151], v[164:167], v[76:79]
	v_mfma_f32_16x16x32_bf16 v[68:71], v[156:159], v[164:167], v[68:71]
	v_mfma_f32_16x16x32_bf16 v[120:123], v[128:131], v[184:187], v[120:123]
	v_mfma_f32_16x16x32_bf16 v[112:115], v[136:139], v[184:187], v[112:115]
	v_mfma_f32_16x16x32_bf16 v[104:107], v[128:131], v[176:179], v[104:107]
	v_mfma_f32_16x16x32_bf16 v[96:99], v[136:139], v[176:179], v[96:99]
	v_mfma_f32_16x16x32_bf16 v[88:91], v[128:131], v[168:171], v[88:91]
	v_mfma_f32_16x16x32_bf16 v[80:83], v[136:139], v[168:171], v[80:83]
	v_mfma_f32_16x16x32_bf16 v[72:75], v[128:131], v[160:163], v[72:75]
	v_mfma_f32_16x16x32_bf16 v[64:67], v[136:139], v[160:163], v[64:67]
	v_mfma_f32_16x16x32_bf16 v[120:123], v[132:135], v[188:191], v[120:123]
	v_mfma_f32_16x16x32_bf16 v[112:115], v[140:143], v[188:191], v[112:115]
	v_mfma_f32_16x16x32_bf16 v[104:107], v[132:135], v[180:183], v[104:107]
	v_mfma_f32_16x16x32_bf16 v[96:99], v[140:143], v[180:183], v[96:99]
	v_mfma_f32_16x16x32_bf16 v[88:91], v[132:135], v[172:175], v[88:91]
	v_mfma_f32_16x16x32_bf16 v[80:83], v[140:143], v[172:175], v[80:83]
	v_mfma_f32_16x16x32_bf16 v[72:75], v[132:135], v[164:167], v[72:75]
	v_mfma_f32_16x16x32_bf16 v[64:67], v[140:143], v[164:167], v[64:67]
	s_barrier
	s_setprio 0
	s_add_u32 s98, s30, s16
	s_addc_u32 s99, s31, s17
	s_add_u32 s100, s34, s16
	s_addc_u32 s101, s35, s17
	s_mov_b32 m0, s41
	s_add_u32 s38, s30, 0x80000
	ds_read_b128 v[184:187], v226 offset:16384
	ds_read_b128 v[188:191], v226 offset:17408
	ds_read_b128 v[176:179], v226 offset:18432
	ds_read_b128 v[180:183], v226 offset:19456
	ds_read_b128 v[168:171], v226 offset:20480
	ds_read_b128 v[172:175], v226 offset:21504
	ds_read_b128 v[160:163], v226 offset:22528
	ds_read_b128 v[164:167], v226 offset:23552
	global_load_lds_dwordx4 v198, s[30:31]
	s_mov_b32 m0, s42
	s_addc_u32 s39, s31, 0
	global_load_lds_dwordx4 v194, s[30:31]
	s_mov_b32 m0, s43
	s_nop 0
	global_load_lds_dwordx4 v198, s[38:39]
	s_mov_b32 m0, s44
	s_nop 0
	global_load_lds_dwordx4 v194, s[38:39]
	s_mov_b64 s[38:39], -1
	s_and_b64 vcc, exec, s[36:37]
	s_cbranch_vccz .LBB0_155
	s_waitcnt vmcnt(6)
	s_mov_b64 s[38:39], 0
.LBB0_155:
	s_andn2_b64 vcc, exec, s[38:39]
	s_cbranch_vccnz .LBB0_148
	s_waitcnt vmcnt(14)
	s_branch .LBB0_148

; #define PG8_STAGE(bufoff, gbase, voff) do { _Pragma("unroll") for (int _i = 0; _i < 2; ++_i) \
;         __builtin_amdgcn_global_load_lds((const unsigned*)((const char*)(gbase) + (voff)[_i]), (LAS unsigned*)(lds + (bufoff) + ldsw + _i * 8192), 16, 0, ((voff) == voffA ? AUXA : 0)); } while (0)
; #define PG8_LDA(dst, b, h) do { _Pragma("unroll") for (int m = 0; m < 4; ++m) _Pragma("unroll") for (int k = 0; k < 2; ++k) dst[m][k] = *(const LAS bf16x8*)(lds + PG8_SA(b, h) + aoff + m * 2048 + k * 1024); } while (0)
; #define PG8_LDB(dst, b, h) do { _Pragma("unroll") for (int n = 0; n < 2; ++n) _Pragma("unroll") for (int k = 0; k < 2; ++k) dst[n][k] = *(const LAS bf16x8*)(lds + PG8_SB(b, h) + boff + n * 2048 + k * 1024); } while (0)
; #define PG8_MMA(ai, bj, At, Bt) do { __builtin_amdgcn_s_setprio(1); _Pragma("unroll") for (int m = 0; m < 4; ++m) _Pragma("unroll") for (int n = 0; n < 2; ++n) _Pragma("unroll") for (int k = 0; k < 2; ++k) \
;         acc[ai][bj][m][n] = __builtin_amdgcn_mfma_f32_16x16x32_bf16(Bt[n][k], At[m][k], acc[ai][bj][m][n], 0, 0, 0); __builtin_amdgcn_s_setprio(0); } while (0)
; #define PG8_WAIT_V(n) asm volatile("s_waitcnt vmcnt(" #n ")" ::: "memory")
; #define PG8_WAIT_L(n) asm volatile("s_waitcnt lgkmcnt(" #n ")" ::: "memory")
; #define PG8_BAR __builtin_amdgcn_s_barrier()
; #define PG8_SCHED __builtin_amdgcn_sched_barrier(0)
;     ...
;             const char* a2 = last ? nA : cA + (size_t)(t + 2) * kstep; const char* b2 = last ? nB : cB + (size_t)(t + 2) * kstep;
;             const char* a3 = a2 + kstep; const char* b3 = b2 + kstep;
;             PG8_LDB(B0, 0, 0); PG8_LDB(B1, 0, 1); PG8_SCHED; PG8_LDA(At, 0, 0); PG8_STAGE(PG8_SA(1, 1), a1 + hsA, voffA);
;             if (Epi::NPRE != 0 && last) { E.pre(sv, cur, wr, fr); PG8_WAIT_V(16); } else { PG8_WAIT_V(8); }
;             PG8_WAIT_L(0); PG8_BAR; PG8_MMA(0, 0, At, B0); PG8_MMA(0, 1, At, B1); PG8_BAR; PG8_SCHED;
;             PG8_LDA(At, 0, 1); PG8_STAGE(PG8_SB(0, 0), b2, voffB); PG8_STAGE(PG8_SB(0, 1), b2 + hsB, voffB); PG8_STAGE(PG8_SA(0, 0), a2, voffA);
;             if (Epi::NPRE != 0 && last) { PG8_WAIT_V(16); } else { PG8_WAIT_V(8); }
;             PG8_WAIT_L(0); PG8_BAR; PG8_MMA(1, 0, At, B0); PG8_MMA(1, 1, At, B1); PG8_BAR; PG8_SCHED;
.LBB0_246:
	s_add_u32 s98, s24, 0xffea0000
	s_addc_u32 s99, s25, -1
	s_mov_b32 m0, s39
	s_nop 0
	global_load_lds_dwordx4 v128, s[98:99]
	s_mov_b32 m0, s40
	s_nop 0
	global_load_lds_dwordx4 v132, s[98:99]
	ds_read_b128 v[144:147], v208
	ds_read_b128 v[148:151], v208 offset:1024
	ds_read_b128 v[152:155], v208 offset:2048
	ds_read_b128 v[156:159], v208 offset:3072
	ds_read_b128 v[160:163], v209
	ds_read_b128 v[164:167], v209 offset:1024
	ds_read_b128 v[168:171], v209 offset:2048
	ds_read_b128 v[172:175], v209 offset:3072
	s_add_i32 s52, s26, 2
	s_add_u32 s27, s24, 0xffea0080
	s_addc_u32 s28, s25, -1
	s_cmp_eq_u32 s41, s26
	s_cselect_b32 s26, s22, s50
	s_cselect_b32 s29, s11, s28
	s_cselect_b32 s28, s10, s27
	s_cselect_b32 s27, s23, s51
	s_add_i32 m0, s30, 0xc000
	ds_read_b128 v[176:179], v210
	ds_read_b128 v[180:183], v210 offset:1024
	ds_read_b128 v[184:187], v210 offset:2048
	ds_read_b128 v[188:191], v210 offset:3072
	ds_read_b128 v[194:197], v210 offset:4096
	ds_read_b128 v[198:201], v210 offset:5120
	ds_read_b128 v[202:205], v210 offset:6144
	ds_read_b128 v[212:215], v210 offset:7168
	global_load_lds_dwordx4 v136, s[24:25]
	s_add_i32 m0, s30, 0xe000
	s_nop 0
	global_load_lds_dwordx4 v138, s[24:25]
	s_waitcnt vmcnt(8)
	s_waitcnt lgkmcnt(0)
	s_setprio 1
	s_barrier
	v_mfma_f32_16x16x32_bf16 v[124:127], v[144:147], v[176:179], v[124:127]
	v_mfma_f32_16x16x32_bf16 v[120:123], v[152:155], v[176:179], v[120:123]
	v_mfma_f32_16x16x32_bf16 v[116:119], v[144:147], v[184:187], v[116:119]
	v_mfma_f32_16x16x32_bf16 v[112:115], v[152:155], v[184:187], v[112:115]
	v_mfma_f32_16x16x32_bf16 v[104:107], v[144:147], v[194:197], v[104:107]
	v_mfma_f32_16x16x32_bf16 v[96:99], v[152:155], v[194:197], v[96:99]
	v_mfma_f32_16x16x32_bf16 v[88:91], v[144:147], v[202:205], v[88:91]
	v_mfma_f32_16x16x32_bf16 v[80:83], v[152:155], v[202:205], v[80:83]
	v_mfma_f32_16x16x32_bf16 v[124:127], v[148:151], v[180:183], v[124:127]
	v_mfma_f32_16x16x32_bf16 v[120:123], v[156:159], v[180:183], v[120:123]
	v_mfma_f32_16x16x32_bf16 v[116:119], v[148:151], v[188:191], v[116:119]
	v_mfma_f32_16x16x32_bf16 v[112:115], v[156:159], v[188:191], v[112:115]
	v_mfma_f32_16x16x32_bf16 v[104:107], v[148:151], v[198:201], v[104:107]
	v_mfma_f32_16x16x32_bf16 v[96:99], v[156:159], v[198:201], v[96:99]
	v_mfma_f32_16x16x32_bf16 v[88:91], v[148:151], v[212:215], v[88:91]
	v_mfma_f32_16x16x32_bf16 v[80:83], v[156:159], v[212:215], v[80:83]
	v_mfma_f32_16x16x32_bf16 v[108:111], v[160:163], v[176:179], v[108:111]
	v_mfma_f32_16x16x32_bf16 v[100:103], v[168:171], v[176:179], v[100:103]
	v_mfma_f32_16x16x32_bf16 v[92:95], v[160:163], v[184:187], v[92:95]
	v_mfma_f32_16x16x32_bf16 v[84:87], v[168:171], v[184:187], v[84:87]
	v_mfma_f32_16x16x32_bf16 v[76:79], v[160:163], v[194:197], v[76:79]
	v_mfma_f32_16x16x32_bf16 v[72:75], v[168:171], v[194:197], v[72:75]
	v_mfma_f32_16x16x32_bf16 v[68:71], v[160:163], v[202:205], v[68:71]
	v_mfma_f32_16x16x32_bf16 v[64:67], v[168:171], v[202:205], v[64:67]
	v_mfma_f32_16x16x32_bf16 v[108:111], v[164:167], v[180:183], v[108:111]
	v_mfma_f32_16x16x32_bf16 v[100:103], v[172:175], v[180:183], v[100:103]
	v_mfma_f32_16x16x32_bf16 v[92:95], v[164:167], v[188:191], v[92:95]
	v_mfma_f32_16x16x32_bf16 v[84:87], v[172:175], v[188:191], v[84:87]
	v_mfma_f32_16x16x32_bf16 v[76:79], v[164:167], v[198:201], v[76:79]
	v_mfma_f32_16x16x32_bf16 v[72:75], v[172:175], v[198:201], v[72:75]
	v_mfma_f32_16x16x32_bf16 v[68:71], v[164:167], v[212:215], v[68:71]
	v_mfma_f32_16x16x32_bf16 v[64:67], v[172:175], v[212:215], v[64:67]
	s_barrier
	s_setprio 0
	s_add_u32 s98, s26, s16
	s_addc_u32 s99, s27, s17
	s_add_u32 s100, s28, s16
	s_addc_u32 s101, s29, s17
	s_add_i32 s53, s44, s5
	s_mov_b32 m0, s53
	ds_read_b128 v[176:179], v210 offset:16384
	ds_read_b128 v[180:183], v210 offset:17408
	ds_read_b128 v[184:187], v210 offset:18432
	ds_read_b128 v[188:191], v210 offset:19456
	ds_read_b128 v[194:197], v210 offset:20480
	ds_read_b128 v[198:201], v210 offset:21504
	ds_read_b128 v[202:205], v210 offset:22528
	ds_read_b128 v[212:215], v210 offset:23552
	global_load_lds_dwordx4 v130, s[26:27]
	s_add_i32 m0, s53, 0x2000
	s_add_u32 s54, s26, 0x160000
	s_addc_u32 s55, s27, 0
	s_add_i32 s53, s45, s5
	global_load_lds_dwordx4 v134, s[26:27]
	s_mov_b32 m0, s53
	s_nop 0
	global_load_lds_dwordx4 v130, s[54:55]
	s_add_i32 m0, s53, 0x2000
	s_nop 0
	global_load_lds_dwordx4 v134, s[54:55]
	s_waitcnt vmcnt(6)
	s_waitcnt lgkmcnt(0)
	s_setprio 1
	s_barrier
	v_mfma_f32_16x16x32_bf16 v[60:63], v[144:147], v[176:179], v[60:63]
	v_mfma_f32_16x16x32_bf16 v[56:59], v[152:155], v[176:179], v[56:59]
	v_mfma_f32_16x16x32_bf16 v[52:55], v[144:147], v[184:187], v[52:55]
	v_mfma_f32_16x16x32_bf16 v[48:51], v[152:155], v[184:187], v[48:51]
	v_mfma_f32_16x16x32_bf16 v[40:43], v[144:147], v[194:197], v[40:43]
	v_mfma_f32_16x16x32_bf16 v[32:35], v[152:155], v[194:197], v[32:35]
	v_mfma_f32_16x16x32_bf16 v[24:27], v[144:147], v[202:205], v[24:27]
	v_mfma_f32_16x16x32_bf16 v[16:19], v[152:155], v[202:205], v[16:19]
	v_mfma_f32_16x16x32_bf16 v[60:63], v[148:151], v[180:183], v[60:63]
	v_mfma_f32_16x16x32_bf16 v[56:59], v[156:159], v[180:183], v[56:59]
	v_mfma_f32_16x16x32_bf16 v[52:55], v[148:151], v[188:191], v[52:55]
	v_mfma_f32_16x16x32_bf16 v[48:51], v[156:159], v[188:191], v[48:51]
	v_mfma_f32_16x16x32_bf16 v[40:43], v[148:151], v[198:201], v[40:43]
	v_mfma_f32_16x16x32_bf16 v[32:35], v[156:159], v[198:201], v[32:35]
	v_mfma_f32_16x16x32_bf16 v[24:27], v[148:151], v[212:215], v[24:27]
	v_mfma_f32_16x16x32_bf16 v[16:19], v[156:159], v[212:215], v[16:19]
	v_mfma_f32_16x16x32_bf16 v[44:47], v[160:163], v[176:179], v[44:47]
	v_mfma_f32_16x16x32_bf16 v[36:39], v[168:171], v[176:179], v[36:39]
	v_mfma_f32_16x16x32_bf16 v[28:31], v[160:163], v[184:187], v[28:31]
	v_mfma_f32_16x16x32_bf16 v[20:23], v[168:171], v[184:187], v[20:23]
	v_mfma_f32_16x16x32_bf16 v[12:15], v[160:163], v[194:197], v[12:15]
	v_mfma_f32_16x16x32_bf16 v[8:11], v[168:171], v[194:197], v[8:11]
	v_mfma_f32_16x16x32_bf16 v[4:7], v[160:163], v[202:205], v[4:7]
	v_mfma_f32_16x16x32_bf16 v[0:3], v[168:171], v[202:205], v[0:3]
	v_mfma_f32_16x16x32_bf16 v[44:47], v[164:167], v[180:183], v[44:47]
	v_mfma_f32_16x16x32_bf16 v[36:39], v[172:175], v[180:183], v[36:39]
	v_mfma_f32_16x16x32_bf16 v[28:31], v[164:167], v[188:191], v[28:31]
	v_mfma_f32_16x16x32_bf16 v[20:23], v[172:175], v[188:191], v[20:23]
	v_mfma_f32_16x16x32_bf16 v[12:15], v[164:167], v[198:201], v[12:15]
	v_mfma_f32_16x16x32_bf16 v[8:11], v[172:175], v[198:201], v[8:11]
	v_mfma_f32_16x16x32_bf16 v[4:7], v[164:167], v[212:215], v[4:7]
	v_mfma_f32_16x16x32_bf16 v[0:3], v[172:175], v[212:215], v[0:3]
	s_barrier
; #define PG8_STAGE(bufoff, gbase, voff) do { _Pragma("unroll") for (int _i = 0; _i < 2; ++_i) \
;         __builtin_amdgcn_global_load_lds((const unsigned*)((const char*)(gbase) + (voff)[_i]), (LAS unsigned*)(lds + (bufoff) + ldsw + _i * 8192), 16, 0, ((voff) == voffA ? AUXA : 0)); } while (0)
; #define PG8_LDA(dst, b, h) do { _Pragma("unroll") for (int m = 0; m < 4; ++m) _Pragma("unroll") for (int k = 0; k < 2; ++k) dst[m][k] = *(const LAS bf16x8*)(lds + PG8_SA(b, h) + aoff + m * 2048 + k * 1024); } while (0)
; #define PG8_LDB(dst, b, h) do { _Pragma("unroll") for (int n = 0; n < 2; ++n) _Pragma("unroll") for (int k = 0; k < 2; ++k) dst[n][k] = *(const LAS bf16x8*)(lds + PG8_SB(b, h) + boff + n * 2048 + k * 1024); } while (0)
; #define PG8_MMA(ai, bj, At, Bt) do { __builtin_amdgcn_s_setprio(1); _Pragma("unroll") for (int m = 0; m < 4; ++m) _Pragma("unroll") for (int n = 0; n < 2; ++n) _Pragma("unroll") for (int k = 0; k < 2; ++k) \
;         acc[ai][bj][m][n] = __builtin_amdgcn_mfma_f32_16x16x32_bf16(Bt[n][k], At[m][k], acc[ai][bj][m][n], 0, 0, 0); __builtin_amdgcn_s_setprio(0); } while (0)
; #define PG8_WAIT_V(n) asm volatile("s_waitcnt vmcnt(" #n ")" ::: "memory")
; #define PG8_WAIT_L(n) asm volatile("s_waitcnt lgkmcnt(" #n ")" ::: "memory")
; #define PG8_BAR __builtin_amdgcn_s_barrier()
; #define PG8_SCHED __builtin_amdgcn_sched_barrier(0)
;     ...
;             PG8_LDA(At, 0, 1); PG8_STAGE(PG8_SB(0, 0), b2, voffB); PG8_STAGE(PG8_SB(0, 1), b2 + hsB, voffB); PG8_STAGE(PG8_SA(0, 0), a2, voffA);
;     ...
;             PG8_LDB(B0, 1, 0); PG8_LDB(B1, 1, 1); PG8_SCHED; PG8_LDA(At, 1, 0); PG8_STAGE(PG8_SA(0, 1), a2 + hsA, voffA);
;             PG8_WAIT_V(8); PG8_WAIT_L(0); PG8_BAR; PG8_MMA(0, 0, At, B0); PG8_MMA(0, 1, At, B1); PG8_BAR; PG8_SCHED;
;             PG8_LDA(At, 1, 1); PG8_STAGE(PG8_SB(1, 0), b3, voffB); PG8_STAGE(PG8_SB(1, 1), b3 + hsB, voffB); PG8_STAGE(PG8_SA(1, 0), a3, voffA);
;             PG8_WAIT_V(8); PG8_WAIT_L(0); PG8_BAR; PG8_MMA(1, 0, At, B0); PG8_MMA(1, 1, At, B1); PG8_BAR; PG8_SCHED;
	s_mov_b32 m0, s30
	s_nop 0
	global_load_lds_dwordx4 v128, s[28:29]
	s_mov_b32 m0, s31
	s_nop 0
	global_load_lds_dwordx4 v132, s[28:29]
	s_setprio 0
	s_add_i32 s53, 0, 0x18000
	s_add_i32 s54, 0, 0x1c000
	v_add_u32_e32 v156, s53, v206
	v_add_u32_e32 v172, s54, v206
	ds_read_b128 v[144:147], v156
	ds_read_b128 v[148:151], v156 offset:1024
	ds_read_b128 v[152:155], v156 offset:2048
	ds_read_b128 v[156:159], v156 offset:3072
	ds_read_b128 v[160:163], v172
	ds_read_b128 v[164:167], v172 offset:1024
	ds_read_b128 v[168:171], v172 offset:2048
	ds_read_b128 v[172:175], v172 offset:3072
	s_add_u32 s28, s28, 0x160000
	s_addc_u32 s29, s29, 0
	s_mov_b32 m0, s34
	ds_read_b128 v[176:179], v210 offset:32768
	ds_read_b128 v[180:183], v210 offset:33792
	ds_read_b128 v[184:187], v210 offset:34816
	ds_read_b128 v[188:191], v210 offset:35840
	ds_read_b128 v[194:197], v210 offset:36864
	ds_read_b128 v[198:201], v210 offset:37888
	ds_read_b128 v[202:205], v210 offset:38912
	ds_read_b128 v[212:215], v210 offset:39936
	global_load_lds_dwordx4 v128, s[28:29]
	s_mov_b32 m0, s35
	s_nop 0
	global_load_lds_dwordx4 v132, s[28:29]
	s_waitcnt vmcnt(8)
	s_waitcnt lgkmcnt(0)
	s_setprio 1
	s_barrier
	v_mfma_f32_16x16x32_bf16 v[124:127], v[144:147], v[176:179], v[124:127]
	v_mfma_f32_16x16x32_bf16 v[120:123], v[152:155], v[176:179], v[120:123]
	v_mfma_f32_16x16x32_bf16 v[116:119], v[144:147], v[184:187], v[116:119]
	v_mfma_f32_16x16x32_bf16 v[112:115], v[152:155], v[184:187], v[112:115]
	v_mfma_f32_16x16x32_bf16 v[104:107], v[144:147], v[194:197], v[104:107]
	v_mfma_f32_16x16x32_bf16 v[96:99], v[152:155], v[194:197], v[96:99]
	v_mfma_f32_16x16x32_bf16 v[88:91], v[144:147], v[202:205], v[88:91]
	v_mfma_f32_16x16x32_bf16 v[80:83], v[152:155], v[202:205], v[80:83]
	v_mfma_f32_16x16x32_bf16 v[124:127], v[148:151], v[180:183], v[124:127]
	v_mfma_f32_16x16x32_bf16 v[120:123], v[156:159], v[180:183], v[120:123]
	v_mfma_f32_16x16x32_bf16 v[116:119], v[148:151], v[188:191], v[116:119]
	v_mfma_f32_16x16x32_bf16 v[112:115], v[156:159], v[188:191], v[112:115]
	v_mfma_f32_16x16x32_bf16 v[104:107], v[148:151], v[198:201], v[104:107]
	v_mfma_f32_16x16x32_bf16 v[96:99], v[156:159], v[198:201], v[96:99]
	v_mfma_f32_16x16x32_bf16 v[88:91], v[148:151], v[212:215], v[88:91]
	v_mfma_f32_16x16x32_bf16 v[80:83], v[156:159], v[212:215], v[80:83]
	v_mfma_f32_16x16x32_bf16 v[108:111], v[160:163], v[176:179], v[108:111]
	v_mfma_f32_16x16x32_bf16 v[100:103], v[168:171], v[176:179], v[100:103]
	v_mfma_f32_16x16x32_bf16 v[92:95], v[160:163], v[184:187], v[92:95]
	v_mfma_f32_16x16x32_bf16 v[84:87], v[168:171], v[184:187], v[84:87]
	v_mfma_f32_16x16x32_bf16 v[76:79], v[160:163], v[194:197], v[76:79]
	v_mfma_f32_16x16x32_bf16 v[72:75], v[168:171], v[194:197], v[72:75]
	v_mfma_f32_16x16x32_bf16 v[68:71], v[160:163], v[202:205], v[68:71]
	v_mfma_f32_16x16x32_bf16 v[64:67], v[168:171], v[202:205], v[64:67]
	v_mfma_f32_16x16x32_bf16 v[108:111], v[164:167], v[180:183], v[108:111]
	v_mfma_f32_16x16x32_bf16 v[100:103], v[172:175], v[180:183], v[100:103]
	v_mfma_f32_16x16x32_bf16 v[92:95], v[164:167], v[188:191], v[92:95]
	v_mfma_f32_16x16x32_bf16 v[84:87], v[172:175], v[188:191], v[84:87]
	v_mfma_f32_16x16x32_bf16 v[76:79], v[164:167], v[198:201], v[76:79]
	v_mfma_f32_16x16x32_bf16 v[72:75], v[172:175], v[198:201], v[72:75]
	v_mfma_f32_16x16x32_bf16 v[68:71], v[164:167], v[212:215], v[68:71]
	v_mfma_f32_16x16x32_bf16 v[64:67], v[172:175], v[212:215], v[64:67]
	s_barrier
	s_setprio 0
	s_add_i32 s28, s53, s5
	s_mov_b32 m0, s28
	ds_read_b128 v[176:179], v210 offset:49152
	ds_read_b128 v[180:183], v210 offset:50176
	ds_read_b128 v[184:187], v210 offset:51200
	ds_read_b128 v[188:191], v210 offset:52224
	ds_read_b128 v[194:197], v210 offset:53248
	ds_read_b128 v[198:201], v210 offset:54272
	ds_read_b128 v[202:205], v210 offset:55296
	ds_read_b128 v[212:215], v210 offset:56320
	global_load_lds_dwordx4 v130, s[98:99]
	s_add_i32 m0, s28, 0x2000
	s_add_u32 s26, s26, 0x160080
	s_addc_u32 s27, s27, 0
	s_add_i32 s28, s54, s5
	global_load_lds_dwordx4 v134, s[98:99]
	s_mov_b32 m0, s28
	s_nop 0
	global_load_lds_dwordx4 v130, s[26:27]
	s_add_i32 m0, s28, 0x2000
	s_nop 0
	global_load_lds_dwordx4 v134, s[26:27]
	s_waitcnt vmcnt(6)
	s_waitcnt lgkmcnt(0)
	s_setprio 1
	s_barrier
; #define PG8_STAGE(bufoff, gbase, voff) do { _Pragma("unroll") for (int _i = 0; _i < 2; ++_i) \
;         __builtin_amdgcn_global_load_lds((const unsigned*)((const char*)(gbase) + (voff)[_i]), (LAS unsigned*)(lds + (bufoff) + ldsw + _i * 8192), 16, 0, ((voff) == voffA ? AUXA : 0)); } while (0)
; #define PG8_LDA(dst, b, h) do { _Pragma("unroll") for (int m = 0; m < 4; ++m) _Pragma("unroll") for (int k = 0; k < 2; ++k) dst[m][k] = *(const LAS bf16x8*)(lds + PG8_SA(b, h) + aoff + m * 2048 + k * 1024); } while (0)
; #define PG8_MMA(ai, bj, At, Bt) do { __builtin_amdgcn_s_setprio(1); _Pragma("unroll") for (int m = 0; m < 4; ++m) _Pragma("unroll") for (int n = 0; n < 2; ++n) _Pragma("unroll") for (int k = 0; k < 2; ++k) \
;         acc[ai][bj][m][n] = __builtin_amdgcn_mfma_f32_16x16x32_bf16(Bt[n][k], At[m][k], acc[ai][bj][m][n], 0, 0, 0); __builtin_amdgcn_s_setprio(0); } while (0)
; #define PG8_WAIT_V(n) asm volatile("s_waitcnt vmcnt(" #n ")" ::: "memory")
; #define PG8_WAIT_L(n) asm volatile("s_waitcnt lgkmcnt(" #n ")" ::: "memory")
; #define PG8_BAR __builtin_amdgcn_s_barrier()
; #define PG8_SCHED __builtin_amdgcn_sched_barrier(0)
;     ...
;             PG8_WAIT_V(8); PG8_WAIT_L(0); PG8_BAR; PG8_MMA(0, 0, At, B0); PG8_MMA(0, 1, At, B1); PG8_BAR; PG8_SCHED;
;             PG8_LDA(At, 1, 1); PG8_STAGE(PG8_SB(1, 0), b3, voffB); PG8_STAGE(PG8_SB(1, 1), b3 + hsB, voffB); PG8_STAGE(PG8_SA(1, 0), a3, voffA);
;             PG8_WAIT_V(8); PG8_WAIT_L(0); PG8_BAR; PG8_MMA(1, 0, At, B0); PG8_MMA(1, 1, At, B1); PG8_BAR; PG8_SCHED;
;         }
;     __device__ __forceinline__ void operator()(const Acc& acc, const Unit& u, int wr, int wc, int fr, int fq, const float (&sv8)[8]) const {
;     ...
;                     const f32x4 y0 = xr[m][bj][0] + acc[ai][bj][m][0] * scale, y1 = xr[m][bj][1] + acc[ai][bj][m][1] * scale;
	v_mfma_f32_16x16x32_bf16 v[60:63], v[144:147], v[176:179], v[60:63]
	v_mfma_f32_16x16x32_bf16 v[56:59], v[152:155], v[176:179], v[56:59]
	v_mfma_f32_16x16x32_bf16 v[52:55], v[144:147], v[184:187], v[52:55]
	v_mfma_f32_16x16x32_bf16 v[48:51], v[152:155], v[184:187], v[48:51]
	v_mfma_f32_16x16x32_bf16 v[40:43], v[144:147], v[194:197], v[40:43]
	v_mfma_f32_16x16x32_bf16 v[32:35], v[152:155], v[194:197], v[32:35]
	v_mfma_f32_16x16x32_bf16 v[24:27], v[144:147], v[202:205], v[24:27]
	v_mfma_f32_16x16x32_bf16 v[16:19], v[152:155], v[202:205], v[16:19]
	v_mfma_f32_16x16x32_bf16 v[60:63], v[148:151], v[180:183], v[60:63]
	v_mfma_f32_16x16x32_bf16 v[56:59], v[156:159], v[180:183], v[56:59]
	v_mfma_f32_16x16x32_bf16 v[52:55], v[148:151], v[188:191], v[52:55]
	v_mfma_f32_16x16x32_bf16 v[48:51], v[156:159], v[188:191], v[48:51]
	v_mfma_f32_16x16x32_bf16 v[40:43], v[148:151], v[198:201], v[40:43]
	v_mfma_f32_16x16x32_bf16 v[32:35], v[156:159], v[198:201], v[32:35]
	v_mfma_f32_16x16x32_bf16 v[24:27], v[148:151], v[212:215], v[24:27]
	v_mfma_f32_16x16x32_bf16 v[16:19], v[156:159], v[212:215], v[16:19]
	v_mfma_f32_16x16x32_bf16 v[44:47], v[160:163], v[176:179], v[44:47]
	v_mfma_f32_16x16x32_bf16 v[36:39], v[168:171], v[176:179], v[36:39]
	v_mfma_f32_16x16x32_bf16 v[28:31], v[160:163], v[184:187], v[28:31]
	v_mfma_f32_16x16x32_bf16 v[20:23], v[168:171], v[184:187], v[20:23]
	v_mfma_f32_16x16x32_bf16 v[12:15], v[160:163], v[194:197], v[12:15]
	v_mfma_f32_16x16x32_bf16 v[8:11], v[168:171], v[194:197], v[8:11]
	v_mfma_f32_16x16x32_bf16 v[4:7], v[160:163], v[202:205], v[4:7]
	v_mfma_f32_16x16x32_bf16 v[0:3], v[168:171], v[202:205], v[0:3]
	v_mfma_f32_16x16x32_bf16 v[44:47], v[164:167], v[180:183], v[44:47]
	v_mfma_f32_16x16x32_bf16 v[36:39], v[172:175], v[180:183], v[36:39]
	v_mfma_f32_16x16x32_bf16 v[28:31], v[164:167], v[188:191], v[28:31]
	v_mfma_f32_16x16x32_bf16 v[20:23], v[172:175], v[188:191], v[20:23]
	v_mfma_f32_16x16x32_bf16 v[12:15], v[164:167], v[198:201], v[12:15]
	v_mfma_f32_16x16x32_bf16 v[8:11], v[172:175], v[198:201], v[8:11]
	v_mfma_f32_16x16x32_bf16 v[4:7], v[164:167], v[212:215], v[4:7]
	v_mfma_f32_16x16x32_bf16 v[0:3], v[172:175], v[212:215], v[0:3]
	s_barrier
	s_setprio 0
	s_add_u32 s24, s24, 0x100
	s_addc_u32 s25, s25, 0
	s_add_u32 s50, s50, 0x100
	s_addc_u32 s51, s51, 0
	s_cmp_ge_i32 s52, s38
	s_mov_b32 s26, s52
	s_cbranch_scc0 .LBB0_246
	v_pk_mul_f32 v[178:179], v[126:127], 0.5 op_sel_hi:[1,0]
	v_pk_mul_f32 v[184:185], v[124:125], 0.5 op_sel_hi:[1,0]
	v_pk_mul_f32 v[182:183], v[122:123], 0.5 op_sel_hi:[1,0]
	v_pk_mul_f32 v[180:181], v[120:121], 0.5 op_sel_hi:[1,0]
	v_pk_mul_f32 v[194:195], v[110:111], 0.5 op_sel_hi:[1,0]
	v_pk_mul_f32 v[190:191], v[108:109], 0.5 op_sel_hi:[1,0]
	v_pk_mul_f32 v[188:189], v[102:103], 0.5 op_sel_hi:[1,0]
	v_pk_mul_f32 v[186:187], v[100:101], 0.5 op_sel_hi:[1,0]
	v_pk_mul_f32 v[168:169], v[118:119], 0.5 op_sel_hi:[1,0]
	v_pk_mul_f32 v[166:167], v[116:117], 0.5 op_sel_hi:[1,0]
	v_pk_mul_f32 v[164:165], v[114:115], 0.5 op_sel_hi:[1,0]
	v_pk_mul_f32 v[162:163], v[112:113], 0.5 op_sel_hi:[1,0]
	v_pk_mul_f32 v[176:177], v[94:95], 0.5 op_sel_hi:[1,0]
	v_pk_mul_f32 v[174:175], v[92:93], 0.5 op_sel_hi:[1,0]
	v_pk_mul_f32 v[172:173], v[86:87], 0.5 op_sel_hi:[1,0]
	v_pk_mul_f32 v[170:171], v[84:85], 0.5 op_sel_hi:[1,0]
	v_pk_mul_f32 v[152:153], v[106:107], 0.5 op_sel_hi:[1,0]
	v_pk_mul_f32 v[150:151], v[104:105], 0.5 op_sel_hi:[1,0]
	v_pk_mul_f32 v[148:149], v[98:99], 0.5 op_sel_hi:[1,0]
	v_pk_mul_f32 v[146:147], v[96:97], 0.5 op_sel_hi:[1,0]
	v_pk_mul_f32 v[160:161], v[78:79], 0.5 op_sel_hi:[1,0]
	v_pk_mul_f32 v[158:159], v[76:77], 0.5 op_sel_hi:[1,0]
	v_pk_mul_f32 v[156:157], v[74:75], 0.5 op_sel_hi:[1,0]
	v_pk_mul_f32 v[154:155], v[72:73], 0.5 op_sel_hi:[1,0]
	v_pk_mul_f32 v[120:121], v[90:91], 0.5 op_sel_hi:[1,0]
	v_pk_mul_f32 v[118:119], v[88:89], 0.5 op_sel_hi:[1,0]
	v_pk_mul_f32 v[116:117], v[82:83], 0.5 op_sel_hi:[1,0]
	v_pk_mul_f32 v[114:115], v[80:81], 0.5 op_sel_hi:[1,0]
	v_pk_mul_f32 v[144:145], v[70:71], 0.5 op_sel_hi:[1,0]
	v_pk_mul_f32 v[126:127], v[68:69], 0.5 op_sel_hi:[1,0]
	v_pk_mul_f32 v[124:125], v[66:67], 0.5 op_sel_hi:[1,0]
	v_pk_mul_f32 v[122:123], v[64:65], 0.5 op_sel_hi:[1,0]
	v_pk_mul_f32 v[102:103], v[62:63], 0.5 op_sel_hi:[1,0]
	v_pk_mul_f32 v[100:101], v[60:61], 0.5 op_sel_hi:[1,0]
	v_pk_mul_f32 v[98:99], v[58:59], 0.5 op_sel_hi:[1,0]
	v_pk_mul_f32 v[96:97], v[56:57], 0.5 op_sel_hi:[1,0]
	v_pk_mul_f32 v[110:111], v[46:47], 0.5 op_sel_hi:[1,0]
	v_pk_mul_f32 v[108:109], v[44:45], 0.5 op_sel_hi:[1,0]
	v_pk_mul_f32 v[106:107], v[38:39], 0.5 op_sel_hi:[1,0]
	v_pk_mul_f32 v[104:105], v[36:37], 0.5 op_sel_hi:[1,0]
	v_pk_mul_f32 v[86:87], v[54:55], 0.5 op_sel_hi:[1,0]
	v_pk_mul_f32 v[84:85], v[52:53], 0.5 op_sel_hi:[1,0]
	v_pk_mul_f32 v[82:83], v[50:51], 0.5 op_sel_hi:[1,0]
	v_pk_mul_f32 v[80:81], v[48:49], 0.5 op_sel_hi:[1,0]
	v_pk_mul_f32 v[94:95], v[30:31], 0.5 op_sel_hi:[1,0]
	v_pk_mul_f32 v[92:93], v[28:29], 0.5 op_sel_hi:[1,0]
	v_pk_mul_f32 v[90:91], v[22:23], 0.5 op_sel_hi:[1,0]
	v_pk_mul_f32 v[88:89], v[20:21], 0.5 op_sel_hi:[1,0]
	v_pk_mul_f32 v[70:71], v[42:43], 0.5 op_sel_hi:[1,0]
	v_pk_mul_f32 v[68:69], v[40:41], 0.5 op_sel_hi:[1,0]
	v_pk_mul_f32 v[66:67], v[34:35], 0.5 op_sel_hi:[1,0]
	v_pk_mul_f32 v[64:65], v[32:33], 0.5 op_sel_hi:[1,0]
	v_pk_mul_f32 v[78:79], v[14:15], 0.5 op_sel_hi:[1,0]
	v_pk_mul_f32 v[76:77], v[12:13], 0.5 op_sel_hi:[1,0]
	v_pk_mul_f32 v[74:75], v[10:11], 0.5 op_sel_hi:[1,0]
	v_pk_mul_f32 v[72:73], v[8:9], 0.5 op_sel_hi:[1,0]
	v_pk_mul_f32 v[54:55], v[26:27], 0.5 op_sel_hi:[1,0]
	v_pk_mul_f32 v[52:53], v[24:25], 0.5 op_sel_hi:[1,0]
	v_pk_mul_f32 v[50:51], v[18:19], 0.5 op_sel_hi:[1,0]
	v_pk_mul_f32 v[48:49], v[16:17], 0.5 op_sel_hi:[1,0]
	v_pk_mul_f32 v[62:63], v[6:7], 0.5 op_sel_hi:[1,0]
	v_pk_mul_f32 v[60:61], v[4:5], 0.5 op_sel_hi:[1,0]
	v_pk_mul_f32 v[58:59], v[2:3], 0.5 op_sel_hi:[1,0]
	v_pk_mul_f32 v[56:57], v[0:1], 0.5 op_sel_hi:[1,0]

; #define PG8_STAGE(bufoff, gbase, voff) do { _Pragma("unroll") for (int _i = 0; _i < 2; ++_i) \
;         __builtin_amdgcn_global_load_lds((const unsigned*)((const char*)(gbase) + (voff)[_i]), (LAS unsigned*)(lds + (bufoff) + ldsw + _i * 8192), 16, 0, ((voff) == voffA ? AUXA : 0)); } while (0)
; #define PG8_LDA(dst, b, h) do { _Pragma("unroll") for (int m = 0; m < 4; ++m) _Pragma("unroll") for (int k = 0; k < 2; ++k) dst[m][k] = *(const LAS bf16x8*)(lds + PG8_SA(b, h) + aoff + m * 2048 + k * 1024); } while (0)
; #define PG8_LDB(dst, b, h) do { _Pragma("unroll") for (int n = 0; n < 2; ++n) _Pragma("unroll") for (int k = 0; k < 2; ++k) dst[n][k] = *(const LAS bf16x8*)(lds + PG8_SB(b, h) + boff + n * 2048 + k * 1024); } while (0)
; #define PG8_MMA(ai, bj, At, Bt) do { __builtin_amdgcn_s_setprio(1); _Pragma("unroll") for (int m = 0; m < 4; ++m) _Pragma("unroll") for (int n = 0; n < 2; ++n) _Pragma("unroll") for (int k = 0; k < 2; ++k) \
;         acc[ai][bj][m][n] = __builtin_amdgcn_mfma_f32_16x16x32_bf16(Bt[n][k], At[m][k], acc[ai][bj][m][n], 0, 0, 0); __builtin_amdgcn_s_setprio(0); } while (0)
; #define PG8_WAIT_V(n) asm volatile("s_waitcnt vmcnt(" #n ")" ::: "memory")
; #define PG8_WAIT_L(n) asm volatile("s_waitcnt lgkmcnt(" #n ")" ::: "memory")
; #define PG8_BAR __builtin_amdgcn_s_barrier()
; #define PG8_SCHED __builtin_amdgcn_sched_barrier(0)
;     ...
;             PG8_LDA(At, 0, 1); PG8_STAGE(PG8_SB(0, 0), b2, voffB); PG8_STAGE(PG8_SB(0, 1), b2 + hsB, voffB); PG8_STAGE(PG8_SA(0, 0), a2, voffA);
;             if (Epi::NPRE != 0 && last) { PG8_WAIT_V(16); } else { PG8_WAIT_V(8); }
;             PG8_WAIT_L(0); PG8_BAR; PG8_MMA(1, 0, At, B0); PG8_MMA(1, 1, At, B1); PG8_BAR; PG8_SCHED;
;             PG8_LDB(B0, 1, 0); PG8_LDB(B1, 1, 1); PG8_SCHED; PG8_LDA(At, 1, 0); PG8_STAGE(PG8_SA(0, 1), a2 + hsA, voffA);
;             PG8_WAIT_V(8); PG8_WAIT_L(0); PG8_BAR; PG8_MMA(0, 0, At, B0); PG8_MMA(0, 1, At, B1); PG8_BAR; PG8_SCHED;
.LBB0_370:
	s_waitcnt lgkmcnt(0)
	s_add_i32 s71, s71, 2
	s_setprio 1
	s_barrier
	v_mfma_f32_16x16x32_bf16 v[60:63], v[144:147], v[184:187], v[60:63]
	v_mfma_f32_16x16x32_bf16 v[56:59], v[152:155], v[184:187], v[56:59]
	v_mfma_f32_16x16x32_bf16 v[44:47], v[144:147], v[176:179], v[44:47]
	v_mfma_f32_16x16x32_bf16 v[40:43], v[152:155], v[176:179], v[40:43]
	v_mfma_f32_16x16x32_bf16 v[28:31], v[144:147], v[168:171], v[28:31]
	v_mfma_f32_16x16x32_bf16 v[24:27], v[152:155], v[168:171], v[24:27]
	v_mfma_f32_16x16x32_bf16 v[12:15], v[144:147], v[160:163], v[12:15]
	v_mfma_f32_16x16x32_bf16 v[8:11], v[152:155], v[160:163], v[8:11]
	v_mfma_f32_16x16x32_bf16 v[60:63], v[148:151], v[188:191], v[60:63]
	v_mfma_f32_16x16x32_bf16 v[56:59], v[156:159], v[188:191], v[56:59]
	v_mfma_f32_16x16x32_bf16 v[44:47], v[148:151], v[180:183], v[44:47]
	v_mfma_f32_16x16x32_bf16 v[40:43], v[156:159], v[180:183], v[40:43]
	v_mfma_f32_16x16x32_bf16 v[28:31], v[148:151], v[172:175], v[28:31]
	v_mfma_f32_16x16x32_bf16 v[24:27], v[156:159], v[172:175], v[24:27]
	v_mfma_f32_16x16x32_bf16 v[12:15], v[148:151], v[164:167], v[12:15]
	v_mfma_f32_16x16x32_bf16 v[8:11], v[156:159], v[164:167], v[8:11]
	v_mfma_f32_16x16x32_bf16 v[52:55], v[128:131], v[184:187], v[52:55]
	v_mfma_f32_16x16x32_bf16 v[48:51], v[136:139], v[184:187], v[48:51]
	v_mfma_f32_16x16x32_bf16 v[36:39], v[128:131], v[176:179], v[36:39]
	v_mfma_f32_16x16x32_bf16 v[32:35], v[136:139], v[176:179], v[32:35]
	v_mfma_f32_16x16x32_bf16 v[20:23], v[128:131], v[168:171], v[20:23]
	v_mfma_f32_16x16x32_bf16 v[16:19], v[136:139], v[168:171], v[16:19]
	v_mfma_f32_16x16x32_bf16 v[4:7], v[128:131], v[160:163], v[4:7]
	v_mfma_f32_16x16x32_bf16 v[0:3], v[136:139], v[160:163], v[0:3]
	v_mfma_f32_16x16x32_bf16 v[52:55], v[132:135], v[188:191], v[52:55]
	v_mfma_f32_16x16x32_bf16 v[48:51], v[140:143], v[188:191], v[48:51]
	v_mfma_f32_16x16x32_bf16 v[36:39], v[132:135], v[180:183], v[36:39]
	v_mfma_f32_16x16x32_bf16 v[32:35], v[140:143], v[180:183], v[32:35]
	v_mfma_f32_16x16x32_bf16 v[20:23], v[132:135], v[172:175], v[20:23]
	v_mfma_f32_16x16x32_bf16 v[16:19], v[140:143], v[172:175], v[16:19]
	v_mfma_f32_16x16x32_bf16 v[4:7], v[132:135], v[164:167], v[4:7]
	v_mfma_f32_16x16x32_bf16 v[0:3], v[140:143], v[164:167], v[0:3]
	s_barrier
	s_mov_b32 m0, s13
	s_nop 0
	global_load_lds_dwordx4 v194, s[34:35]
	s_mov_b32 m0, s44
	s_nop 0
	global_load_lds_dwordx4 v198, s[34:35]
	s_setprio 0
	s_add_i32 s36, 0, 0x18000
	s_add_i32 s37, 0, 0x1c000
	v_add_u32_e32 v140, s36, v235
	v_add_u32_e32 v156, s37, v235
	ds_read_b128 v[128:131], v140
	ds_read_b128 v[132:135], v140 offset:1024
	ds_read_b128 v[136:139], v140 offset:2048
	ds_read_b128 v[140:143], v140 offset:3072
	ds_read_b128 v[144:147], v156
	ds_read_b128 v[148:151], v156 offset:1024
	ds_read_b128 v[152:155], v156 offset:2048
	ds_read_b128 v[156:159], v156 offset:3072
	s_add_u32 s34, s34, 0x80000
	s_addc_u32 s35, s35, 0
	s_mov_b32 m0, s45
	ds_read_b128 v[160:163], v239 offset:32768
	ds_read_b128 v[164:167], v239 offset:33792
	ds_read_b128 v[168:171], v239 offset:34816
	ds_read_b128 v[172:175], v239 offset:35840
	ds_read_b128 v[176:179], v239 offset:36864
	ds_read_b128 v[180:183], v239 offset:37888
	ds_read_b128 v[184:187], v239 offset:38912
	ds_read_b128 v[188:191], v239 offset:39936
	global_load_lds_dwordx4 v194, s[34:35]
	s_mov_b32 m0, s46
	s_nop 0
	global_load_lds_dwordx4 v198, s[34:35]
	s_waitcnt vmcnt(8)
	s_waitcnt lgkmcnt(0)
	s_setprio 1
	s_barrier
	v_mfma_f32_16x16x32_bf16 v[124:127], v[128:131], v[160:163], v[124:127]
	v_mfma_f32_16x16x32_bf16 v[120:123], v[136:139], v[160:163], v[120:123]
	v_mfma_f32_16x16x32_bf16 v[108:111], v[128:131], v[168:171], v[108:111]
	v_mfma_f32_16x16x32_bf16 v[104:107], v[136:139], v[168:171], v[104:107]
	v_mfma_f32_16x16x32_bf16 v[92:95], v[128:131], v[176:179], v[92:95]
	v_mfma_f32_16x16x32_bf16 v[88:91], v[136:139], v[176:179], v[88:91]
	v_mfma_f32_16x16x32_bf16 v[76:79], v[128:131], v[184:187], v[76:79]
	v_mfma_f32_16x16x32_bf16 v[72:75], v[136:139], v[184:187], v[72:75]
	v_mfma_f32_16x16x32_bf16 v[124:127], v[132:135], v[164:167], v[124:127]
	v_mfma_f32_16x16x32_bf16 v[120:123], v[140:143], v[164:167], v[120:123]
	v_mfma_f32_16x16x32_bf16 v[108:111], v[132:135], v[172:175], v[108:111]
	v_mfma_f32_16x16x32_bf16 v[104:107], v[140:143], v[172:175], v[104:107]
	v_mfma_f32_16x16x32_bf16 v[92:95], v[132:135], v[180:183], v[92:95]
	v_mfma_f32_16x16x32_bf16 v[88:91], v[140:143], v[180:183], v[88:91]
	v_mfma_f32_16x16x32_bf16 v[76:79], v[132:135], v[188:191], v[76:79]
	v_mfma_f32_16x16x32_bf16 v[72:75], v[140:143], v[188:191], v[72:75]
	v_mfma_f32_16x16x32_bf16 v[116:119], v[144:147], v[160:163], v[116:119]
	v_mfma_f32_16x16x32_bf16 v[112:115], v[152:155], v[160:163], v[112:115]
	v_mfma_f32_16x16x32_bf16 v[100:103], v[144:147], v[168:171], v[100:103]
	v_mfma_f32_16x16x32_bf16 v[96:99], v[152:155], v[168:171], v[96:99]
	v_mfma_f32_16x16x32_bf16 v[84:87], v[144:147], v[176:179], v[84:87]
	v_mfma_f32_16x16x32_bf16 v[80:83], v[152:155], v[176:179], v[80:83]
	v_mfma_f32_16x16x32_bf16 v[68:71], v[144:147], v[184:187], v[68:71]
	v_mfma_f32_16x16x32_bf16 v[64:67], v[152:155], v[184:187], v[64:67]
	v_mfma_f32_16x16x32_bf16 v[116:119], v[148:151], v[164:167], v[116:119]
	v_mfma_f32_16x16x32_bf16 v[112:115], v[156:159], v[164:167], v[112:115]
	v_mfma_f32_16x16x32_bf16 v[100:103], v[148:151], v[172:175], v[100:103]
	v_mfma_f32_16x16x32_bf16 v[96:99], v[156:159], v[172:175], v[96:99]
	v_mfma_f32_16x16x32_bf16 v[84:87], v[148:151], v[180:183], v[84:87]
	v_mfma_f32_16x16x32_bf16 v[80:83], v[156:159], v[180:183], v[80:83]
	v_mfma_f32_16x16x32_bf16 v[68:71], v[148:151], v[188:191], v[68:71]
	v_mfma_f32_16x16x32_bf16 v[64:67], v[156:159], v[188:191], v[64:67]
	s_barrier
; #define PG8_STAGE(bufoff, gbase, voff) do { _Pragma("unroll") for (int _i = 0; _i < 2; ++_i) \
;         __builtin_amdgcn_global_load_lds((const unsigned*)((const char*)(gbase) + (voff)[_i]), (LAS unsigned*)(lds + (bufoff) + ldsw + _i * 8192), 16, 0, ((voff) == voffA ? AUXA : 0)); } while (0)
; #define PG8_LDA(dst, b, h) do { _Pragma("unroll") for (int m = 0; m < 4; ++m) _Pragma("unroll") for (int k = 0; k < 2; ++k) dst[m][k] = *(const LAS bf16x8*)(lds + PG8_SA(b, h) + aoff + m * 2048 + k * 1024); } while (0)
; #define PG8_LDB(dst, b, h) do { _Pragma("unroll") for (int n = 0; n < 2; ++n) _Pragma("unroll") for (int k = 0; k < 2; ++k) dst[n][k] = *(const LAS bf16x8*)(lds + PG8_SB(b, h) + boff + n * 2048 + k * 1024); } while (0)
; #define PG8_MMA(ai, bj, At, Bt) do { __builtin_amdgcn_s_setprio(1); _Pragma("unroll") for (int m = 0; m < 4; ++m) _Pragma("unroll") for (int n = 0; n < 2; ++n) _Pragma("unroll") for (int k = 0; k < 2; ++k) \
;         acc[ai][bj][m][n] = __builtin_amdgcn_mfma_f32_16x16x32_bf16(Bt[n][k], At[m][k], acc[ai][bj][m][n], 0, 0, 0); __builtin_amdgcn_s_setprio(0); } while (0)
; #define PG8_WAIT_V(n) asm volatile("s_waitcnt vmcnt(" #n ")" ::: "memory")
;     ...
;             PG8_LDB(B0, 0, 0); PG8_LDB(B1, 0, 1); PG8_SCHED; PG8_LDA(At, 0, 0); PG8_STAGE(PG8_SA(1, 1), a1 + hsA, voffA);
;             if (Epi::NPRE != 0 && last) { E.pre(sv, cur, wr, fr); PG8_WAIT_V(16); } else { PG8_WAIT_V(8); }
;             PG8_WAIT_L(0); PG8_BAR; PG8_MMA(0, 0, At, B0); PG8_MMA(0, 1, At, B1); PG8_BAR; PG8_SCHED;
;             PG8_LDA(At, 0, 1); PG8_STAGE(PG8_SB(0, 0), b2, voffB); PG8_STAGE(PG8_SB(0, 1), b2 + hsB, voffB); PG8_STAGE(PG8_SA(0, 0), a2, voffA);
;             if (Epi::NPRE != 0 && last) { PG8_WAIT_V(16); } else { PG8_WAIT_V(8); }
;             PG8_WAIT_L(0); PG8_BAR; PG8_MMA(1, 0, At, B0); PG8_MMA(1, 1, At, B1); PG8_BAR; PG8_SCHED;
;             PG8_LDB(B0, 1, 0); PG8_LDB(B1, 1, 1); PG8_SCHED; PG8_LDA(At, 1, 0); PG8_STAGE(PG8_SA(0, 1), a2 + hsA, voffA);
;             PG8_WAIT_V(8); PG8_WAIT_L(0); PG8_BAR; PG8_MMA(0, 0, At, B0); PG8_MMA(0, 1, At, B1); PG8_BAR; PG8_SCHED;
;             PG8_LDA(At, 1, 1); PG8_STAGE(PG8_SB(1, 0), b3, voffB); PG8_STAGE(PG8_SB(1, 1), b3 + hsB, voffB); PG8_STAGE(PG8_SA(1, 0), a3, voffA);
;             PG8_WAIT_V(8); PG8_WAIT_L(0); PG8_BAR; PG8_MMA(1, 0, At, B0); PG8_MMA(1, 1, At, B1); PG8_BAR; PG8_SCHED;
	s_setprio 0
	s_add_i32 s34, s36, s5
	s_mov_b32 m0, s34
	ds_read_b128 v[160:163], v239 offset:49152
	ds_read_b128 v[164:167], v239 offset:50176
	ds_read_b128 v[168:171], v239 offset:51200
	ds_read_b128 v[172:175], v239 offset:52224
	ds_read_b128 v[176:179], v239 offset:53248
	ds_read_b128 v[180:183], v239 offset:54272
	ds_read_b128 v[184:187], v239 offset:55296
	ds_read_b128 v[188:191], v239 offset:56320
	global_load_lds_dwordx4 v196, s[98:99]
	s_add_i32 m0, s34, 0x2000
	s_add_u32 s30, s30, 0x80080
	s_addc_u32 s31, s31, 0
	s_add_i32 s34, s37, s5
	global_load_lds_dwordx4 v200, s[98:99]
	s_mov_b32 m0, s34
	s_nop 0
	global_load_lds_dwordx4 v196, s[30:31]
	s_add_i32 m0, s34, 0x2000
	s_nop 0
	global_load_lds_dwordx4 v200, s[30:31]
	s_waitcnt vmcnt(6)
	s_waitcnt lgkmcnt(0)
	s_setprio 1
	s_barrier
	v_mfma_f32_16x16x32_bf16 v[60:63], v[128:131], v[160:163], v[60:63]
	v_mfma_f32_16x16x32_bf16 v[56:59], v[136:139], v[160:163], v[56:59]
	v_mfma_f32_16x16x32_bf16 v[44:47], v[128:131], v[168:171], v[44:47]
	v_mfma_f32_16x16x32_bf16 v[40:43], v[136:139], v[168:171], v[40:43]
	v_mfma_f32_16x16x32_bf16 v[28:31], v[128:131], v[176:179], v[28:31]
	v_mfma_f32_16x16x32_bf16 v[24:27], v[136:139], v[176:179], v[24:27]
	v_mfma_f32_16x16x32_bf16 v[12:15], v[128:131], v[184:187], v[12:15]
	v_mfma_f32_16x16x32_bf16 v[8:11], v[136:139], v[184:187], v[8:11]
	v_mfma_f32_16x16x32_bf16 v[60:63], v[132:135], v[164:167], v[60:63]
	v_mfma_f32_16x16x32_bf16 v[56:59], v[140:143], v[164:167], v[56:59]
	v_mfma_f32_16x16x32_bf16 v[44:47], v[132:135], v[172:175], v[44:47]
	v_mfma_f32_16x16x32_bf16 v[40:43], v[140:143], v[172:175], v[40:43]
	v_mfma_f32_16x16x32_bf16 v[28:31], v[132:135], v[180:183], v[28:31]
	v_mfma_f32_16x16x32_bf16 v[24:27], v[140:143], v[180:183], v[24:27]
	v_mfma_f32_16x16x32_bf16 v[12:15], v[132:135], v[188:191], v[12:15]
	v_mfma_f32_16x16x32_bf16 v[8:11], v[140:143], v[188:191], v[8:11]
	v_mfma_f32_16x16x32_bf16 v[52:55], v[144:147], v[160:163], v[52:55]
	v_mfma_f32_16x16x32_bf16 v[48:51], v[152:155], v[160:163], v[48:51]
	v_mfma_f32_16x16x32_bf16 v[36:39], v[144:147], v[168:171], v[36:39]
	v_mfma_f32_16x16x32_bf16 v[32:35], v[152:155], v[168:171], v[32:35]
	v_mfma_f32_16x16x32_bf16 v[20:23], v[144:147], v[176:179], v[20:23]
	v_mfma_f32_16x16x32_bf16 v[16:19], v[152:155], v[176:179], v[16:19]
	v_mfma_f32_16x16x32_bf16 v[4:7], v[144:147], v[184:187], v[4:7]
	v_mfma_f32_16x16x32_bf16 v[0:3], v[152:155], v[184:187], v[0:3]
	v_mfma_f32_16x16x32_bf16 v[52:55], v[148:151], v[164:167], v[52:55]
	v_mfma_f32_16x16x32_bf16 v[48:51], v[156:159], v[164:167], v[48:51]
	v_mfma_f32_16x16x32_bf16 v[36:39], v[148:151], v[172:175], v[36:39]
	v_mfma_f32_16x16x32_bf16 v[32:35], v[156:159], v[172:175], v[32:35]
	v_mfma_f32_16x16x32_bf16 v[20:23], v[148:151], v[180:183], v[20:23]
	v_mfma_f32_16x16x32_bf16 v[16:19], v[156:159], v[180:183], v[16:19]
	v_mfma_f32_16x16x32_bf16 v[4:7], v[148:151], v[188:191], v[4:7]
	v_mfma_f32_16x16x32_bf16 v[0:3], v[156:159], v[188:191], v[0:3]
	s_barrier
	s_setprio 0
	s_add_u32 s28, s28, 0x100
	s_addc_u32 s29, s29, 0
	s_add_u32 s69, s69, 0x100
	s_addc_u32 s70, s70, 0
	s_cmp_ge_i32 s71, s48
	s_cbranch_scc1 .LBB0_380
.LBB0_371:
	s_add_u32 s98, s28, 0xfff80000
	s_addc_u32 s99, s29, -1
	s_mov_b32 m0, s50
	s_nop 0
	global_load_lds_dwordx4 v194, s[98:99]
	s_mov_b32 m0, s51
	s_nop 0
	global_load_lds_dwordx4 v198, s[98:99]
	ds_read_b128 v[144:147], v237
	ds_read_b128 v[148:151], v237 offset:1024
	ds_read_b128 v[152:155], v237 offset:2048
	ds_read_b128 v[156:159], v237 offset:3072
	ds_read_b128 v[128:131], v238
	ds_read_b128 v[132:135], v238 offset:1024
	ds_read_b128 v[136:139], v238 offset:2048
	ds_read_b128 v[140:143], v238 offset:3072
	s_cmp_eq_u32 s53, s71
	s_cselect_b64 s[30:31], -1, 0
	s_cmp_lg_u32 s53, s71
	s_cselect_b64 s[36:37], -1, 0
	s_add_i32 m0, s13, 0xc000
	ds_read_b128 v[184:187], v239
	ds_read_b128 v[188:191], v239 offset:1024
	ds_read_b128 v[176:179], v239 offset:2048
	ds_read_b128 v[180:183], v239 offset:3072
	ds_read_b128 v[168:171], v239 offset:4096
	ds_read_b128 v[172:175], v239 offset:5120
	ds_read_b128 v[160:163], v239 offset:6144
	ds_read_b128 v[164:167], v239 offset:7168
	global_load_lds_dwordx4 v216, s[28:29]
	s_add_i32 m0, s13, 0xe000
	s_mov_b64 s[34:35], -1
	global_load_lds_dwordx4 v218, s[28:29]
	s_and_b64 vcc, exec, s[36:37]
	s_cbranch_vccz .LBB0_373
	s_waitcnt vmcnt(8)
	s_mov_b64 s[34:35], 0

; #define PG8_STAGE(bufoff, gbase, voff) do { _Pragma("unroll") for (int _i = 0; _i < 2; ++_i) \
;         __builtin_amdgcn_global_load_lds((const unsigned*)((const char*)(gbase) + (voff)[_i]), (LAS unsigned*)(lds + (bufoff) + ldsw + _i * 8192), 16, 0, ((voff) == voffA ? AUXA : 0)); } while (0)
; #define PG8_LDA(dst, b, h) do { _Pragma("unroll") for (int m = 0; m < 4; ++m) _Pragma("unroll") for (int k = 0; k < 2; ++k) dst[m][k] = *(const LAS bf16x8*)(lds + PG8_SA(b, h) + aoff + m * 2048 + k * 1024); } while (0)
; #define PG8_MMA(ai, bj, At, Bt) do { __builtin_amdgcn_s_setprio(1); _Pragma("unroll") for (int m = 0; m < 4; ++m) _Pragma("unroll") for (int n = 0; n < 2; ++n) _Pragma("unroll") for (int k = 0; k < 2; ++k) \
;         acc[ai][bj][m][n] = __builtin_amdgcn_mfma_f32_16x16x32_bf16(Bt[n][k], At[m][k], acc[ai][bj][m][n], 0, 0, 0); __builtin_amdgcn_s_setprio(0); } while (0)
; #define PG8_WAIT_V(n) asm volatile("s_waitcnt vmcnt(" #n ")" ::: "memory")
; #define PG8_WAIT_L(n) asm volatile("s_waitcnt lgkmcnt(" #n ")" ::: "memory")
; #define PG8_BAR __builtin_amdgcn_s_barrier()
; #define PG8_SCHED __builtin_amdgcn_sched_barrier(0)
;     ...
;             if (Epi::NPRE != 0 && last) { E.pre(sv, cur, wr, fr); PG8_WAIT_V(16); } else { PG8_WAIT_V(8); }
;             PG8_WAIT_L(0); PG8_BAR; PG8_MMA(0, 0, At, B0); PG8_MMA(0, 1, At, B1); PG8_BAR; PG8_SCHED;
;             PG8_LDA(At, 0, 1); PG8_STAGE(PG8_SB(0, 0), b2, voffB); PG8_STAGE(PG8_SB(0, 1), b2 + hsB, voffB); PG8_STAGE(PG8_SA(0, 0), a2, voffA);
;             if (Epi::NPRE != 0 && last) { PG8_WAIT_V(16); } else { PG8_WAIT_V(8); }
;             PG8_WAIT_L(0); PG8_BAR; PG8_MMA(1, 0, At, B0); PG8_MMA(1, 1, At, B1); PG8_BAR; PG8_SCHED;
.LBB0_375:
	s_add_u32 s34, s28, 0xfff80080
	s_addc_u32 s35, s29, -1
	s_waitcnt lgkmcnt(0)
	s_and_b64 s[30:31], s[30:31], exec
	s_cselect_b32 s35, s7, s35
	s_cselect_b32 s34, s21, s34
	s_cselect_b32 s31, s23, s70
	s_cselect_b32 s30, s68, s69
	s_setprio 1
	s_barrier
	v_mfma_f32_16x16x32_bf16 v[124:127], v[144:147], v[184:187], v[124:127]
	v_mfma_f32_16x16x32_bf16 v[120:123], v[152:155], v[184:187], v[120:123]
	v_mfma_f32_16x16x32_bf16 v[108:111], v[144:147], v[176:179], v[108:111]
	v_mfma_f32_16x16x32_bf16 v[104:107], v[152:155], v[176:179], v[104:107]
	v_mfma_f32_16x16x32_bf16 v[92:95], v[144:147], v[168:171], v[92:95]
	v_mfma_f32_16x16x32_bf16 v[88:91], v[152:155], v[168:171], v[88:91]
	v_mfma_f32_16x16x32_bf16 v[76:79], v[144:147], v[160:163], v[76:79]
	v_mfma_f32_16x16x32_bf16 v[72:75], v[152:155], v[160:163], v[72:75]
	v_mfma_f32_16x16x32_bf16 v[124:127], v[148:151], v[188:191], v[124:127]
	v_mfma_f32_16x16x32_bf16 v[120:123], v[156:159], v[188:191], v[120:123]
	v_mfma_f32_16x16x32_bf16 v[108:111], v[148:151], v[180:183], v[108:111]
	v_mfma_f32_16x16x32_bf16 v[104:107], v[156:159], v[180:183], v[104:107]
	v_mfma_f32_16x16x32_bf16 v[92:95], v[148:151], v[172:175], v[92:95]
	v_mfma_f32_16x16x32_bf16 v[88:91], v[156:159], v[172:175], v[88:91]
	v_mfma_f32_16x16x32_bf16 v[76:79], v[148:151], v[164:167], v[76:79]
	v_mfma_f32_16x16x32_bf16 v[72:75], v[156:159], v[164:167], v[72:75]
	v_mfma_f32_16x16x32_bf16 v[116:119], v[128:131], v[184:187], v[116:119]
	v_mfma_f32_16x16x32_bf16 v[112:115], v[136:139], v[184:187], v[112:115]
	v_mfma_f32_16x16x32_bf16 v[100:103], v[128:131], v[176:179], v[100:103]
	v_mfma_f32_16x16x32_bf16 v[96:99], v[136:139], v[176:179], v[96:99]
	v_mfma_f32_16x16x32_bf16 v[84:87], v[128:131], v[168:171], v[84:87]
	v_mfma_f32_16x16x32_bf16 v[80:83], v[136:139], v[168:171], v[80:83]
	v_mfma_f32_16x16x32_bf16 v[68:71], v[128:131], v[160:163], v[68:71]
	v_mfma_f32_16x16x32_bf16 v[64:67], v[136:139], v[160:163], v[64:67]
	v_mfma_f32_16x16x32_bf16 v[116:119], v[132:135], v[188:191], v[116:119]
	v_mfma_f32_16x16x32_bf16 v[112:115], v[140:143], v[188:191], v[112:115]
	v_mfma_f32_16x16x32_bf16 v[100:103], v[132:135], v[180:183], v[100:103]
	v_mfma_f32_16x16x32_bf16 v[96:99], v[140:143], v[180:183], v[96:99]
	v_mfma_f32_16x16x32_bf16 v[84:87], v[132:135], v[172:175], v[84:87]
	v_mfma_f32_16x16x32_bf16 v[80:83], v[140:143], v[172:175], v[80:83]
	v_mfma_f32_16x16x32_bf16 v[68:71], v[132:135], v[164:167], v[68:71]
	v_mfma_f32_16x16x32_bf16 v[64:67], v[140:143], v[164:167], v[64:67]
	s_barrier
	s_setprio 0
	s_add_u32 s98, s30, s10
	s_addc_u32 s99, s31, s11
	s_add_u32 s100, s34, s10
	s_addc_u32 s101, s35, s11
	s_mov_b32 m0, s40
	s_add_u32 s38, s30, 0x80000
	ds_read_b128 v[184:187], v239 offset:16384
	ds_read_b128 v[188:191], v239 offset:17408
	ds_read_b128 v[176:179], v239 offset:18432
	ds_read_b128 v[180:183], v239 offset:19456
	ds_read_b128 v[168:171], v239 offset:20480
	ds_read_b128 v[172:175], v239 offset:21504
	ds_read_b128 v[160:163], v239 offset:22528
	ds_read_b128 v[164:167], v239 offset:23552
	global_load_lds_dwordx4 v196, s[30:31]
	s_mov_b32 m0, s41
	s_addc_u32 s39, s31, 0
	global_load_lds_dwordx4 v200, s[30:31]
	s_mov_b32 m0, s42
	s_nop 0
	global_load_lds_dwordx4 v196, s[38:39]
	s_mov_b32 m0, s43
	s_nop 0
	global_load_lds_dwordx4 v200, s[38:39]
	s_mov_b64 s[38:39], -1
	s_and_b64 vcc, exec, s[36:37]
	s_cbranch_vccz .LBB0_377
	s_waitcnt vmcnt(6)
	s_mov_b64 s[38:39], 0

; #define PG8_STAGE(bufoff, gbase, voff) do { _Pragma("unroll") for (int _i = 0; _i < 2; ++_i) \
;         __builtin_amdgcn_global_load_lds((const unsigned*)((const char*)(gbase) + (voff)[_i]), (LAS unsigned*)(lds + (bufoff) + ldsw + _i * 8192), 16, 0, ((voff) == voffA ? AUXA : 0)); } while (0)
; #define PG8_LDA(dst, b, h) do { _Pragma("unroll") for (int m = 0; m < 4; ++m) _Pragma("unroll") for (int k = 0; k < 2; ++k) dst[m][k] = *(const LAS bf16x8*)(lds + PG8_SA(b, h) + aoff + m * 2048 + k * 1024); } while (0)
; #define PG8_LDB(dst, b, h) do { _Pragma("unroll") for (int n = 0; n < 2; ++n) _Pragma("unroll") for (int k = 0; k < 2; ++k) dst[n][k] = *(const LAS bf16x8*)(lds + PG8_SB(b, h) + boff + n * 2048 + k * 1024); } while (0)
; #define PG8_MMA(ai, bj, At, Bt) do { __builtin_amdgcn_s_setprio(1); _Pragma("unroll") for (int m = 0; m < 4; ++m) _Pragma("unroll") for (int n = 0; n < 2; ++n) _Pragma("unroll") for (int k = 0; k < 2; ++k) \
;         acc[ai][bj][m][n] = __builtin_amdgcn_mfma_f32_16x16x32_bf16(Bt[n][k], At[m][k], acc[ai][bj][m][n], 0, 0, 0); __builtin_amdgcn_s_setprio(0); } while (0)
; #define PG8_WAIT_V(n) asm volatile("s_waitcnt vmcnt(" #n ")" ::: "memory")
; #define PG8_WAIT_L(n) asm volatile("s_waitcnt lgkmcnt(" #n ")" ::: "memory")
; #define PG8_BAR __builtin_amdgcn_s_barrier()
; #define PG8_SCHED __builtin_amdgcn_sched_barrier(0)
;     ...
;         for (int t = 0; t < nt; t += 2) {
;             const bool last = (t == nt - 2);
;             const char* a1 = cA + (size_t)(t + 1) * kstep;
;             const char* a2 = last ? nA : cA + (size_t)(t + 2) * kstep; const char* b2 = last ? nB : cB + (size_t)(t + 2) * kstep;
;             const char* a3 = a2 + kstep; const char* b3 = b2 + kstep;
;             PG8_LDB(B0, 0, 0); PG8_LDB(B1, 0, 1); PG8_SCHED; PG8_LDA(At, 0, 0); PG8_STAGE(PG8_SA(1, 1), a1 + hsA, voffA);
;             if (Epi::NPRE != 0 && last) { E.pre(sv, cur, wr, fr); PG8_WAIT_V(16); } else { PG8_WAIT_V(8); }
;             PG8_WAIT_L(0); PG8_BAR; PG8_MMA(0, 0, At, B0); PG8_MMA(0, 1, At, B1); PG8_BAR; PG8_SCHED;
;             PG8_LDA(At, 0, 1); PG8_STAGE(PG8_SB(0, 0), b2, voffB); PG8_STAGE(PG8_SB(0, 1), b2 + hsB, voffB); PG8_STAGE(PG8_SA(0, 0), a2, voffA);
;             if (Epi::NPRE != 0 && last) { PG8_WAIT_V(16); } else { PG8_WAIT_V(8); }
;             PG8_WAIT_L(0); PG8_BAR; PG8_MMA(1, 0, At, B0); PG8_MMA(1, 1, At, B1); PG8_BAR; PG8_SCHED;
.LBB0_648:
	s_add_u32 s98, s22, 0xfffe0000
	s_addc_u32 s99, s23, -1
	s_mov_b32 m0, s36
	s_nop 0
	global_load_lds_dwordx4 v134, s[98:99]
	s_mov_b32 m0, s37
	s_nop 0
	global_load_lds_dwordx4 v130, s[98:99]
	ds_read_b128 v[148:151], v143
	ds_read_b128 v[152:155], v143 offset:1024
	ds_read_b128 v[156:159], v143 offset:2048
	ds_read_b128 v[160:163], v143 offset:3072
	ds_read_b128 v[164:167], v144
	ds_read_b128 v[168:171], v144 offset:1024
	ds_read_b128 v[172:175], v144 offset:2048
	ds_read_b128 v[176:179], v144 offset:3072
	s_add_i32 s56, s24, 2
	s_add_u32 s25, s22, 0xfffe0080
	s_addc_u32 s26, s23, -1
	s_cmp_eq_u32 s38, s24
	s_cselect_b32 s24, s53, s54
	s_cselect_b32 s27, s50, s26
	s_cselect_b32 s26, s51, s25
	s_cselect_b32 s25, s52, s55
	s_mov_b32 m0, s39
	ds_read_b128 v[180:183], v145
	ds_read_b128 v[184:187], v145 offset:1024
	ds_read_b128 v[188:191], v145 offset:2048
	ds_read_b128 v[194:197], v145 offset:3072
	ds_read_b128 v[198:201], v145 offset:4096
	ds_read_b128 v[202:205], v145 offset:5120
	ds_read_b128 v[206:209], v145 offset:6144
	ds_read_b128 v[210:213], v145 offset:7168
	global_load_lds_dwordx4 v138, s[22:23]
	s_mov_b32 m0, s40
	s_nop 0
	global_load_lds_dwordx4 v140, s[22:23]
	s_waitcnt vmcnt(8)
	s_waitcnt lgkmcnt(0)
	s_setprio 1
	s_barrier
	v_mfma_f32_16x16x32_bf16 v[124:127], v[148:151], v[180:183], v[124:127]
	v_mfma_f32_16x16x32_bf16 v[120:123], v[156:159], v[180:183], v[120:123]
	v_mfma_f32_16x16x32_bf16 v[108:111], v[148:151], v[188:191], v[108:111]
	v_mfma_f32_16x16x32_bf16 v[104:107], v[156:159], v[188:191], v[104:107]
	v_mfma_f32_16x16x32_bf16 v[92:95], v[148:151], v[198:201], v[92:95]
	v_mfma_f32_16x16x32_bf16 v[88:91], v[156:159], v[198:201], v[88:91]
	v_mfma_f32_16x16x32_bf16 v[76:79], v[148:151], v[206:209], v[76:79]
	v_mfma_f32_16x16x32_bf16 v[72:75], v[156:159], v[206:209], v[72:75]
	v_mfma_f32_16x16x32_bf16 v[124:127], v[152:155], v[184:187], v[124:127]
	v_mfma_f32_16x16x32_bf16 v[120:123], v[160:163], v[184:187], v[120:123]
	v_mfma_f32_16x16x32_bf16 v[108:111], v[152:155], v[194:197], v[108:111]
	v_mfma_f32_16x16x32_bf16 v[104:107], v[160:163], v[194:197], v[104:107]
	v_mfma_f32_16x16x32_bf16 v[92:95], v[152:155], v[202:205], v[92:95]
	v_mfma_f32_16x16x32_bf16 v[88:91], v[160:163], v[202:205], v[88:91]
	v_mfma_f32_16x16x32_bf16 v[76:79], v[152:155], v[210:213], v[76:79]
	v_mfma_f32_16x16x32_bf16 v[72:75], v[160:163], v[210:213], v[72:75]
	v_mfma_f32_16x16x32_bf16 v[116:119], v[164:167], v[180:183], v[116:119]
	v_mfma_f32_16x16x32_bf16 v[112:115], v[172:175], v[180:183], v[112:115]
	v_mfma_f32_16x16x32_bf16 v[100:103], v[164:167], v[188:191], v[100:103]
	v_mfma_f32_16x16x32_bf16 v[96:99], v[172:175], v[188:191], v[96:99]
	v_mfma_f32_16x16x32_bf16 v[84:87], v[164:167], v[198:201], v[84:87]
	v_mfma_f32_16x16x32_bf16 v[80:83], v[172:175], v[198:201], v[80:83]
	v_mfma_f32_16x16x32_bf16 v[68:71], v[164:167], v[206:209], v[68:71]
	v_mfma_f32_16x16x32_bf16 v[64:67], v[172:175], v[206:209], v[64:67]
	v_mfma_f32_16x16x32_bf16 v[116:119], v[168:171], v[184:187], v[116:119]
	v_mfma_f32_16x16x32_bf16 v[112:115], v[176:179], v[184:187], v[112:115]
	v_mfma_f32_16x16x32_bf16 v[100:103], v[168:171], v[194:197], v[100:103]
	v_mfma_f32_16x16x32_bf16 v[96:99], v[176:179], v[194:197], v[96:99]
	v_mfma_f32_16x16x32_bf16 v[84:87], v[168:171], v[202:205], v[84:87]
	v_mfma_f32_16x16x32_bf16 v[80:83], v[176:179], v[202:205], v[80:83]
	v_mfma_f32_16x16x32_bf16 v[68:71], v[168:171], v[210:213], v[68:71]
	v_mfma_f32_16x16x32_bf16 v[64:67], v[176:179], v[210:213], v[64:67]
	s_barrier
	s_setprio 0
	s_add_u32 s98, s24, s12
	s_addc_u32 s99, s25, s13
	s_add_u32 s100, s26, s12
	s_addc_u32 s101, s27, s13
	s_mov_b32 m0, s41
	s_add_u32 s66, s24, 0x10000
	ds_read_b128 v[180:183], v145 offset:16384
	ds_read_b128 v[184:187], v145 offset:17408
	ds_read_b128 v[188:191], v145 offset:18432
	ds_read_b128 v[194:197], v145 offset:19456
	ds_read_b128 v[198:201], v145 offset:20480
	ds_read_b128 v[202:205], v145 offset:21504
	ds_read_b128 v[206:209], v145 offset:22528
	ds_read_b128 v[210:213], v145 offset:23552
	global_load_lds_dwordx4 v132, s[24:25]
	s_mov_b32 m0, s42
	s_addc_u32 s67, s25, 0
	global_load_lds_dwordx4 v128, s[24:25]
	s_mov_b32 m0, s43
	s_nop 0
	global_load_lds_dwordx4 v132, s[66:67]
	s_mov_b32 m0, s44
	s_nop 0
	global_load_lds_dwordx4 v128, s[66:67]
	s_waitcnt vmcnt(6)
	s_waitcnt lgkmcnt(0)
	s_setprio 1
	s_barrier
	v_mfma_f32_16x16x32_bf16 v[60:63], v[148:151], v[180:183], v[60:63]
	v_mfma_f32_16x16x32_bf16 v[56:59], v[156:159], v[180:183], v[56:59]
	v_mfma_f32_16x16x32_bf16 v[44:47], v[148:151], v[188:191], v[44:47]
	v_mfma_f32_16x16x32_bf16 v[40:43], v[156:159], v[188:191], v[40:43]
	v_mfma_f32_16x16x32_bf16 v[28:31], v[148:151], v[198:201], v[28:31]
	v_mfma_f32_16x16x32_bf16 v[24:27], v[156:159], v[198:201], v[24:27]
	v_mfma_f32_16x16x32_bf16 v[12:15], v[148:151], v[206:209], v[12:15]
	v_mfma_f32_16x16x32_bf16 v[8:11], v[156:159], v[206:209], v[8:11]
	v_mfma_f32_16x16x32_bf16 v[60:63], v[152:155], v[184:187], v[60:63]
	v_mfma_f32_16x16x32_bf16 v[56:59], v[160:163], v[184:187], v[56:59]
	v_mfma_f32_16x16x32_bf16 v[44:47], v[152:155], v[194:197], v[44:47]
	v_mfma_f32_16x16x32_bf16 v[40:43], v[160:163], v[194:197], v[40:43]
	v_mfma_f32_16x16x32_bf16 v[28:31], v[152:155], v[202:205], v[28:31]
	v_mfma_f32_16x16x32_bf16 v[24:27], v[160:163], v[202:205], v[24:27]
	v_mfma_f32_16x16x32_bf16 v[12:15], v[152:155], v[210:213], v[12:15]
	v_mfma_f32_16x16x32_bf16 v[8:11], v[160:163], v[210:213], v[8:11]
	v_mfma_f32_16x16x32_bf16 v[52:55], v[164:167], v[180:183], v[52:55]
	v_mfma_f32_16x16x32_bf16 v[48:51], v[172:175], v[180:183], v[48:51]
	v_mfma_f32_16x16x32_bf16 v[36:39], v[164:167], v[188:191], v[36:39]
	v_mfma_f32_16x16x32_bf16 v[32:35], v[172:175], v[188:191], v[32:35]
	v_mfma_f32_16x16x32_bf16 v[20:23], v[164:167], v[198:201], v[20:23]
	v_mfma_f32_16x16x32_bf16 v[16:19], v[172:175], v[198:201], v[16:19]
	v_mfma_f32_16x16x32_bf16 v[4:7], v[164:167], v[206:209], v[4:7]
	v_mfma_f32_16x16x32_bf16 v[0:3], v[172:175], v[206:209], v[0:3]
	v_mfma_f32_16x16x32_bf16 v[52:55], v[168:171], v[184:187], v[52:55]
	v_mfma_f32_16x16x32_bf16 v[48:51], v[176:179], v[184:187], v[48:51]
	v_mfma_f32_16x16x32_bf16 v[36:39], v[168:171], v[194:197], v[36:39]
	v_mfma_f32_16x16x32_bf16 v[32:35], v[176:179], v[194:197], v[32:35]
	v_mfma_f32_16x16x32_bf16 v[20:23], v[168:171], v[202:205], v[20:23]
	v_mfma_f32_16x16x32_bf16 v[16:19], v[176:179], v[202:205], v[16:19]
	v_mfma_f32_16x16x32_bf16 v[4:7], v[168:171], v[210:213], v[4:7]
	v_mfma_f32_16x16x32_bf16 v[0:3], v[176:179], v[210:213], v[0:3]
	s_barrier
; #define PG8_STAGE(bufoff, gbase, voff) do { _Pragma("unroll") for (int _i = 0; _i < 2; ++_i) \
;         __builtin_amdgcn_global_load_lds((const unsigned*)((const char*)(gbase) + (voff)[_i]), (LAS unsigned*)(lds + (bufoff) + ldsw + _i * 8192), 16, 0, ((voff) == voffA ? AUXA : 0)); } while (0)
; #define PG8_LDA(dst, b, h) do { _Pragma("unroll") for (int m = 0; m < 4; ++m) _Pragma("unroll") for (int k = 0; k < 2; ++k) dst[m][k] = *(const LAS bf16x8*)(lds + PG8_SA(b, h) + aoff + m * 2048 + k * 1024); } while (0)
; #define PG8_LDB(dst, b, h) do { _Pragma("unroll") for (int n = 0; n < 2; ++n) _Pragma("unroll") for (int k = 0; k < 2; ++k) dst[n][k] = *(const LAS bf16x8*)(lds + PG8_SB(b, h) + boff + n * 2048 + k * 1024); } while (0)
; #define PG8_MMA(ai, bj, At, Bt) do { __builtin_amdgcn_s_setprio(1); _Pragma("unroll") for (int m = 0; m < 4; ++m) _Pragma("unroll") for (int n = 0; n < 2; ++n) _Pragma("unroll") for (int k = 0; k < 2; ++k) \
;         acc[ai][bj][m][n] = __builtin_amdgcn_mfma_f32_16x16x32_bf16(Bt[n][k], At[m][k], acc[ai][bj][m][n], 0, 0, 0); __builtin_amdgcn_s_setprio(0); } while (0)
; #define PG8_WAIT_V(n) asm volatile("s_waitcnt vmcnt(" #n ")" ::: "memory")
; #define PG8_WAIT_L(n) asm volatile("s_waitcnt lgkmcnt(" #n ")" ::: "memory")
; #define PG8_BAR __builtin_amdgcn_s_barrier()
; #define PG8_SCHED __builtin_amdgcn_sched_barrier(0)
;     ...
;             PG8_WAIT_L(0); PG8_BAR; PG8_MMA(1, 0, At, B0); PG8_MMA(1, 1, At, B1); PG8_BAR; PG8_SCHED;
;             PG8_LDB(B0, 1, 0); PG8_LDB(B1, 1, 1); PG8_SCHED; PG8_LDA(At, 1, 0); PG8_STAGE(PG8_SA(0, 1), a2 + hsA, voffA);
;             PG8_WAIT_V(8); PG8_WAIT_L(0); PG8_BAR; PG8_MMA(0, 0, At, B0); PG8_MMA(0, 1, At, B1); PG8_BAR; PG8_SCHED;
;             PG8_LDA(At, 1, 1); PG8_STAGE(PG8_SB(1, 0), b3, voffB); PG8_STAGE(PG8_SB(1, 1), b3 + hsB, voffB); PG8_STAGE(PG8_SA(1, 0), a3, voffA);
;             PG8_WAIT_V(8); PG8_WAIT_L(0); PG8_BAR; PG8_MMA(1, 0, At, B0); PG8_MMA(1, 1, At, B1); PG8_BAR; PG8_SCHED;
;         }
	s_mov_b32 m0, s3
	s_nop 0
	global_load_lds_dwordx4 v134, s[26:27]
	s_mov_b32 m0, s29
	s_nop 0
	global_load_lds_dwordx4 v130, s[26:27]
	s_setprio 0
	ds_read_b128 v[148:151], v146
	ds_read_b128 v[152:155], v146 offset:1024
	ds_read_b128 v[156:159], v146 offset:2048
	ds_read_b128 v[160:163], v146 offset:3072
	ds_read_b128 v[164:167], v147
	ds_read_b128 v[168:171], v147 offset:1024
	ds_read_b128 v[172:175], v147 offset:2048
	ds_read_b128 v[176:179], v147 offset:3072
	s_add_u32 s26, s26, 0x20000
	s_addc_u32 s27, s27, 0
	s_mov_b32 m0, s30
	ds_read_b128 v[180:183], v145 offset:32768
	ds_read_b128 v[184:187], v145 offset:33792
	ds_read_b128 v[188:191], v145 offset:34816
	ds_read_b128 v[194:197], v145 offset:35840
	ds_read_b128 v[198:201], v145 offset:36864
	ds_read_b128 v[202:205], v145 offset:37888
	ds_read_b128 v[206:209], v145 offset:38912
	ds_read_b128 v[210:213], v145 offset:39936
	global_load_lds_dwordx4 v134, s[26:27]
	s_mov_b32 m0, s31
	s_nop 0
	global_load_lds_dwordx4 v130, s[26:27]
	s_waitcnt vmcnt(8)
	s_waitcnt lgkmcnt(0)
	s_setprio 1
	s_barrier
	v_mfma_f32_16x16x32_bf16 v[124:127], v[148:151], v[180:183], v[124:127]
	v_mfma_f32_16x16x32_bf16 v[120:123], v[156:159], v[180:183], v[120:123]
	v_mfma_f32_16x16x32_bf16 v[108:111], v[148:151], v[188:191], v[108:111]
	v_mfma_f32_16x16x32_bf16 v[104:107], v[156:159], v[188:191], v[104:107]
	v_mfma_f32_16x16x32_bf16 v[92:95], v[148:151], v[198:201], v[92:95]
	v_mfma_f32_16x16x32_bf16 v[88:91], v[156:159], v[198:201], v[88:91]
	v_mfma_f32_16x16x32_bf16 v[76:79], v[148:151], v[206:209], v[76:79]
	v_mfma_f32_16x16x32_bf16 v[72:75], v[156:159], v[206:209], v[72:75]
	v_mfma_f32_16x16x32_bf16 v[124:127], v[152:155], v[184:187], v[124:127]
	v_mfma_f32_16x16x32_bf16 v[120:123], v[160:163], v[184:187], v[120:123]
	v_mfma_f32_16x16x32_bf16 v[108:111], v[152:155], v[194:197], v[108:111]
	v_mfma_f32_16x16x32_bf16 v[104:107], v[160:163], v[194:197], v[104:107]
	v_mfma_f32_16x16x32_bf16 v[92:95], v[152:155], v[202:205], v[92:95]
	v_mfma_f32_16x16x32_bf16 v[88:91], v[160:163], v[202:205], v[88:91]
	v_mfma_f32_16x16x32_bf16 v[76:79], v[152:155], v[210:213], v[76:79]
	v_mfma_f32_16x16x32_bf16 v[72:75], v[160:163], v[210:213], v[72:75]
	v_mfma_f32_16x16x32_bf16 v[116:119], v[164:167], v[180:183], v[116:119]
	v_mfma_f32_16x16x32_bf16 v[112:115], v[172:175], v[180:183], v[112:115]
	v_mfma_f32_16x16x32_bf16 v[100:103], v[164:167], v[188:191], v[100:103]
	v_mfma_f32_16x16x32_bf16 v[96:99], v[172:175], v[188:191], v[96:99]
	v_mfma_f32_16x16x32_bf16 v[84:87], v[164:167], v[198:201], v[84:87]
	v_mfma_f32_16x16x32_bf16 v[80:83], v[172:175], v[198:201], v[80:83]
	v_mfma_f32_16x16x32_bf16 v[68:71], v[164:167], v[206:209], v[68:71]
	v_mfma_f32_16x16x32_bf16 v[64:67], v[172:175], v[206:209], v[64:67]
	v_mfma_f32_16x16x32_bf16 v[116:119], v[168:171], v[184:187], v[116:119]
	v_mfma_f32_16x16x32_bf16 v[112:115], v[176:179], v[184:187], v[112:115]
	v_mfma_f32_16x16x32_bf16 v[100:103], v[168:171], v[194:197], v[100:103]
	v_mfma_f32_16x16x32_bf16 v[96:99], v[176:179], v[194:197], v[96:99]
	v_mfma_f32_16x16x32_bf16 v[84:87], v[168:171], v[202:205], v[84:87]
	v_mfma_f32_16x16x32_bf16 v[80:83], v[176:179], v[202:205], v[80:83]
	v_mfma_f32_16x16x32_bf16 v[68:71], v[168:171], v[210:213], v[68:71]
	v_mfma_f32_16x16x32_bf16 v[64:67], v[176:179], v[210:213], v[64:67]
	s_barrier
	s_setprio 0
	s_add_i32 s26, s45, s28
	s_mov_b32 m0, s26
	ds_read_b128 v[180:183], v145 offset:49152
	ds_read_b128 v[184:187], v145 offset:50176
	ds_read_b128 v[188:191], v145 offset:51200
	ds_read_b128 v[194:197], v145 offset:52224
	ds_read_b128 v[198:201], v145 offset:53248
	ds_read_b128 v[202:205], v145 offset:54272
	ds_read_b128 v[206:209], v145 offset:55296
	ds_read_b128 v[210:213], v145 offset:56320
	global_load_lds_dwordx4 v132, s[98:99]
	s_add_i32 m0, s26, 0x2000
	s_add_u32 s24, s24, 0x10080
	s_addc_u32 s25, s25, 0
	s_add_i32 s26, s46, s28
	global_load_lds_dwordx4 v128, s[98:99]
	s_mov_b32 m0, s26
	s_nop 0
	global_load_lds_dwordx4 v132, s[24:25]
	s_add_i32 m0, s26, 0x2000
	s_nop 0
	global_load_lds_dwordx4 v128, s[24:25]
	s_waitcnt vmcnt(6)
	s_waitcnt lgkmcnt(0)
	s_setprio 1
	s_barrier
	v_mfma_f32_16x16x32_bf16 v[60:63], v[148:151], v[180:183], v[60:63]
	v_mfma_f32_16x16x32_bf16 v[56:59], v[156:159], v[180:183], v[56:59]
	v_mfma_f32_16x16x32_bf16 v[44:47], v[148:151], v[188:191], v[44:47]
	v_mfma_f32_16x16x32_bf16 v[40:43], v[156:159], v[188:191], v[40:43]
	v_mfma_f32_16x16x32_bf16 v[28:31], v[148:151], v[198:201], v[28:31]
	v_mfma_f32_16x16x32_bf16 v[24:27], v[156:159], v[198:201], v[24:27]
	v_mfma_f32_16x16x32_bf16 v[12:15], v[148:151], v[206:209], v[12:15]
	v_mfma_f32_16x16x32_bf16 v[8:11], v[156:159], v[206:209], v[8:11]
	v_mfma_f32_16x16x32_bf16 v[60:63], v[152:155], v[184:187], v[60:63]
	v_mfma_f32_16x16x32_bf16 v[56:59], v[160:163], v[184:187], v[56:59]
	v_mfma_f32_16x16x32_bf16 v[44:47], v[152:155], v[194:197], v[44:47]
	v_mfma_f32_16x16x32_bf16 v[40:43], v[160:163], v[194:197], v[40:43]
	v_mfma_f32_16x16x32_bf16 v[28:31], v[152:155], v[202:205], v[28:31]
	v_mfma_f32_16x16x32_bf16 v[24:27], v[160:163], v[202:205], v[24:27]
	v_mfma_f32_16x16x32_bf16 v[12:15], v[152:155], v[210:213], v[12:15]
	v_mfma_f32_16x16x32_bf16 v[8:11], v[160:163], v[210:213], v[8:11]
	v_mfma_f32_16x16x32_bf16 v[52:55], v[164:167], v[180:183], v[52:55]
	v_mfma_f32_16x16x32_bf16 v[48:51], v[172:175], v[180:183], v[48:51]
	v_mfma_f32_16x16x32_bf16 v[36:39], v[164:167], v[188:191], v[36:39]
	v_mfma_f32_16x16x32_bf16 v[32:35], v[172:175], v[188:191], v[32:35]
	v_mfma_f32_16x16x32_bf16 v[20:23], v[164:167], v[198:201], v[20:23]
	v_mfma_f32_16x16x32_bf16 v[16:19], v[172:175], v[198:201], v[16:19]
	v_mfma_f32_16x16x32_bf16 v[4:7], v[164:167], v[206:209], v[4:7]
	v_mfma_f32_16x16x32_bf16 v[0:3], v[172:175], v[206:209], v[0:3]
	v_mfma_f32_16x16x32_bf16 v[52:55], v[168:171], v[184:187], v[52:55]
	v_mfma_f32_16x16x32_bf16 v[48:51], v[176:179], v[184:187], v[48:51]
	v_mfma_f32_16x16x32_bf16 v[36:39], v[168:171], v[194:197], v[36:39]
	v_mfma_f32_16x16x32_bf16 v[32:35], v[176:179], v[194:197], v[32:35]
	v_mfma_f32_16x16x32_bf16 v[20:23], v[168:171], v[202:205], v[20:23]
	v_mfma_f32_16x16x32_bf16 v[16:19], v[176:179], v[202:205], v[16:19]
	v_mfma_f32_16x16x32_bf16 v[4:7], v[168:171], v[210:213], v[4:7]
	v_mfma_f32_16x16x32_bf16 v[0:3], v[176:179], v[210:213], v[0:3]
	s_barrier
	s_setprio 0
	s_add_u32 s22, s22, 0x100
	s_addc_u32 s23, s23, 0
	s_add_u32 s54, s54, 0x100
	s_addc_u32 s55, s55, 0
	s_cmp_ge_i32 s56, s35
	s_mov_b32 s24, s56
	s_cbranch_scc0 .LBB0_648

; #define PG8_STAGE(bufoff, gbase, voff) do { _Pragma("unroll") for (int _i = 0; _i < 2; ++_i) \
;         __builtin_amdgcn_global_load_lds((const unsigned*)((const char*)(gbase) + (voff)[_i]), (LAS unsigned*)(lds + (bufoff) + ldsw + _i * 8192), 16, 0, ((voff) == voffA ? AUXA : 0)); } while (0)
; #define PG8_LDA(dst, b, h) do { _Pragma("unroll") for (int m = 0; m < 4; ++m) _Pragma("unroll") for (int k = 0; k < 2; ++k) dst[m][k] = *(const LAS bf16x8*)(lds + PG8_SA(b, h) + aoff + m * 2048 + k * 1024); } while (0)
; #define PG8_LDB(dst, b, h) do { _Pragma("unroll") for (int n = 0; n < 2; ++n) _Pragma("unroll") for (int k = 0; k < 2; ++k) dst[n][k] = *(const LAS bf16x8*)(lds + PG8_SB(b, h) + boff + n * 2048 + k * 1024); } while (0)
; #define PG8_MMA(ai, bj, At, Bt) do { __builtin_amdgcn_s_setprio(1); _Pragma("unroll") for (int m = 0; m < 4; ++m) _Pragma("unroll") for (int n = 0; n < 2; ++n) _Pragma("unroll") for (int k = 0; k < 2; ++k) \
;         acc[ai][bj][m][n] = __builtin_amdgcn_mfma_f32_16x16x32_bf16(Bt[n][k], At[m][k], acc[ai][bj][m][n], 0, 0, 0); __builtin_amdgcn_s_setprio(0); } while (0)
; #define PG8_WAIT_V(n) asm volatile("s_waitcnt vmcnt(" #n ")" ::: "memory")
; #define PG8_WAIT_L(n) asm volatile("s_waitcnt lgkmcnt(" #n ")" ::: "memory")
; #define PG8_BAR __builtin_amdgcn_s_barrier()
; #define PG8_SCHED __builtin_amdgcn_sched_barrier(0)
;     ...
;         for (int t = 0; t < nt; t += 2) {
;             const bool last = (t == nt - 2);
;             const char* a1 = cA + (size_t)(t + 1) * kstep;
;             const char* a2 = last ? nA : cA + (size_t)(t + 2) * kstep; const char* b2 = last ? nB : cB + (size_t)(t + 2) * kstep;
;             const char* a3 = a2 + kstep; const char* b3 = b2 + kstep;
;             PG8_LDB(B0, 0, 0); PG8_LDB(B1, 0, 1); PG8_SCHED; PG8_LDA(At, 0, 0); PG8_STAGE(PG8_SA(1, 1), a1 + hsA, voffA);
;             if (Epi::NPRE != 0 && last) { E.pre(sv, cur, wr, fr); PG8_WAIT_V(16); } else { PG8_WAIT_V(8); }
;             PG8_WAIT_L(0); PG8_BAR; PG8_MMA(0, 0, At, B0); PG8_MMA(0, 1, At, B1); PG8_BAR; PG8_SCHED;
;             PG8_LDA(At, 0, 1); PG8_STAGE(PG8_SB(0, 0), b2, voffB); PG8_STAGE(PG8_SB(0, 1), b2 + hsB, voffB); PG8_STAGE(PG8_SA(0, 0), a2, voffA);
;             if (Epi::NPRE != 0 && last) { PG8_WAIT_V(16); } else { PG8_WAIT_V(8); }
;             PG8_WAIT_L(0); PG8_BAR; PG8_MMA(1, 0, At, B0); PG8_MMA(1, 1, At, B1); PG8_BAR; PG8_SCHED;
.LBB0_887:
	s_add_u32 s98, s24, 0xfffe0000
	s_addc_u32 s99, s25, -1
	s_mov_b32 m0, s40
	s_nop 0
	global_load_lds_dwordx4 v134, s[98:99]
	s_mov_b32 m0, s41
	s_nop 0
	global_load_lds_dwordx4 v130, s[98:99]
	ds_read_b128 v[150:153], v146
	ds_read_b128 v[154:157], v146 offset:1024
	ds_read_b128 v[158:161], v146 offset:2048
	ds_read_b128 v[162:165], v146 offset:3072
	ds_read_b128 v[166:169], v147
	ds_read_b128 v[170:173], v147 offset:1024
	ds_read_b128 v[174:177], v147 offset:2048
	ds_read_b128 v[178:181], v147 offset:3072
	s_add_i32 s53, s26, 2
	s_add_u32 s27, s24, 0xfffe0080
	s_addc_u32 s28, s25, -1
	s_cmp_eq_u32 s42, s26
	s_cselect_b32 s26, s50, s51
	s_cselect_b32 s29, s23, s28
	s_cselect_b32 s28, s48, s27
	s_cselect_b32 s27, s49, s52
	s_add_i32 m0, s3, 0xc000
	ds_read_b128 v[182:185], v148
	ds_read_b128 v[186:189], v148 offset:1024
	ds_read_b128 v[194:197], v148 offset:2048
	ds_read_b128 v[198:201], v148 offset:3072
	ds_read_b128 v[202:205], v148 offset:4096
	ds_read_b128 v[206:209], v148 offset:5120
	ds_read_b128 v[210:213], v148 offset:6144
	ds_read_b128 v[214:217], v148 offset:7168
	global_load_lds_dwordx4 v138, s[24:25]
	s_add_i32 m0, s3, 0xe000
	s_nop 0
	global_load_lds_dwordx4 v140, s[24:25]
	s_waitcnt vmcnt(8)
	s_waitcnt lgkmcnt(0)
	s_setprio 1
	s_barrier
	v_mfma_f32_16x16x32_bf16 v[124:127], v[150:153], v[182:185], v[124:127]
	v_mfma_f32_16x16x32_bf16 v[120:123], v[158:161], v[182:185], v[120:123]
	v_mfma_f32_16x16x32_bf16 v[108:111], v[150:153], v[194:197], v[108:111]
	v_mfma_f32_16x16x32_bf16 v[104:107], v[158:161], v[194:197], v[104:107]
	v_mfma_f32_16x16x32_bf16 v[92:95], v[150:153], v[202:205], v[92:95]
	v_mfma_f32_16x16x32_bf16 v[88:91], v[158:161], v[202:205], v[88:91]
	v_mfma_f32_16x16x32_bf16 v[76:79], v[150:153], v[210:213], v[76:79]
	v_mfma_f32_16x16x32_bf16 v[72:75], v[158:161], v[210:213], v[72:75]
	v_mfma_f32_16x16x32_bf16 v[124:127], v[154:157], v[186:189], v[124:127]
	v_mfma_f32_16x16x32_bf16 v[120:123], v[162:165], v[186:189], v[120:123]
	v_mfma_f32_16x16x32_bf16 v[108:111], v[154:157], v[198:201], v[108:111]
	v_mfma_f32_16x16x32_bf16 v[104:107], v[162:165], v[198:201], v[104:107]
	v_mfma_f32_16x16x32_bf16 v[92:95], v[154:157], v[206:209], v[92:95]
	v_mfma_f32_16x16x32_bf16 v[88:91], v[162:165], v[206:209], v[88:91]
	v_mfma_f32_16x16x32_bf16 v[76:79], v[154:157], v[214:217], v[76:79]
	v_mfma_f32_16x16x32_bf16 v[72:75], v[162:165], v[214:217], v[72:75]
	v_mfma_f32_16x16x32_bf16 v[116:119], v[166:169], v[182:185], v[116:119]
	v_mfma_f32_16x16x32_bf16 v[112:115], v[174:177], v[182:185], v[112:115]
	v_mfma_f32_16x16x32_bf16 v[100:103], v[166:169], v[194:197], v[100:103]
	v_mfma_f32_16x16x32_bf16 v[96:99], v[174:177], v[194:197], v[96:99]
	v_mfma_f32_16x16x32_bf16 v[84:87], v[166:169], v[202:205], v[84:87]
	v_mfma_f32_16x16x32_bf16 v[80:83], v[174:177], v[202:205], v[80:83]
	v_mfma_f32_16x16x32_bf16 v[68:71], v[166:169], v[210:213], v[68:71]
	v_mfma_f32_16x16x32_bf16 v[64:67], v[174:177], v[210:213], v[64:67]
	v_mfma_f32_16x16x32_bf16 v[116:119], v[170:173], v[186:189], v[116:119]
	v_mfma_f32_16x16x32_bf16 v[112:115], v[178:181], v[186:189], v[112:115]
	v_mfma_f32_16x16x32_bf16 v[100:103], v[170:173], v[198:201], v[100:103]
	v_mfma_f32_16x16x32_bf16 v[96:99], v[178:181], v[198:201], v[96:99]
	v_mfma_f32_16x16x32_bf16 v[84:87], v[170:173], v[206:209], v[84:87]
	v_mfma_f32_16x16x32_bf16 v[80:83], v[178:181], v[206:209], v[80:83]
	v_mfma_f32_16x16x32_bf16 v[68:71], v[170:173], v[214:217], v[68:71]
	v_mfma_f32_16x16x32_bf16 v[64:67], v[178:181], v[214:217], v[64:67]
	s_barrier
	s_setprio 0
	s_add_u32 s98, s26, s12
	s_addc_u32 s99, s27, s13
	s_add_u32 s100, s28, s12
	s_addc_u32 s101, s29, s13
	s_add_i32 s54, s43, s34
	s_mov_b32 m0, s54
	ds_read_b128 v[182:185], v148 offset:16384
	ds_read_b128 v[186:189], v148 offset:17408
	ds_read_b128 v[194:197], v148 offset:18432
	ds_read_b128 v[198:201], v148 offset:19456
	ds_read_b128 v[202:205], v148 offset:20480
	ds_read_b128 v[206:209], v148 offset:21504
	ds_read_b128 v[210:213], v148 offset:22528
	ds_read_b128 v[214:217], v148 offset:23552
	global_load_lds_dwordx4 v132, s[26:27]
	s_add_i32 m0, s54, 0x2000
	s_add_u32 s54, s26, 0x20000
	s_addc_u32 s55, s27, 0
	s_add_i32 s56, s44, s34
	global_load_lds_dwordx4 v128, s[26:27]
	s_mov_b32 m0, s56
	s_nop 0
	global_load_lds_dwordx4 v132, s[54:55]
	s_add_i32 m0, s56, 0x2000
	s_nop 0
	global_load_lds_dwordx4 v128, s[54:55]
	s_waitcnt vmcnt(6)
	s_waitcnt lgkmcnt(0)
	s_setprio 1
	s_barrier
	v_mfma_f32_16x16x32_bf16 v[60:63], v[150:153], v[182:185], v[60:63]
	v_mfma_f32_16x16x32_bf16 v[56:59], v[158:161], v[182:185], v[56:59]
	v_mfma_f32_16x16x32_bf16 v[44:47], v[150:153], v[194:197], v[44:47]
	v_mfma_f32_16x16x32_bf16 v[40:43], v[158:161], v[194:197], v[40:43]
	v_mfma_f32_16x16x32_bf16 v[28:31], v[150:153], v[202:205], v[28:31]
	v_mfma_f32_16x16x32_bf16 v[24:27], v[158:161], v[202:205], v[24:27]
	v_mfma_f32_16x16x32_bf16 v[12:15], v[150:153], v[210:213], v[12:15]
	v_mfma_f32_16x16x32_bf16 v[8:11], v[158:161], v[210:213], v[8:11]
	v_mfma_f32_16x16x32_bf16 v[60:63], v[154:157], v[186:189], v[60:63]
	v_mfma_f32_16x16x32_bf16 v[56:59], v[162:165], v[186:189], v[56:59]
	v_mfma_f32_16x16x32_bf16 v[44:47], v[154:157], v[198:201], v[44:47]
	v_mfma_f32_16x16x32_bf16 v[40:43], v[162:165], v[198:201], v[40:43]
	v_mfma_f32_16x16x32_bf16 v[28:31], v[154:157], v[206:209], v[28:31]
	v_mfma_f32_16x16x32_bf16 v[24:27], v[162:165], v[206:209], v[24:27]
	v_mfma_f32_16x16x32_bf16 v[12:15], v[154:157], v[214:217], v[12:15]
	v_mfma_f32_16x16x32_bf16 v[8:11], v[162:165], v[214:217], v[8:11]
	v_mfma_f32_16x16x32_bf16 v[52:55], v[166:169], v[182:185], v[52:55]
	v_mfma_f32_16x16x32_bf16 v[48:51], v[174:177], v[182:185], v[48:51]
	v_mfma_f32_16x16x32_bf16 v[36:39], v[166:169], v[194:197], v[36:39]
	v_mfma_f32_16x16x32_bf16 v[32:35], v[174:177], v[194:197], v[32:35]
	v_mfma_f32_16x16x32_bf16 v[20:23], v[166:169], v[202:205], v[20:23]
	v_mfma_f32_16x16x32_bf16 v[16:19], v[174:177], v[202:205], v[16:19]
	v_mfma_f32_16x16x32_bf16 v[4:7], v[166:169], v[210:213], v[4:7]
	v_mfma_f32_16x16x32_bf16 v[0:3], v[174:177], v[210:213], v[0:3]
	v_mfma_f32_16x16x32_bf16 v[52:55], v[170:173], v[186:189], v[52:55]
	v_mfma_f32_16x16x32_bf16 v[48:51], v[178:181], v[186:189], v[48:51]
	v_mfma_f32_16x16x32_bf16 v[36:39], v[170:173], v[198:201], v[36:39]
	v_mfma_f32_16x16x32_bf16 v[32:35], v[178:181], v[198:201], v[32:35]
	v_mfma_f32_16x16x32_bf16 v[20:23], v[170:173], v[206:209], v[20:23]
	v_mfma_f32_16x16x32_bf16 v[16:19], v[178:181], v[206:209], v[16:19]
	v_mfma_f32_16x16x32_bf16 v[4:7], v[170:173], v[214:217], v[4:7]
	v_mfma_f32_16x16x32_bf16 v[0:3], v[178:181], v[214:217], v[0:3]
	s_barrier
; #define PG8_STAGE(bufoff, gbase, voff) do { _Pragma("unroll") for (int _i = 0; _i < 2; ++_i) \
;         __builtin_amdgcn_global_load_lds((const unsigned*)((const char*)(gbase) + (voff)[_i]), (LAS unsigned*)(lds + (bufoff) + ldsw + _i * 8192), 16, 0, ((voff) == voffA ? AUXA : 0)); } while (0)
; #define PG8_LDA(dst, b, h) do { _Pragma("unroll") for (int m = 0; m < 4; ++m) _Pragma("unroll") for (int k = 0; k < 2; ++k) dst[m][k] = *(const LAS bf16x8*)(lds + PG8_SA(b, h) + aoff + m * 2048 + k * 1024); } while (0)
; #define PG8_LDB(dst, b, h) do { _Pragma("unroll") for (int n = 0; n < 2; ++n) _Pragma("unroll") for (int k = 0; k < 2; ++k) dst[n][k] = *(const LAS bf16x8*)(lds + PG8_SB(b, h) + boff + n * 2048 + k * 1024); } while (0)
; #define PG8_MMA(ai, bj, At, Bt) do { __builtin_amdgcn_s_setprio(1); _Pragma("unroll") for (int m = 0; m < 4; ++m) _Pragma("unroll") for (int n = 0; n < 2; ++n) _Pragma("unroll") for (int k = 0; k < 2; ++k) \
;         acc[ai][bj][m][n] = __builtin_amdgcn_mfma_f32_16x16x32_bf16(Bt[n][k], At[m][k], acc[ai][bj][m][n], 0, 0, 0); __builtin_amdgcn_s_setprio(0); } while (0)
; #define PG8_WAIT_V(n) asm volatile("s_waitcnt vmcnt(" #n ")" ::: "memory")
; #define PG8_WAIT_L(n) asm volatile("s_waitcnt lgkmcnt(" #n ")" ::: "memory")
; #define PG8_BAR __builtin_amdgcn_s_barrier()
; #define PG8_SCHED __builtin_amdgcn_sched_barrier(0)
;     ...
;             PG8_WAIT_L(0); PG8_BAR; PG8_MMA(1, 0, At, B0); PG8_MMA(1, 1, At, B1); PG8_BAR; PG8_SCHED;
;             PG8_LDB(B0, 1, 0); PG8_LDB(B1, 1, 1); PG8_SCHED; PG8_LDA(At, 1, 0); PG8_STAGE(PG8_SA(0, 1), a2 + hsA, voffA);
;             PG8_WAIT_V(8); PG8_WAIT_L(0); PG8_BAR; PG8_MMA(0, 0, At, B0); PG8_MMA(0, 1, At, B1); PG8_BAR; PG8_SCHED;
;             PG8_LDA(At, 1, 1); PG8_STAGE(PG8_SB(1, 0), b3, voffB); PG8_STAGE(PG8_SB(1, 1), b3 + hsB, voffB); PG8_STAGE(PG8_SA(1, 0), a3, voffA);
;             PG8_WAIT_V(8); PG8_WAIT_L(0); PG8_BAR; PG8_MMA(1, 0, At, B0); PG8_MMA(1, 1, At, B1); PG8_BAR; PG8_SCHED;
;         }
	s_mov_b32 m0, s3
	s_nop 0
	global_load_lds_dwordx4 v134, s[28:29]
	s_mov_b32 m0, s35
	s_nop 0
	global_load_lds_dwordx4 v130, s[28:29]
	s_setprio 0
	s_add_i32 s54, 0, 0x18000
	v_add_u32_e32 v149, s54, v143
	s_add_i32 s55, 0, 0x1c000
	ds_read_b128 v[150:153], v149
	ds_read_b128 v[154:157], v149 offset:1024
	ds_read_b128 v[158:161], v149 offset:2048
	ds_read_b128 v[162:165], v149 offset:3072
	v_add_u32_e32 v149, s55, v143
	ds_read_b128 v[166:169], v149
	ds_read_b128 v[170:173], v149 offset:1024
	ds_read_b128 v[174:177], v149 offset:2048
	ds_read_b128 v[178:181], v149 offset:3072
	s_add_u32 s28, s28, 0x20000
	s_addc_u32 s29, s29, 0
	s_mov_b32 m0, s36
	ds_read_b128 v[182:185], v148 offset:32768
	ds_read_b128 v[186:189], v148 offset:33792
	ds_read_b128 v[194:197], v148 offset:34816
	ds_read_b128 v[198:201], v148 offset:35840
	ds_read_b128 v[202:205], v148 offset:36864
	ds_read_b128 v[206:209], v148 offset:37888
	ds_read_b128 v[210:213], v148 offset:38912
	ds_read_b128 v[214:217], v148 offset:39936
	global_load_lds_dwordx4 v134, s[28:29]
	s_mov_b32 m0, s37
	s_nop 0
	global_load_lds_dwordx4 v130, s[28:29]
	s_waitcnt vmcnt(8)
	s_waitcnt lgkmcnt(0)
	s_setprio 1
	s_barrier
	v_mfma_f32_16x16x32_bf16 v[124:127], v[150:153], v[182:185], v[124:127]
	v_mfma_f32_16x16x32_bf16 v[120:123], v[158:161], v[182:185], v[120:123]
	v_mfma_f32_16x16x32_bf16 v[108:111], v[150:153], v[194:197], v[108:111]
	v_mfma_f32_16x16x32_bf16 v[104:107], v[158:161], v[194:197], v[104:107]
	v_mfma_f32_16x16x32_bf16 v[92:95], v[150:153], v[202:205], v[92:95]
	v_mfma_f32_16x16x32_bf16 v[88:91], v[158:161], v[202:205], v[88:91]
	v_mfma_f32_16x16x32_bf16 v[76:79], v[150:153], v[210:213], v[76:79]
	v_mfma_f32_16x16x32_bf16 v[72:75], v[158:161], v[210:213], v[72:75]
	v_mfma_f32_16x16x32_bf16 v[124:127], v[154:157], v[186:189], v[124:127]
	v_mfma_f32_16x16x32_bf16 v[120:123], v[162:165], v[186:189], v[120:123]
	v_mfma_f32_16x16x32_bf16 v[108:111], v[154:157], v[198:201], v[108:111]
	v_mfma_f32_16x16x32_bf16 v[104:107], v[162:165], v[198:201], v[104:107]
	v_mfma_f32_16x16x32_bf16 v[92:95], v[154:157], v[206:209], v[92:95]
	v_mfma_f32_16x16x32_bf16 v[88:91], v[162:165], v[206:209], v[88:91]
	v_mfma_f32_16x16x32_bf16 v[76:79], v[154:157], v[214:217], v[76:79]
	v_mfma_f32_16x16x32_bf16 v[72:75], v[162:165], v[214:217], v[72:75]
	v_mfma_f32_16x16x32_bf16 v[116:119], v[166:169], v[182:185], v[116:119]
	v_mfma_f32_16x16x32_bf16 v[112:115], v[174:177], v[182:185], v[112:115]
	v_mfma_f32_16x16x32_bf16 v[100:103], v[166:169], v[194:197], v[100:103]
	v_mfma_f32_16x16x32_bf16 v[96:99], v[174:177], v[194:197], v[96:99]
	v_mfma_f32_16x16x32_bf16 v[84:87], v[166:169], v[202:205], v[84:87]
	v_mfma_f32_16x16x32_bf16 v[80:83], v[174:177], v[202:205], v[80:83]
	v_mfma_f32_16x16x32_bf16 v[68:71], v[166:169], v[210:213], v[68:71]
	v_mfma_f32_16x16x32_bf16 v[64:67], v[174:177], v[210:213], v[64:67]
	v_mfma_f32_16x16x32_bf16 v[116:119], v[170:173], v[186:189], v[116:119]
	v_mfma_f32_16x16x32_bf16 v[112:115], v[178:181], v[186:189], v[112:115]
	v_mfma_f32_16x16x32_bf16 v[100:103], v[170:173], v[198:201], v[100:103]
	v_mfma_f32_16x16x32_bf16 v[96:99], v[178:181], v[198:201], v[96:99]
	v_mfma_f32_16x16x32_bf16 v[84:87], v[170:173], v[206:209], v[84:87]
	v_mfma_f32_16x16x32_bf16 v[80:83], v[178:181], v[206:209], v[80:83]
	v_mfma_f32_16x16x32_bf16 v[68:71], v[170:173], v[214:217], v[68:71]
	v_mfma_f32_16x16x32_bf16 v[64:67], v[178:181], v[214:217], v[64:67]
	s_barrier
	s_setprio 0
	s_add_i32 s28, s54, s34
	s_mov_b32 m0, s28
	ds_read_b128 v[182:185], v148 offset:49152
	ds_read_b128 v[186:189], v148 offset:50176
	ds_read_b128 v[194:197], v148 offset:51200
	ds_read_b128 v[198:201], v148 offset:52224
	ds_read_b128 v[202:205], v148 offset:53248
	ds_read_b128 v[206:209], v148 offset:54272
	ds_read_b128 v[210:213], v148 offset:55296
	ds_read_b128 v[214:217], v148 offset:56320
	global_load_lds_dwordx4 v132, s[98:99]
	s_add_i32 m0, s28, 0x2000
	s_add_u32 s26, s26, 0x20080
	s_addc_u32 s27, s27, 0
	s_add_i32 s28, s55, s34
	global_load_lds_dwordx4 v128, s[98:99]
	s_mov_b32 m0, s28
	s_nop 0
	global_load_lds_dwordx4 v132, s[26:27]
	s_add_i32 m0, s28, 0x2000
	s_nop 0
	global_load_lds_dwordx4 v128, s[26:27]
	s_waitcnt vmcnt(6)
	s_waitcnt lgkmcnt(0)
	s_setprio 1
	s_barrier
	v_mfma_f32_16x16x32_bf16 v[60:63], v[150:153], v[182:185], v[60:63]
	v_mfma_f32_16x16x32_bf16 v[56:59], v[158:161], v[182:185], v[56:59]
	v_mfma_f32_16x16x32_bf16 v[44:47], v[150:153], v[194:197], v[44:47]
	v_mfma_f32_16x16x32_bf16 v[40:43], v[158:161], v[194:197], v[40:43]
	v_mfma_f32_16x16x32_bf16 v[28:31], v[150:153], v[202:205], v[28:31]
	v_mfma_f32_16x16x32_bf16 v[24:27], v[158:161], v[202:205], v[24:27]
	v_mfma_f32_16x16x32_bf16 v[12:15], v[150:153], v[210:213], v[12:15]
	v_mfma_f32_16x16x32_bf16 v[8:11], v[158:161], v[210:213], v[8:11]
	v_mfma_f32_16x16x32_bf16 v[60:63], v[154:157], v[186:189], v[60:63]
	v_mfma_f32_16x16x32_bf16 v[56:59], v[162:165], v[186:189], v[56:59]
	v_mfma_f32_16x16x32_bf16 v[44:47], v[154:157], v[198:201], v[44:47]
	v_mfma_f32_16x16x32_bf16 v[40:43], v[162:165], v[198:201], v[40:43]
	v_mfma_f32_16x16x32_bf16 v[28:31], v[154:157], v[206:209], v[28:31]
	v_mfma_f32_16x16x32_bf16 v[24:27], v[162:165], v[206:209], v[24:27]
	v_mfma_f32_16x16x32_bf16 v[12:15], v[154:157], v[214:217], v[12:15]
	v_mfma_f32_16x16x32_bf16 v[8:11], v[162:165], v[214:217], v[8:11]
	v_mfma_f32_16x16x32_bf16 v[52:55], v[166:169], v[182:185], v[52:55]
	v_mfma_f32_16x16x32_bf16 v[48:51], v[174:177], v[182:185], v[48:51]
	v_mfma_f32_16x16x32_bf16 v[36:39], v[166:169], v[194:197], v[36:39]
	v_mfma_f32_16x16x32_bf16 v[32:35], v[174:177], v[194:197], v[32:35]
	v_mfma_f32_16x16x32_bf16 v[20:23], v[166:169], v[202:205], v[20:23]
	v_mfma_f32_16x16x32_bf16 v[16:19], v[174:177], v[202:205], v[16:19]
	v_mfma_f32_16x16x32_bf16 v[4:7], v[166:169], v[210:213], v[4:7]
	v_mfma_f32_16x16x32_bf16 v[0:3], v[174:177], v[210:213], v[0:3]
	v_mfma_f32_16x16x32_bf16 v[52:55], v[170:173], v[186:189], v[52:55]
	v_mfma_f32_16x16x32_bf16 v[48:51], v[178:181], v[186:189], v[48:51]
	v_mfma_f32_16x16x32_bf16 v[36:39], v[170:173], v[198:201], v[36:39]
	v_mfma_f32_16x16x32_bf16 v[32:35], v[178:181], v[198:201], v[32:35]
	v_mfma_f32_16x16x32_bf16 v[20:23], v[170:173], v[206:209], v[20:23]
	v_mfma_f32_16x16x32_bf16 v[16:19], v[178:181], v[206:209], v[16:19]
	v_mfma_f32_16x16x32_bf16 v[4:7], v[170:173], v[214:217], v[4:7]
	v_mfma_f32_16x16x32_bf16 v[0:3], v[178:181], v[214:217], v[0:3]
	s_barrier
	s_setprio 0
	s_add_u32 s24, s24, 0x100
	s_addc_u32 s25, s25, 0
	s_add_u32 s51, s51, 0x100
	s_addc_u32 s52, s52, 0
	s_cmp_ge_i32 s53, s39
	s_mov_b32 s26, s53
	s_cbranch_scc0 .LBB0_887

; #define PG8_STAGE(bufoff, gbase, voff) do { _Pragma("unroll") for (int _i = 0; _i < 2; ++_i) \
;         __builtin_amdgcn_global_load_lds((const unsigned*)((const char*)(gbase) + (voff)[_i]), (LAS unsigned*)(lds + (bufoff) + ldsw + _i * 8192), 16, 0, ((voff) == voffA ? AUXA : 0)); } while (0)
; #define PG8_LDA(dst, b, h) do { _Pragma("unroll") for (int m = 0; m < 4; ++m) _Pragma("unroll") for (int k = 0; k < 2; ++k) dst[m][k] = *(const LAS bf16x8*)(lds + PG8_SA(b, h) + aoff + m * 2048 + k * 1024); } while (0)
; #define PG8_LDB(dst, b, h) do { _Pragma("unroll") for (int n = 0; n < 2; ++n) _Pragma("unroll") for (int k = 0; k < 2; ++k) dst[n][k] = *(const LAS bf16x8*)(lds + PG8_SB(b, h) + boff + n * 2048 + k * 1024); } while (0)
; #define PG8_MMA(ai, bj, At, Bt) do { __builtin_amdgcn_s_setprio(1); _Pragma("unroll") for (int m = 0; m < 4; ++m) _Pragma("unroll") for (int n = 0; n < 2; ++n) _Pragma("unroll") for (int k = 0; k < 2; ++k) \
;         acc[ai][bj][m][n] = __builtin_amdgcn_mfma_f32_16x16x32_bf16(Bt[n][k], At[m][k], acc[ai][bj][m][n], 0, 0, 0); __builtin_amdgcn_s_setprio(0); } while (0)
; #define PG8_WAIT_V(n) asm volatile("s_waitcnt vmcnt(" #n ")" ::: "memory")
; #define PG8_WAIT_L(n) asm volatile("s_waitcnt lgkmcnt(" #n ")" ::: "memory")
; #define PG8_BAR __builtin_amdgcn_s_barrier()
; #define PG8_SCHED __builtin_amdgcn_sched_barrier(0)
;     ...
;         for (int t = 0; t < nt; t += 2) {
;             const bool last = (t == nt - 2);
;             const char* a1 = cA + (size_t)(t + 1) * kstep;
;             const char* a2 = last ? nA : cA + (size_t)(t + 2) * kstep; const char* b2 = last ? nB : cB + (size_t)(t + 2) * kstep;
;             const char* a3 = a2 + kstep; const char* b3 = b2 + kstep;
;             PG8_LDB(B0, 0, 0); PG8_LDB(B1, 0, 1); PG8_SCHED; PG8_LDA(At, 0, 0); PG8_STAGE(PG8_SA(1, 1), a1 + hsA, voffA);
;             if (Epi::NPRE != 0 && last) { E.pre(sv, cur, wr, fr); PG8_WAIT_V(16); } else { PG8_WAIT_V(8); }
;             PG8_WAIT_L(0); PG8_BAR; PG8_MMA(0, 0, At, B0); PG8_MMA(0, 1, At, B1); PG8_BAR; PG8_SCHED;
;             PG8_LDA(At, 0, 1); PG8_STAGE(PG8_SB(0, 0), b2, voffB); PG8_STAGE(PG8_SB(0, 1), b2 + hsB, voffB); PG8_STAGE(PG8_SA(0, 0), a2, voffA);
;             if (Epi::NPRE != 0 && last) { PG8_WAIT_V(16); } else { PG8_WAIT_V(8); }
;             PG8_WAIT_L(0); PG8_BAR; PG8_MMA(1, 0, At, B0); PG8_MMA(1, 1, At, B1); PG8_BAR; PG8_SCHED;
.LBB0_959:
	s_add_u32 s98, s28, 0xfffc0000
	s_addc_u32 s99, s29, -1
	s_mov_b32 m0, s40
	s_nop 0
	global_load_lds_dwordx4 v170, s[98:99]
	s_mov_b32 m0, s41
	s_nop 0
	global_load_lds_dwordx4 v166, s[98:99]
	ds_read_b128 v[88:91], v196
	ds_read_b128 v[92:95], v196 offset:1024
	ds_read_b128 v[104:107], v196 offset:2048
	ds_read_b128 v[108:111], v196 offset:3072
	ds_read_b128 v[144:147], v197
	ds_read_b128 v[148:151], v197 offset:1024
	ds_read_b128 v[152:155], v197 offset:2048
	ds_read_b128 v[156:159], v197 offset:3072
	s_add_i32 s51, s30, 2
	s_add_u32 s31, s28, 0xfffc0080
	s_addc_u32 s34, s29, -1
	s_cmp_eq_u32 s42, s30
	s_cselect_b32 s30, s48, s49
	s_cselect_b32 s35, s19, s34
	s_cselect_b32 s34, s21, s31
	s_cselect_b32 s31, s47, s50
	s_add_i32 m0, s5, 0xc000
	ds_read_b128 v[160:163], v198
	ds_read_b128 v[180:183], v198 offset:1024
	ds_read_b128 v[184:187], v198 offset:2048
	ds_read_b128 v[188:191], v198 offset:3072
	ds_read_b128 v[200:203], v198 offset:4096
	ds_read_b128 v[204:207], v198 offset:5120
	ds_read_b128 v[208:211], v198 offset:6144
	ds_read_b128 v[212:215], v198 offset:7168
	global_load_lds_dwordx4 v172, s[28:29]
	s_add_i32 m0, s5, 0xe000
	s_nop 0
	global_load_lds_dwordx4 v174, s[28:29]
	s_waitcnt vmcnt(8)
	s_waitcnt lgkmcnt(0)
	s_setprio 1
	s_barrier
	v_mfma_f32_16x16x32_bf16 v[136:139], v[88:91], v[160:163], v[136:139]
	v_mfma_f32_16x16x32_bf16 v[140:143], v[104:107], v[160:163], v[140:143]
	v_mfma_f32_16x16x32_bf16 v[124:127], v[88:91], v[184:187], v[124:127]
	v_mfma_f32_16x16x32_bf16 v[120:123], v[104:107], v[184:187], v[120:123]
	v_mfma_f32_16x16x32_bf16 v[100:103], v[88:91], v[200:203], v[100:103]
	v_mfma_f32_16x16x32_bf16 v[96:99], v[104:107], v[200:203], v[96:99]
	v_mfma_f32_16x16x32_bf16 v[76:79], v[88:91], v[208:211], v[76:79]
	v_mfma_f32_16x16x32_bf16 v[72:75], v[104:107], v[208:211], v[72:75]
	v_mfma_f32_16x16x32_bf16 v[136:139], v[92:95], v[180:183], v[136:139]
	v_mfma_f32_16x16x32_bf16 v[140:143], v[108:111], v[180:183], v[140:143]
	v_mfma_f32_16x16x32_bf16 v[124:127], v[92:95], v[188:191], v[124:127]
	v_mfma_f32_16x16x32_bf16 v[120:123], v[108:111], v[188:191], v[120:123]
	v_mfma_f32_16x16x32_bf16 v[100:103], v[92:95], v[204:207], v[100:103]
	v_mfma_f32_16x16x32_bf16 v[96:99], v[108:111], v[204:207], v[96:99]
	v_mfma_f32_16x16x32_bf16 v[76:79], v[92:95], v[212:215], v[76:79]
	v_mfma_f32_16x16x32_bf16 v[72:75], v[108:111], v[212:215], v[72:75]
	v_mfma_f32_16x16x32_bf16 v[132:135], v[144:147], v[160:163], v[132:135]
	v_mfma_f32_16x16x32_bf16 v[128:131], v[152:155], v[160:163], v[128:131]
	v_mfma_f32_16x16x32_bf16 v[116:119], v[144:147], v[184:187], v[116:119]
	v_mfma_f32_16x16x32_bf16 v[112:115], v[152:155], v[184:187], v[112:115]
	v_mfma_f32_16x16x32_bf16 v[84:87], v[144:147], v[200:203], v[84:87]
	v_mfma_f32_16x16x32_bf16 v[80:83], v[152:155], v[200:203], v[80:83]
	v_mfma_f32_16x16x32_bf16 v[68:71], v[144:147], v[208:211], v[68:71]
	v_mfma_f32_16x16x32_bf16 v[64:67], v[152:155], v[208:211], v[64:67]
	v_mfma_f32_16x16x32_bf16 v[132:135], v[148:151], v[180:183], v[132:135]
	v_mfma_f32_16x16x32_bf16 v[128:131], v[156:159], v[180:183], v[128:131]
	v_mfma_f32_16x16x32_bf16 v[116:119], v[148:151], v[188:191], v[116:119]
	v_mfma_f32_16x16x32_bf16 v[112:115], v[156:159], v[188:191], v[112:115]
	v_mfma_f32_16x16x32_bf16 v[84:87], v[148:151], v[204:207], v[84:87]
	v_mfma_f32_16x16x32_bf16 v[80:83], v[156:159], v[204:207], v[80:83]
	v_mfma_f32_16x16x32_bf16 v[68:71], v[148:151], v[212:215], v[68:71]
	v_mfma_f32_16x16x32_bf16 v[64:67], v[156:159], v[212:215], v[64:67]
	s_barrier
	s_setprio 0
	s_add_u32 s98, s30, s12
	s_addc_u32 s99, s31, s13
	s_add_u32 s100, s34, s12
	s_addc_u32 s101, s35, s13
	s_add_i32 s52, s44, s3
	s_mov_b32 m0, s52
	ds_read_b128 v[160:163], v198 offset:16384
	ds_read_b128 v[180:183], v198 offset:17408
	ds_read_b128 v[184:187], v198 offset:18432
	ds_read_b128 v[188:191], v198 offset:19456
	ds_read_b128 v[200:203], v198 offset:20480
	ds_read_b128 v[204:207], v198 offset:21504
	ds_read_b128 v[208:211], v198 offset:22528
	ds_read_b128 v[212:215], v198 offset:23552
	global_load_lds_dwordx4 v168, s[30:31]
	s_add_i32 m0, s52, 0x2000
	s_add_u32 s52, s30, 0x40000
	s_addc_u32 s53, s31, 0
	s_add_i32 s54, s45, s3
	global_load_lds_dwordx4 v164, s[30:31]
	s_mov_b32 m0, s54
	s_nop 0
	global_load_lds_dwordx4 v168, s[52:53]
	s_add_i32 m0, s54, 0x2000
	s_nop 0
	global_load_lds_dwordx4 v164, s[52:53]
	s_waitcnt vmcnt(6)
	s_waitcnt lgkmcnt(0)
	s_setprio 1
	s_barrier
	v_mfma_f32_16x16x32_bf16 v[60:63], v[88:91], v[160:163], v[60:63]
	v_mfma_f32_16x16x32_bf16 v[56:59], v[104:107], v[160:163], v[56:59]
	v_mfma_f32_16x16x32_bf16 v[44:47], v[88:91], v[184:187], v[44:47]
	v_mfma_f32_16x16x32_bf16 v[40:43], v[104:107], v[184:187], v[40:43]
	v_mfma_f32_16x16x32_bf16 v[28:31], v[88:91], v[200:203], v[28:31]
	v_mfma_f32_16x16x32_bf16 v[24:27], v[104:107], v[200:203], v[24:27]
	v_mfma_f32_16x16x32_bf16 v[12:15], v[88:91], v[208:211], v[12:15]
	v_mfma_f32_16x16x32_bf16 v[8:11], v[104:107], v[208:211], v[8:11]
	v_mfma_f32_16x16x32_bf16 v[60:63], v[92:95], v[180:183], v[60:63]
	v_mfma_f32_16x16x32_bf16 v[56:59], v[108:111], v[180:183], v[56:59]
	v_mfma_f32_16x16x32_bf16 v[44:47], v[92:95], v[188:191], v[44:47]
	v_mfma_f32_16x16x32_bf16 v[40:43], v[108:111], v[188:191], v[40:43]
	v_mfma_f32_16x16x32_bf16 v[28:31], v[92:95], v[204:207], v[28:31]
	v_mfma_f32_16x16x32_bf16 v[24:27], v[108:111], v[204:207], v[24:27]
	v_mfma_f32_16x16x32_bf16 v[12:15], v[92:95], v[212:215], v[12:15]
	v_mfma_f32_16x16x32_bf16 v[8:11], v[108:111], v[212:215], v[8:11]
	v_mfma_f32_16x16x32_bf16 v[52:55], v[144:147], v[160:163], v[52:55]
	v_mfma_f32_16x16x32_bf16 v[48:51], v[152:155], v[160:163], v[48:51]
	v_mfma_f32_16x16x32_bf16 v[36:39], v[144:147], v[184:187], v[36:39]
	v_mfma_f32_16x16x32_bf16 v[32:35], v[152:155], v[184:187], v[32:35]
	v_mfma_f32_16x16x32_bf16 v[20:23], v[144:147], v[200:203], v[20:23]
	v_mfma_f32_16x16x32_bf16 v[16:19], v[152:155], v[200:203], v[16:19]
	v_mfma_f32_16x16x32_bf16 v[4:7], v[144:147], v[208:211], v[4:7]
	v_mfma_f32_16x16x32_bf16 v[0:3], v[152:155], v[208:211], v[0:3]
	v_mfma_f32_16x16x32_bf16 v[52:55], v[148:151], v[180:183], v[52:55]
	v_mfma_f32_16x16x32_bf16 v[48:51], v[156:159], v[180:183], v[48:51]
	v_mfma_f32_16x16x32_bf16 v[36:39], v[148:151], v[188:191], v[36:39]
	v_mfma_f32_16x16x32_bf16 v[32:35], v[156:159], v[188:191], v[32:35]
	v_mfma_f32_16x16x32_bf16 v[20:23], v[148:151], v[204:207], v[20:23]
	v_mfma_f32_16x16x32_bf16 v[16:19], v[156:159], v[204:207], v[16:19]
	v_mfma_f32_16x16x32_bf16 v[4:7], v[148:151], v[212:215], v[4:7]
	v_mfma_f32_16x16x32_bf16 v[0:3], v[156:159], v[212:215], v[0:3]
	s_barrier
; #define PG8_STAGE(bufoff, gbase, voff) do { _Pragma("unroll") for (int _i = 0; _i < 2; ++_i) \
;         __builtin_amdgcn_global_load_lds((const unsigned*)((const char*)(gbase) + (voff)[_i]), (LAS unsigned*)(lds + (bufoff) + ldsw + _i * 8192), 16, 0, ((voff) == voffA ? AUXA : 0)); } while (0)
; #define PG8_LDA(dst, b, h) do { _Pragma("unroll") for (int m = 0; m < 4; ++m) _Pragma("unroll") for (int k = 0; k < 2; ++k) dst[m][k] = *(const LAS bf16x8*)(lds + PG8_SA(b, h) + aoff + m * 2048 + k * 1024); } while (0)
; #define PG8_LDB(dst, b, h) do { _Pragma("unroll") for (int n = 0; n < 2; ++n) _Pragma("unroll") for (int k = 0; k < 2; ++k) dst[n][k] = *(const LAS bf16x8*)(lds + PG8_SB(b, h) + boff + n * 2048 + k * 1024); } while (0)
; #define PG8_MMA(ai, bj, At, Bt) do { __builtin_amdgcn_s_setprio(1); _Pragma("unroll") for (int m = 0; m < 4; ++m) _Pragma("unroll") for (int n = 0; n < 2; ++n) _Pragma("unroll") for (int k = 0; k < 2; ++k) \
;         acc[ai][bj][m][n] = __builtin_amdgcn_mfma_f32_16x16x32_bf16(Bt[n][k], At[m][k], acc[ai][bj][m][n], 0, 0, 0); __builtin_amdgcn_s_setprio(0); } while (0)
; #define PG8_WAIT_V(n) asm volatile("s_waitcnt vmcnt(" #n ")" ::: "memory")
; #define PG8_WAIT_L(n) asm volatile("s_waitcnt lgkmcnt(" #n ")" ::: "memory")
; #define PG8_BAR __builtin_amdgcn_s_barrier()
; #define PG8_SCHED __builtin_amdgcn_sched_barrier(0)
;     ...
;             PG8_WAIT_L(0); PG8_BAR; PG8_MMA(1, 0, At, B0); PG8_MMA(1, 1, At, B1); PG8_BAR; PG8_SCHED;
;             PG8_LDB(B0, 1, 0); PG8_LDB(B1, 1, 1); PG8_SCHED; PG8_LDA(At, 1, 0); PG8_STAGE(PG8_SA(0, 1), a2 + hsA, voffA);
;             PG8_WAIT_V(8); PG8_WAIT_L(0); PG8_BAR; PG8_MMA(0, 0, At, B0); PG8_MMA(0, 1, At, B1); PG8_BAR; PG8_SCHED;
;             PG8_LDA(At, 1, 1); PG8_STAGE(PG8_SB(1, 0), b3, voffB); PG8_STAGE(PG8_SB(1, 1), b3 + hsB, voffB); PG8_STAGE(PG8_SA(1, 0), a3, voffA);
;             PG8_WAIT_V(8); PG8_WAIT_L(0); PG8_BAR; PG8_MMA(1, 0, At, B0); PG8_MMA(1, 1, At, B1); PG8_BAR; PG8_SCHED;
;         }
	s_mov_b32 m0, s5
	s_nop 0
	global_load_lds_dwordx4 v170, s[34:35]
	s_mov_b32 m0, s27
	s_nop 0
	global_load_lds_dwordx4 v166, s[34:35]
	s_setprio 0
	s_add_i32 s52, 0, 0x18000
	s_add_i32 s53, 0, 0x1c000
	v_add_u32_e32 v108, s52, v194
	v_add_u32_e32 v156, s53, v194
	ds_read_b128 v[88:91], v108
	ds_read_b128 v[92:95], v108 offset:1024
	ds_read_b128 v[104:107], v108 offset:2048
	ds_read_b128 v[108:111], v108 offset:3072
	ds_read_b128 v[144:147], v156
	ds_read_b128 v[148:151], v156 offset:1024
	ds_read_b128 v[152:155], v156 offset:2048
	ds_read_b128 v[156:159], v156 offset:3072
	s_add_u32 s34, s34, 0x40000
	s_addc_u32 s35, s35, 0
	s_mov_b32 m0, s36
	ds_read_b128 v[160:163], v198 offset:32768
	ds_read_b128 v[180:183], v198 offset:33792
	ds_read_b128 v[184:187], v198 offset:34816
	ds_read_b128 v[188:191], v198 offset:35840
	ds_read_b128 v[200:203], v198 offset:36864
	ds_read_b128 v[204:207], v198 offset:37888
	ds_read_b128 v[208:211], v198 offset:38912
	ds_read_b128 v[212:215], v198 offset:39936
	global_load_lds_dwordx4 v170, s[34:35]
	s_mov_b32 m0, s37
	s_nop 0
	global_load_lds_dwordx4 v166, s[34:35]
	s_waitcnt vmcnt(8)
	s_waitcnt lgkmcnt(0)
	s_setprio 1
	s_barrier
	v_mfma_f32_16x16x32_bf16 v[136:139], v[88:91], v[160:163], v[136:139]
	v_mfma_f32_16x16x32_bf16 v[140:143], v[104:107], v[160:163], v[140:143]
	v_mfma_f32_16x16x32_bf16 v[124:127], v[88:91], v[184:187], v[124:127]
	v_mfma_f32_16x16x32_bf16 v[120:123], v[104:107], v[184:187], v[120:123]
	v_mfma_f32_16x16x32_bf16 v[100:103], v[88:91], v[200:203], v[100:103]
	v_mfma_f32_16x16x32_bf16 v[96:99], v[104:107], v[200:203], v[96:99]
	v_mfma_f32_16x16x32_bf16 v[76:79], v[88:91], v[208:211], v[76:79]
	v_mfma_f32_16x16x32_bf16 v[72:75], v[104:107], v[208:211], v[72:75]
	v_mfma_f32_16x16x32_bf16 v[136:139], v[92:95], v[180:183], v[136:139]
	v_mfma_f32_16x16x32_bf16 v[140:143], v[108:111], v[180:183], v[140:143]
	v_mfma_f32_16x16x32_bf16 v[124:127], v[92:95], v[188:191], v[124:127]
	v_mfma_f32_16x16x32_bf16 v[120:123], v[108:111], v[188:191], v[120:123]
	v_mfma_f32_16x16x32_bf16 v[100:103], v[92:95], v[204:207], v[100:103]
	v_mfma_f32_16x16x32_bf16 v[96:99], v[108:111], v[204:207], v[96:99]
	v_mfma_f32_16x16x32_bf16 v[76:79], v[92:95], v[212:215], v[76:79]
	v_mfma_f32_16x16x32_bf16 v[72:75], v[108:111], v[212:215], v[72:75]
	v_mfma_f32_16x16x32_bf16 v[132:135], v[144:147], v[160:163], v[132:135]
	v_mfma_f32_16x16x32_bf16 v[128:131], v[152:155], v[160:163], v[128:131]
	v_mfma_f32_16x16x32_bf16 v[116:119], v[144:147], v[184:187], v[116:119]
	v_mfma_f32_16x16x32_bf16 v[112:115], v[152:155], v[184:187], v[112:115]
	v_mfma_f32_16x16x32_bf16 v[84:87], v[144:147], v[200:203], v[84:87]
	v_mfma_f32_16x16x32_bf16 v[80:83], v[152:155], v[200:203], v[80:83]
	v_mfma_f32_16x16x32_bf16 v[68:71], v[144:147], v[208:211], v[68:71]
	v_mfma_f32_16x16x32_bf16 v[64:67], v[152:155], v[208:211], v[64:67]
	v_mfma_f32_16x16x32_bf16 v[132:135], v[148:151], v[180:183], v[132:135]
	v_mfma_f32_16x16x32_bf16 v[128:131], v[156:159], v[180:183], v[128:131]
	v_mfma_f32_16x16x32_bf16 v[116:119], v[148:151], v[188:191], v[116:119]
	v_mfma_f32_16x16x32_bf16 v[112:115], v[156:159], v[188:191], v[112:115]
	v_mfma_f32_16x16x32_bf16 v[84:87], v[148:151], v[204:207], v[84:87]
	v_mfma_f32_16x16x32_bf16 v[80:83], v[156:159], v[204:207], v[80:83]
	v_mfma_f32_16x16x32_bf16 v[68:71], v[148:151], v[212:215], v[68:71]
	v_mfma_f32_16x16x32_bf16 v[64:67], v[156:159], v[212:215], v[64:67]
	s_barrier
	s_setprio 0
	s_add_i32 s34, s52, s3
	s_mov_b32 m0, s34
	ds_read_b128 v[160:163], v198 offset:49152
	ds_read_b128 v[180:183], v198 offset:50176
	ds_read_b128 v[184:187], v198 offset:51200
	ds_read_b128 v[188:191], v198 offset:52224
	ds_read_b128 v[200:203], v198 offset:53248
	ds_read_b128 v[204:207], v198 offset:54272
	ds_read_b128 v[208:211], v198 offset:55296
	ds_read_b128 v[212:215], v198 offset:56320
	global_load_lds_dwordx4 v168, s[98:99]
	s_add_i32 m0, s34, 0x2000
	s_add_u32 s30, s30, 0x40080
	s_addc_u32 s31, s31, 0
	s_add_i32 s34, s53, s3
	global_load_lds_dwordx4 v164, s[98:99]
	s_mov_b32 m0, s34
	s_nop 0
	global_load_lds_dwordx4 v168, s[30:31]
	s_add_i32 m0, s34, 0x2000
	s_nop 0
	global_load_lds_dwordx4 v164, s[30:31]
	s_waitcnt vmcnt(6)
	s_waitcnt lgkmcnt(0)
	s_setprio 1
	s_barrier
	v_mfma_f32_16x16x32_bf16 v[60:63], v[88:91], v[160:163], v[60:63]
	v_mfma_f32_16x16x32_bf16 v[56:59], v[104:107], v[160:163], v[56:59]
	v_mfma_f32_16x16x32_bf16 v[44:47], v[88:91], v[184:187], v[44:47]
	v_mfma_f32_16x16x32_bf16 v[40:43], v[104:107], v[184:187], v[40:43]
	v_mfma_f32_16x16x32_bf16 v[28:31], v[88:91], v[200:203], v[28:31]
	v_mfma_f32_16x16x32_bf16 v[24:27], v[104:107], v[200:203], v[24:27]
	v_mfma_f32_16x16x32_bf16 v[12:15], v[88:91], v[208:211], v[12:15]
	v_mfma_f32_16x16x32_bf16 v[8:11], v[104:107], v[208:211], v[8:11]
	v_mfma_f32_16x16x32_bf16 v[60:63], v[92:95], v[180:183], v[60:63]
	v_mfma_f32_16x16x32_bf16 v[56:59], v[108:111], v[180:183], v[56:59]
	v_mfma_f32_16x16x32_bf16 v[44:47], v[92:95], v[188:191], v[44:47]
	v_mfma_f32_16x16x32_bf16 v[40:43], v[108:111], v[188:191], v[40:43]
	v_mfma_f32_16x16x32_bf16 v[28:31], v[92:95], v[204:207], v[28:31]
	v_mfma_f32_16x16x32_bf16 v[24:27], v[108:111], v[204:207], v[24:27]
	v_mfma_f32_16x16x32_bf16 v[12:15], v[92:95], v[212:215], v[12:15]
	v_mfma_f32_16x16x32_bf16 v[8:11], v[108:111], v[212:215], v[8:11]
	v_mfma_f32_16x16x32_bf16 v[52:55], v[144:147], v[160:163], v[52:55]
	v_mfma_f32_16x16x32_bf16 v[48:51], v[152:155], v[160:163], v[48:51]
	v_mfma_f32_16x16x32_bf16 v[36:39], v[144:147], v[184:187], v[36:39]
	v_mfma_f32_16x16x32_bf16 v[32:35], v[152:155], v[184:187], v[32:35]
	v_mfma_f32_16x16x32_bf16 v[20:23], v[144:147], v[200:203], v[20:23]
	v_mfma_f32_16x16x32_bf16 v[16:19], v[152:155], v[200:203], v[16:19]
	v_mfma_f32_16x16x32_bf16 v[4:7], v[144:147], v[208:211], v[4:7]
	v_mfma_f32_16x16x32_bf16 v[0:3], v[152:155], v[208:211], v[0:3]
	v_mfma_f32_16x16x32_bf16 v[52:55], v[148:151], v[180:183], v[52:55]
	v_mfma_f32_16x16x32_bf16 v[48:51], v[156:159], v[180:183], v[48:51]
	v_mfma_f32_16x16x32_bf16 v[36:39], v[148:151], v[188:191], v[36:39]
	v_mfma_f32_16x16x32_bf16 v[32:35], v[156:159], v[188:191], v[32:35]
	v_mfma_f32_16x16x32_bf16 v[20:23], v[148:151], v[204:207], v[20:23]
	v_mfma_f32_16x16x32_bf16 v[16:19], v[156:159], v[204:207], v[16:19]
	v_mfma_f32_16x16x32_bf16 v[4:7], v[148:151], v[212:215], v[4:7]
	v_mfma_f32_16x16x32_bf16 v[0:3], v[156:159], v[212:215], v[0:3]
	s_barrier
	s_setprio 0
	s_add_u32 s28, s28, 0x100
	s_addc_u32 s29, s29, 0
	s_add_u32 s49, s49, 0x100
	s_addc_u32 s50, s50, 0
	s_cmp_ge_i32 s51, s39
	s_mov_b32 s30, s51
	s_cbranch_scc0 .LBB0_959

; #define PG8_STAGE(bufoff, gbase, voff) do { _Pragma("unroll") for (int _i = 0; _i < 2; ++_i) \
;         __builtin_amdgcn_global_load_lds((const unsigned*)((const char*)(gbase) + (voff)[_i]), (LAS unsigned*)(lds + (bufoff) + ldsw + _i * 8192), 16, 0, ((voff) == voffA ? AUXA : 0)); } while (0)
; #define PG8_LDA(dst, b, h) do { _Pragma("unroll") for (int m = 0; m < 4; ++m) _Pragma("unroll") for (int k = 0; k < 2; ++k) dst[m][k] = *(const LAS bf16x8*)(lds + PG8_SA(b, h) + aoff + m * 2048 + k * 1024); } while (0)
; #define PG8_LDB(dst, b, h) do { _Pragma("unroll") for (int n = 0; n < 2; ++n) _Pragma("unroll") for (int k = 0; k < 2; ++k) dst[n][k] = *(const LAS bf16x8*)(lds + PG8_SB(b, h) + boff + n * 2048 + k * 1024); } while (0)
; #define PG8_MMA(ai, bj, At, Bt) do { __builtin_amdgcn_s_setprio(1); _Pragma("unroll") for (int m = 0; m < 4; ++m) _Pragma("unroll") for (int n = 0; n < 2; ++n) _Pragma("unroll") for (int k = 0; k < 2; ++k) \
;         acc[ai][bj][m][n] = __builtin_amdgcn_mfma_f32_16x16x32_bf16(Bt[n][k], At[m][k], acc[ai][bj][m][n], 0, 0, 0); __builtin_amdgcn_s_setprio(0); } while (0)
; #define PG8_WAIT_V(n) asm volatile("s_waitcnt vmcnt(" #n ")" ::: "memory")
; #define PG8_WAIT_L(n) asm volatile("s_waitcnt lgkmcnt(" #n ")" ::: "memory")
; #define PG8_BAR __builtin_amdgcn_s_barrier()
; #define PG8_SCHED __builtin_amdgcn_sched_barrier(0)
;     ...
;         for (int t = 0; t < nt; t += 2) {
;             const bool last = (t == nt - 2);
;             const char* a1 = cA + (size_t)(t + 1) * kstep;
;             const char* a2 = last ? nA : cA + (size_t)(t + 2) * kstep; const char* b2 = last ? nB : cB + (size_t)(t + 2) * kstep;
;             const char* a3 = a2 + kstep; const char* b3 = b2 + kstep;
;             PG8_LDB(B0, 0, 0); PG8_LDB(B1, 0, 1); PG8_SCHED; PG8_LDA(At, 0, 0); PG8_STAGE(PG8_SA(1, 1), a1 + hsA, voffA);
;             if (Epi::NPRE != 0 && last) { E.pre(sv, cur, wr, fr); PG8_WAIT_V(16); } else { PG8_WAIT_V(8); }
;             PG8_WAIT_L(0); PG8_BAR; PG8_MMA(0, 0, At, B0); PG8_MMA(0, 1, At, B1); PG8_BAR; PG8_SCHED;
;             PG8_LDA(At, 0, 1); PG8_STAGE(PG8_SB(0, 0), b2, voffB); PG8_STAGE(PG8_SB(0, 1), b2 + hsB, voffB); PG8_STAGE(PG8_SA(0, 0), a2, voffA);
;             if (Epi::NPRE != 0 && last) { PG8_WAIT_V(16); } else { PG8_WAIT_V(8); }
;             PG8_WAIT_L(0); PG8_BAR; PG8_MMA(1, 0, At, B0); PG8_MMA(1, 1, At, B1); PG8_BAR; PG8_SCHED;
.LBB0_1040:
	s_add_u32 s98, s28, 0xfffc0000
	s_addc_u32 s99, s29, -1
	s_mov_b32 m0, s45
	s_nop 0
	global_load_lds_dwordx4 v134, s[98:99]
	s_mov_b32 m0, s46
	s_nop 0
	global_load_lds_dwordx4 v130, s[98:99]
	ds_read_b128 v[150:153], v147
	ds_read_b128 v[154:157], v147 offset:1024
	ds_read_b128 v[158:161], v147 offset:2048
	ds_read_b128 v[162:165], v147 offset:3072
	ds_read_b128 v[166:169], v148
	ds_read_b128 v[170:173], v148 offset:1024
	ds_read_b128 v[174:177], v148 offset:2048
	ds_read_b128 v[178:181], v148 offset:3072
	s_add_i32 s56, s30, 2
	s_add_u32 s31, s28, 0xfffc0080
	s_addc_u32 s34, s29, -1
	s_cmp_eq_u32 s47, s30
	s_cselect_b32 s30, s53, s54
	s_cselect_b32 s35, s21, s34
	s_cselect_b32 s34, s23, s31
	s_cselect_b32 s31, s52, s55
	s_add_i32 m0, s19, 0xc000
	ds_read_b128 v[182:185], v149
	ds_read_b128 v[186:189], v149 offset:1024
	ds_read_b128 v[190:193], v149 offset:2048
	ds_read_b128 v[194:197], v149 offset:3072
	ds_read_b128 v[198:201], v149 offset:4096
	ds_read_b128 v[202:205], v149 offset:5120
	ds_read_b128 v[206:209], v149 offset:6144
	ds_read_b128 v[210:213], v149 offset:7168
	global_load_lds_dwordx4 v136, s[28:29]
	s_add_i32 m0, s19, 0xe000
	s_nop 0
	global_load_lds_dwordx4 v138, s[28:29]
	s_waitcnt vmcnt(8)
	s_waitcnt lgkmcnt(0)
	s_setprio 1
	s_barrier
	v_mfma_f32_16x16x32_bf16 v[124:127], v[150:153], v[182:185], v[124:127]
	v_mfma_f32_16x16x32_bf16 v[120:123], v[158:161], v[182:185], v[120:123]
	v_mfma_f32_16x16x32_bf16 v[108:111], v[150:153], v[190:193], v[108:111]
	v_mfma_f32_16x16x32_bf16 v[104:107], v[158:161], v[190:193], v[104:107]
	v_mfma_f32_16x16x32_bf16 v[92:95], v[150:153], v[198:201], v[92:95]
	v_mfma_f32_16x16x32_bf16 v[88:91], v[158:161], v[198:201], v[88:91]
	v_mfma_f32_16x16x32_bf16 v[76:79], v[150:153], v[206:209], v[76:79]
	v_mfma_f32_16x16x32_bf16 v[72:75], v[158:161], v[206:209], v[72:75]
	v_mfma_f32_16x16x32_bf16 v[124:127], v[154:157], v[186:189], v[124:127]
	v_mfma_f32_16x16x32_bf16 v[120:123], v[162:165], v[186:189], v[120:123]
	v_mfma_f32_16x16x32_bf16 v[108:111], v[154:157], v[194:197], v[108:111]
	v_mfma_f32_16x16x32_bf16 v[104:107], v[162:165], v[194:197], v[104:107]
	v_mfma_f32_16x16x32_bf16 v[92:95], v[154:157], v[202:205], v[92:95]
	v_mfma_f32_16x16x32_bf16 v[88:91], v[162:165], v[202:205], v[88:91]
	v_mfma_f32_16x16x32_bf16 v[76:79], v[154:157], v[210:213], v[76:79]
	v_mfma_f32_16x16x32_bf16 v[72:75], v[162:165], v[210:213], v[72:75]
	v_mfma_f32_16x16x32_bf16 v[116:119], v[166:169], v[182:185], v[116:119]
	v_mfma_f32_16x16x32_bf16 v[112:115], v[174:177], v[182:185], v[112:115]
	v_mfma_f32_16x16x32_bf16 v[100:103], v[166:169], v[190:193], v[100:103]
	v_mfma_f32_16x16x32_bf16 v[96:99], v[174:177], v[190:193], v[96:99]
	v_mfma_f32_16x16x32_bf16 v[84:87], v[166:169], v[198:201], v[84:87]
	v_mfma_f32_16x16x32_bf16 v[80:83], v[174:177], v[198:201], v[80:83]
	v_mfma_f32_16x16x32_bf16 v[68:71], v[166:169], v[206:209], v[68:71]
	v_mfma_f32_16x16x32_bf16 v[64:67], v[174:177], v[206:209], v[64:67]
	v_mfma_f32_16x16x32_bf16 v[116:119], v[170:173], v[186:189], v[116:119]
	v_mfma_f32_16x16x32_bf16 v[112:115], v[178:181], v[186:189], v[112:115]
	v_mfma_f32_16x16x32_bf16 v[100:103], v[170:173], v[194:197], v[100:103]
	v_mfma_f32_16x16x32_bf16 v[96:99], v[178:181], v[194:197], v[96:99]
	v_mfma_f32_16x16x32_bf16 v[84:87], v[170:173], v[202:205], v[84:87]
	v_mfma_f32_16x16x32_bf16 v[80:83], v[178:181], v[202:205], v[80:83]
	v_mfma_f32_16x16x32_bf16 v[68:71], v[170:173], v[210:213], v[68:71]
	v_mfma_f32_16x16x32_bf16 v[64:67], v[178:181], v[210:213], v[64:67]
	s_barrier
	s_setprio 0
	s_add_u32 s98, s30, s14
	s_addc_u32 s99, s31, s15
	s_add_u32 s100, s34, s14
	s_addc_u32 s101, s35, s15
	s_add_i32 s57, s49, s37
	s_mov_b32 m0, s57
	ds_read_b128 v[182:185], v149 offset:16384
	ds_read_b128 v[186:189], v149 offset:17408
	ds_read_b128 v[190:193], v149 offset:18432
	ds_read_b128 v[194:197], v149 offset:19456
	ds_read_b128 v[198:201], v149 offset:20480
	ds_read_b128 v[202:205], v149 offset:21504
	ds_read_b128 v[206:209], v149 offset:22528
	ds_read_b128 v[210:213], v149 offset:23552
	global_load_lds_dwordx4 v132, s[30:31]
	s_add_i32 m0, s57, 0x2000
	s_add_u32 s58, s30, 0x40000
	s_addc_u32 s59, s31, 0
	s_add_i32 s57, s50, s37
	global_load_lds_dwordx4 v128, s[30:31]
	s_mov_b32 m0, s57
	s_nop 0
	global_load_lds_dwordx4 v132, s[58:59]
	s_add_i32 m0, s57, 0x2000
	s_nop 0
	global_load_lds_dwordx4 v128, s[58:59]
	s_waitcnt vmcnt(6)
	s_waitcnt lgkmcnt(0)
	s_setprio 1
	s_barrier
	v_mfma_f32_16x16x32_bf16 v[60:63], v[150:153], v[182:185], v[60:63]
	v_mfma_f32_16x16x32_bf16 v[56:59], v[158:161], v[182:185], v[56:59]
	v_mfma_f32_16x16x32_bf16 v[44:47], v[150:153], v[190:193], v[44:47]
	v_mfma_f32_16x16x32_bf16 v[40:43], v[158:161], v[190:193], v[40:43]
	v_mfma_f32_16x16x32_bf16 v[28:31], v[150:153], v[198:201], v[28:31]
	v_mfma_f32_16x16x32_bf16 v[24:27], v[158:161], v[198:201], v[24:27]
	v_mfma_f32_16x16x32_bf16 v[12:15], v[150:153], v[206:209], v[12:15]
	v_mfma_f32_16x16x32_bf16 v[8:11], v[158:161], v[206:209], v[8:11]
	v_mfma_f32_16x16x32_bf16 v[60:63], v[154:157], v[186:189], v[60:63]
	v_mfma_f32_16x16x32_bf16 v[56:59], v[162:165], v[186:189], v[56:59]
	v_mfma_f32_16x16x32_bf16 v[44:47], v[154:157], v[194:197], v[44:47]
	v_mfma_f32_16x16x32_bf16 v[40:43], v[162:165], v[194:197], v[40:43]
	v_mfma_f32_16x16x32_bf16 v[28:31], v[154:157], v[202:205], v[28:31]
	v_mfma_f32_16x16x32_bf16 v[24:27], v[162:165], v[202:205], v[24:27]
	v_mfma_f32_16x16x32_bf16 v[12:15], v[154:157], v[210:213], v[12:15]
	v_mfma_f32_16x16x32_bf16 v[8:11], v[162:165], v[210:213], v[8:11]
	v_mfma_f32_16x16x32_bf16 v[52:55], v[166:169], v[182:185], v[52:55]
	v_mfma_f32_16x16x32_bf16 v[48:51], v[174:177], v[182:185], v[48:51]
	v_mfma_f32_16x16x32_bf16 v[36:39], v[166:169], v[190:193], v[36:39]
	v_mfma_f32_16x16x32_bf16 v[32:35], v[174:177], v[190:193], v[32:35]
	v_mfma_f32_16x16x32_bf16 v[20:23], v[166:169], v[198:201], v[20:23]
	v_mfma_f32_16x16x32_bf16 v[16:19], v[174:177], v[198:201], v[16:19]
	v_mfma_f32_16x16x32_bf16 v[4:7], v[166:169], v[206:209], v[4:7]
	v_mfma_f32_16x16x32_bf16 v[0:3], v[174:177], v[206:209], v[0:3]
	v_mfma_f32_16x16x32_bf16 v[52:55], v[170:173], v[186:189], v[52:55]
	v_mfma_f32_16x16x32_bf16 v[48:51], v[178:181], v[186:189], v[48:51]
	v_mfma_f32_16x16x32_bf16 v[36:39], v[170:173], v[194:197], v[36:39]
	v_mfma_f32_16x16x32_bf16 v[32:35], v[178:181], v[194:197], v[32:35]
	v_mfma_f32_16x16x32_bf16 v[20:23], v[170:173], v[202:205], v[20:23]
	v_mfma_f32_16x16x32_bf16 v[16:19], v[178:181], v[202:205], v[16:19]
	v_mfma_f32_16x16x32_bf16 v[4:7], v[170:173], v[210:213], v[4:7]
	v_mfma_f32_16x16x32_bf16 v[0:3], v[178:181], v[210:213], v[0:3]
	s_barrier
; #define PG8_STAGE(bufoff, gbase, voff) do { _Pragma("unroll") for (int _i = 0; _i < 2; ++_i) \
;         __builtin_amdgcn_global_load_lds((const unsigned*)((const char*)(gbase) + (voff)[_i]), (LAS unsigned*)(lds + (bufoff) + ldsw + _i * 8192), 16, 0, ((voff) == voffA ? AUXA : 0)); } while (0)
; #define PG8_LDA(dst, b, h) do { _Pragma("unroll") for (int m = 0; m < 4; ++m) _Pragma("unroll") for (int k = 0; k < 2; ++k) dst[m][k] = *(const LAS bf16x8*)(lds + PG8_SA(b, h) + aoff + m * 2048 + k * 1024); } while (0)
; #define PG8_LDB(dst, b, h) do { _Pragma("unroll") for (int n = 0; n < 2; ++n) _Pragma("unroll") for (int k = 0; k < 2; ++k) dst[n][k] = *(const LAS bf16x8*)(lds + PG8_SB(b, h) + boff + n * 2048 + k * 1024); } while (0)
; #define PG8_MMA(ai, bj, At, Bt) do { __builtin_amdgcn_s_setprio(1); _Pragma("unroll") for (int m = 0; m < 4; ++m) _Pragma("unroll") for (int n = 0; n < 2; ++n) _Pragma("unroll") for (int k = 0; k < 2; ++k) \
;         acc[ai][bj][m][n] = __builtin_amdgcn_mfma_f32_16x16x32_bf16(Bt[n][k], At[m][k], acc[ai][bj][m][n], 0, 0, 0); __builtin_amdgcn_s_setprio(0); } while (0)
; #define PG8_WAIT_V(n) asm volatile("s_waitcnt vmcnt(" #n ")" ::: "memory")
; #define PG8_WAIT_L(n) asm volatile("s_waitcnt lgkmcnt(" #n ")" ::: "memory")
; #define PG8_BAR __builtin_amdgcn_s_barrier()
; #define PG8_SCHED __builtin_amdgcn_sched_barrier(0)
;     ...
;             PG8_WAIT_L(0); PG8_BAR; PG8_MMA(1, 0, At, B0); PG8_MMA(1, 1, At, B1); PG8_BAR; PG8_SCHED;
;             PG8_LDB(B0, 1, 0); PG8_LDB(B1, 1, 1); PG8_SCHED; PG8_LDA(At, 1, 0); PG8_STAGE(PG8_SA(0, 1), a2 + hsA, voffA);
;             PG8_WAIT_V(8); PG8_WAIT_L(0); PG8_BAR; PG8_MMA(0, 0, At, B0); PG8_MMA(0, 1, At, B1); PG8_BAR; PG8_SCHED;
;             PG8_LDA(At, 1, 1); PG8_STAGE(PG8_SB(1, 0), b3, voffB); PG8_STAGE(PG8_SB(1, 1), b3 + hsB, voffB); PG8_STAGE(PG8_SA(1, 0), a3, voffA);
;             PG8_WAIT_V(8); PG8_WAIT_L(0); PG8_BAR; PG8_MMA(1, 0, At, B0); PG8_MMA(1, 1, At, B1); PG8_BAR; PG8_SCHED;
;         }
	s_mov_b32 m0, s19
	s_nop 0
	global_load_lds_dwordx4 v134, s[34:35]
	s_mov_b32 m0, s40
	s_nop 0
	global_load_lds_dwordx4 v130, s[34:35]
	s_setprio 0
	s_add_i32 s57, 0, 0x18000
	s_add_i32 s58, 0, 0x1c000
	v_add_u32_e32 v162, s57, v145
	v_add_u32_e32 v178, s58, v145
	ds_read_b128 v[150:153], v162
	ds_read_b128 v[154:157], v162 offset:1024
	ds_read_b128 v[158:161], v162 offset:2048
	ds_read_b128 v[162:165], v162 offset:3072
	ds_read_b128 v[166:169], v178
	ds_read_b128 v[170:173], v178 offset:1024
	ds_read_b128 v[174:177], v178 offset:2048
	ds_read_b128 v[178:181], v178 offset:3072
	s_add_u32 s34, s34, 0x40000
	s_addc_u32 s35, s35, 0
	s_mov_b32 m0, s41
	ds_read_b128 v[182:185], v149 offset:32768
	ds_read_b128 v[186:189], v149 offset:33792
	ds_read_b128 v[190:193], v149 offset:34816
	ds_read_b128 v[194:197], v149 offset:35840
	ds_read_b128 v[198:201], v149 offset:36864
	ds_read_b128 v[202:205], v149 offset:37888
	ds_read_b128 v[206:209], v149 offset:38912
	ds_read_b128 v[210:213], v149 offset:39936
	global_load_lds_dwordx4 v134, s[34:35]
	s_mov_b32 m0, s42
	s_nop 0
	global_load_lds_dwordx4 v130, s[34:35]
	s_waitcnt vmcnt(8)
	s_waitcnt lgkmcnt(0)
	s_setprio 1
	s_barrier
	v_mfma_f32_16x16x32_bf16 v[124:127], v[150:153], v[182:185], v[124:127]
	v_mfma_f32_16x16x32_bf16 v[120:123], v[158:161], v[182:185], v[120:123]
	v_mfma_f32_16x16x32_bf16 v[108:111], v[150:153], v[190:193], v[108:111]
	v_mfma_f32_16x16x32_bf16 v[104:107], v[158:161], v[190:193], v[104:107]
	v_mfma_f32_16x16x32_bf16 v[92:95], v[150:153], v[198:201], v[92:95]
	v_mfma_f32_16x16x32_bf16 v[88:91], v[158:161], v[198:201], v[88:91]
	v_mfma_f32_16x16x32_bf16 v[76:79], v[150:153], v[206:209], v[76:79]
	v_mfma_f32_16x16x32_bf16 v[72:75], v[158:161], v[206:209], v[72:75]
	v_mfma_f32_16x16x32_bf16 v[124:127], v[154:157], v[186:189], v[124:127]
	v_mfma_f32_16x16x32_bf16 v[120:123], v[162:165], v[186:189], v[120:123]
	v_mfma_f32_16x16x32_bf16 v[108:111], v[154:157], v[194:197], v[108:111]
	v_mfma_f32_16x16x32_bf16 v[104:107], v[162:165], v[194:197], v[104:107]
	v_mfma_f32_16x16x32_bf16 v[92:95], v[154:157], v[202:205], v[92:95]
	v_mfma_f32_16x16x32_bf16 v[88:91], v[162:165], v[202:205], v[88:91]
	v_mfma_f32_16x16x32_bf16 v[76:79], v[154:157], v[210:213], v[76:79]
	v_mfma_f32_16x16x32_bf16 v[72:75], v[162:165], v[210:213], v[72:75]
	v_mfma_f32_16x16x32_bf16 v[116:119], v[166:169], v[182:185], v[116:119]
	v_mfma_f32_16x16x32_bf16 v[112:115], v[174:177], v[182:185], v[112:115]
	v_mfma_f32_16x16x32_bf16 v[100:103], v[166:169], v[190:193], v[100:103]
	v_mfma_f32_16x16x32_bf16 v[96:99], v[174:177], v[190:193], v[96:99]
	v_mfma_f32_16x16x32_bf16 v[84:87], v[166:169], v[198:201], v[84:87]
	v_mfma_f32_16x16x32_bf16 v[80:83], v[174:177], v[198:201], v[80:83]
	v_mfma_f32_16x16x32_bf16 v[68:71], v[166:169], v[206:209], v[68:71]
	v_mfma_f32_16x16x32_bf16 v[64:67], v[174:177], v[206:209], v[64:67]
	v_mfma_f32_16x16x32_bf16 v[116:119], v[170:173], v[186:189], v[116:119]
	v_mfma_f32_16x16x32_bf16 v[112:115], v[178:181], v[186:189], v[112:115]
	v_mfma_f32_16x16x32_bf16 v[100:103], v[170:173], v[194:197], v[100:103]
	v_mfma_f32_16x16x32_bf16 v[96:99], v[178:181], v[194:197], v[96:99]
	v_mfma_f32_16x16x32_bf16 v[84:87], v[170:173], v[202:205], v[84:87]
	v_mfma_f32_16x16x32_bf16 v[80:83], v[178:181], v[202:205], v[80:83]
	v_mfma_f32_16x16x32_bf16 v[68:71], v[170:173], v[210:213], v[68:71]
	v_mfma_f32_16x16x32_bf16 v[64:67], v[178:181], v[210:213], v[64:67]
	s_barrier
	s_setprio 0
	s_add_i32 s34, s57, s37
	s_mov_b32 m0, s34
	ds_read_b128 v[182:185], v149 offset:49152
	ds_read_b128 v[186:189], v149 offset:50176
	ds_read_b128 v[190:193], v149 offset:51200
	ds_read_b128 v[194:197], v149 offset:52224
	ds_read_b128 v[198:201], v149 offset:53248
	ds_read_b128 v[202:205], v149 offset:54272
	ds_read_b128 v[206:209], v149 offset:55296
	ds_read_b128 v[210:213], v149 offset:56320
	global_load_lds_dwordx4 v132, s[98:99]
	s_add_i32 m0, s34, 0x2000
	s_add_u32 s30, s30, 0x40080
	s_addc_u32 s31, s31, 0
	s_add_i32 s34, s58, s37
	global_load_lds_dwordx4 v128, s[98:99]
	s_mov_b32 m0, s34
	s_nop 0
	global_load_lds_dwordx4 v132, s[30:31]
	s_add_i32 m0, s34, 0x2000
	s_nop 0
	global_load_lds_dwordx4 v128, s[30:31]
	s_waitcnt vmcnt(6)
	s_waitcnt lgkmcnt(0)
	s_setprio 1
	s_barrier
	v_mfma_f32_16x16x32_bf16 v[60:63], v[150:153], v[182:185], v[60:63]
	v_mfma_f32_16x16x32_bf16 v[56:59], v[158:161], v[182:185], v[56:59]
	v_mfma_f32_16x16x32_bf16 v[44:47], v[150:153], v[190:193], v[44:47]
	v_mfma_f32_16x16x32_bf16 v[40:43], v[158:161], v[190:193], v[40:43]
	v_mfma_f32_16x16x32_bf16 v[28:31], v[150:153], v[198:201], v[28:31]
	v_mfma_f32_16x16x32_bf16 v[24:27], v[158:161], v[198:201], v[24:27]
	v_mfma_f32_16x16x32_bf16 v[12:15], v[150:153], v[206:209], v[12:15]
	v_mfma_f32_16x16x32_bf16 v[8:11], v[158:161], v[206:209], v[8:11]
	v_mfma_f32_16x16x32_bf16 v[60:63], v[154:157], v[186:189], v[60:63]
	v_mfma_f32_16x16x32_bf16 v[56:59], v[162:165], v[186:189], v[56:59]
	v_mfma_f32_16x16x32_bf16 v[44:47], v[154:157], v[194:197], v[44:47]
	v_mfma_f32_16x16x32_bf16 v[40:43], v[162:165], v[194:197], v[40:43]
	v_mfma_f32_16x16x32_bf16 v[28:31], v[154:157], v[202:205], v[28:31]
	v_mfma_f32_16x16x32_bf16 v[24:27], v[162:165], v[202:205], v[24:27]
	v_mfma_f32_16x16x32_bf16 v[12:15], v[154:157], v[210:213], v[12:15]
	v_mfma_f32_16x16x32_bf16 v[8:11], v[162:165], v[210:213], v[8:11]
	v_mfma_f32_16x16x32_bf16 v[52:55], v[166:169], v[182:185], v[52:55]
	v_mfma_f32_16x16x32_bf16 v[48:51], v[174:177], v[182:185], v[48:51]
	v_mfma_f32_16x16x32_bf16 v[36:39], v[166:169], v[190:193], v[36:39]
	v_mfma_f32_16x16x32_bf16 v[32:35], v[174:177], v[190:193], v[32:35]
	v_mfma_f32_16x16x32_bf16 v[20:23], v[166:169], v[198:201], v[20:23]
	v_mfma_f32_16x16x32_bf16 v[16:19], v[174:177], v[198:201], v[16:19]
	v_mfma_f32_16x16x32_bf16 v[4:7], v[166:169], v[206:209], v[4:7]
	v_mfma_f32_16x16x32_bf16 v[0:3], v[174:177], v[206:209], v[0:3]
	v_mfma_f32_16x16x32_bf16 v[52:55], v[170:173], v[186:189], v[52:55]
	v_mfma_f32_16x16x32_bf16 v[48:51], v[178:181], v[186:189], v[48:51]
	v_mfma_f32_16x16x32_bf16 v[36:39], v[170:173], v[194:197], v[36:39]
	v_mfma_f32_16x16x32_bf16 v[32:35], v[178:181], v[194:197], v[32:35]
	v_mfma_f32_16x16x32_bf16 v[20:23], v[170:173], v[202:205], v[20:23]
	v_mfma_f32_16x16x32_bf16 v[16:19], v[178:181], v[202:205], v[16:19]
	v_mfma_f32_16x16x32_bf16 v[4:7], v[170:173], v[210:213], v[4:7]
	v_mfma_f32_16x16x32_bf16 v[0:3], v[178:181], v[210:213], v[0:3]
	s_barrier
	s_setprio 0
	s_add_u32 s28, s28, 0x100
	s_addc_u32 s29, s29, 0
	s_add_u32 s54, s54, 0x100
	s_addc_u32 s55, s55, 0
	s_cmp_ge_i32 s56, s44
	s_mov_b32 s30, s56
	s_cbranch_scc0 .LBB0_1040

; #define PG8_STAGE(bufoff, gbase, voff) do { _Pragma("unroll") for (int _i = 0; _i < 2; ++_i) \
;         __builtin_amdgcn_global_load_lds((const unsigned*)((const char*)(gbase) + (voff)[_i]), (LAS unsigned*)(lds + (bufoff) + ldsw + _i * 8192), 16, 0, ((voff) == voffA ? AUXA : 0)); } while (0)
; #define PG8_LDA(dst, b, h) do { _Pragma("unroll") for (int m = 0; m < 4; ++m) _Pragma("unroll") for (int k = 0; k < 2; ++k) dst[m][k] = *(const LAS bf16x8*)(lds + PG8_SA(b, h) + aoff + m * 2048 + k * 1024); } while (0)
; #define PG8_LDB(dst, b, h) do { _Pragma("unroll") for (int n = 0; n < 2; ++n) _Pragma("unroll") for (int k = 0; k < 2; ++k) dst[n][k] = *(const LAS bf16x8*)(lds + PG8_SB(b, h) + boff + n * 2048 + k * 1024); } while (0)
; #define PG8_MMA(ai, bj, At, Bt) do { __builtin_amdgcn_s_setprio(1); _Pragma("unroll") for (int m = 0; m < 4; ++m) _Pragma("unroll") for (int n = 0; n < 2; ++n) _Pragma("unroll") for (int k = 0; k < 2; ++k) \
;         acc[ai][bj][m][n] = __builtin_amdgcn_mfma_f32_16x16x32_bf16(Bt[n][k], At[m][k], acc[ai][bj][m][n], 0, 0, 0); __builtin_amdgcn_s_setprio(0); } while (0)
; #define PG8_WAIT_V(n) asm volatile("s_waitcnt vmcnt(" #n ")" ::: "memory")
; #define PG8_WAIT_L(n) asm volatile("s_waitcnt lgkmcnt(" #n ")" ::: "memory")
; #define PG8_BAR __builtin_amdgcn_s_barrier()
; #define PG8_SCHED __builtin_amdgcn_sched_barrier(0)
;     ...
;         for (int t = 0; t < nt; t += 2) {
;             const bool last = (t == nt - 2);
;             const char* a1 = cA + (size_t)(t + 1) * kstep;
;             const char* a2 = last ? nA : cA + (size_t)(t + 2) * kstep; const char* b2 = last ? nB : cB + (size_t)(t + 2) * kstep;
;             const char* a3 = a2 + kstep; const char* b3 = b2 + kstep;
;             PG8_LDB(B0, 0, 0); PG8_LDB(B1, 0, 1); PG8_SCHED; PG8_LDA(At, 0, 0); PG8_STAGE(PG8_SA(1, 1), a1 + hsA, voffA);
;             if (Epi::NPRE != 0 && last) { E.pre(sv, cur, wr, fr); PG8_WAIT_V(16); } else { PG8_WAIT_V(8); }
;             PG8_WAIT_L(0); PG8_BAR; PG8_MMA(0, 0, At, B0); PG8_MMA(0, 1, At, B1); PG8_BAR; PG8_SCHED;
;             PG8_LDA(At, 0, 1); PG8_STAGE(PG8_SB(0, 0), b2, voffB); PG8_STAGE(PG8_SB(0, 1), b2 + hsB, voffB); PG8_STAGE(PG8_SA(0, 0), a2, voffA);
;             if (Epi::NPRE != 0 && last) { PG8_WAIT_V(16); } else { PG8_WAIT_V(8); }
;             PG8_WAIT_L(0); PG8_BAR; PG8_MMA(1, 0, At, B0); PG8_MMA(1, 1, At, B1); PG8_BAR; PG8_SCHED;
.LBB0_1112:
	s_add_u32 s98, s28, 0xfffc0000
	s_addc_u32 s99, s29, -1
	s_mov_b32 m0, s43
	s_nop 0
	global_load_lds_dwordx4 v134, s[98:99]
	s_mov_b32 m0, s44
	s_nop 0
	global_load_lds_dwordx4 v130, s[98:99]
	ds_read_b128 v[150:153], v147
	ds_read_b128 v[154:157], v147 offset:1024
	ds_read_b128 v[158:161], v147 offset:2048
	ds_read_b128 v[162:165], v147 offset:3072
	ds_read_b128 v[166:169], v148
	ds_read_b128 v[170:173], v148 offset:1024
	ds_read_b128 v[174:177], v148 offset:2048
	ds_read_b128 v[178:181], v148 offset:3072
	s_add_i32 s54, s30, 2
	s_add_u32 s31, s28, 0xfffc0080
	s_addc_u32 s34, s29, -1
	s_cmp_eq_u32 s45, s30
	s_cselect_b32 s30, s51, s52
	s_cselect_b32 s35, s21, s34
	s_cselect_b32 s34, s23, s31
	s_cselect_b32 s31, s50, s53
	s_add_i32 m0, s19, 0xc000
	ds_read_b128 v[182:185], v149
	ds_read_b128 v[186:189], v149 offset:1024
	ds_read_b128 v[190:193], v149 offset:2048
	ds_read_b128 v[194:197], v149 offset:3072
	ds_read_b128 v[198:201], v149 offset:4096
	ds_read_b128 v[202:205], v149 offset:5120
	ds_read_b128 v[206:209], v149 offset:6144
	ds_read_b128 v[210:213], v149 offset:7168
	global_load_lds_dwordx4 v136, s[28:29]
	s_add_i32 m0, s19, 0xe000
	s_nop 0
	global_load_lds_dwordx4 v138, s[28:29]
	s_waitcnt vmcnt(8)
	s_waitcnt lgkmcnt(0)
	s_setprio 1
	s_barrier
	v_mfma_f32_16x16x32_bf16 v[124:127], v[150:153], v[182:185], v[124:127]
	v_mfma_f32_16x16x32_bf16 v[120:123], v[158:161], v[182:185], v[120:123]
	v_mfma_f32_16x16x32_bf16 v[108:111], v[150:153], v[190:193], v[108:111]
	v_mfma_f32_16x16x32_bf16 v[104:107], v[158:161], v[190:193], v[104:107]
	v_mfma_f32_16x16x32_bf16 v[92:95], v[150:153], v[198:201], v[92:95]
	v_mfma_f32_16x16x32_bf16 v[88:91], v[158:161], v[198:201], v[88:91]
	v_mfma_f32_16x16x32_bf16 v[76:79], v[150:153], v[206:209], v[76:79]
	v_mfma_f32_16x16x32_bf16 v[72:75], v[158:161], v[206:209], v[72:75]
	v_mfma_f32_16x16x32_bf16 v[124:127], v[154:157], v[186:189], v[124:127]
	v_mfma_f32_16x16x32_bf16 v[120:123], v[162:165], v[186:189], v[120:123]
	v_mfma_f32_16x16x32_bf16 v[108:111], v[154:157], v[194:197], v[108:111]
	v_mfma_f32_16x16x32_bf16 v[104:107], v[162:165], v[194:197], v[104:107]
	v_mfma_f32_16x16x32_bf16 v[92:95], v[154:157], v[202:205], v[92:95]
	v_mfma_f32_16x16x32_bf16 v[88:91], v[162:165], v[202:205], v[88:91]
	v_mfma_f32_16x16x32_bf16 v[76:79], v[154:157], v[210:213], v[76:79]
	v_mfma_f32_16x16x32_bf16 v[72:75], v[162:165], v[210:213], v[72:75]
	v_mfma_f32_16x16x32_bf16 v[116:119], v[166:169], v[182:185], v[116:119]
	v_mfma_f32_16x16x32_bf16 v[112:115], v[174:177], v[182:185], v[112:115]
	v_mfma_f32_16x16x32_bf16 v[100:103], v[166:169], v[190:193], v[100:103]
	v_mfma_f32_16x16x32_bf16 v[96:99], v[174:177], v[190:193], v[96:99]
	v_mfma_f32_16x16x32_bf16 v[84:87], v[166:169], v[198:201], v[84:87]
	v_mfma_f32_16x16x32_bf16 v[80:83], v[174:177], v[198:201], v[80:83]
	v_mfma_f32_16x16x32_bf16 v[68:71], v[166:169], v[206:209], v[68:71]
	v_mfma_f32_16x16x32_bf16 v[64:67], v[174:177], v[206:209], v[64:67]
	v_mfma_f32_16x16x32_bf16 v[116:119], v[170:173], v[186:189], v[116:119]
	v_mfma_f32_16x16x32_bf16 v[112:115], v[178:181], v[186:189], v[112:115]
	v_mfma_f32_16x16x32_bf16 v[100:103], v[170:173], v[194:197], v[100:103]
	v_mfma_f32_16x16x32_bf16 v[96:99], v[178:181], v[194:197], v[96:99]
	v_mfma_f32_16x16x32_bf16 v[84:87], v[170:173], v[202:205], v[84:87]
	v_mfma_f32_16x16x32_bf16 v[80:83], v[178:181], v[202:205], v[80:83]
	v_mfma_f32_16x16x32_bf16 v[68:71], v[170:173], v[210:213], v[68:71]
	v_mfma_f32_16x16x32_bf16 v[64:67], v[178:181], v[210:213], v[64:67]
	s_barrier
	s_setprio 0
	s_add_u32 s98, s30, s14
	s_addc_u32 s99, s31, s15
	s_add_u32 s100, s34, s14
	s_addc_u32 s101, s35, s15
	s_add_i32 s55, s47, s5
	s_mov_b32 m0, s55
	ds_read_b128 v[182:185], v149 offset:16384
	ds_read_b128 v[186:189], v149 offset:17408
	ds_read_b128 v[190:193], v149 offset:18432
	ds_read_b128 v[194:197], v149 offset:19456
	ds_read_b128 v[198:201], v149 offset:20480
	ds_read_b128 v[202:205], v149 offset:21504
	ds_read_b128 v[206:209], v149 offset:22528
	ds_read_b128 v[210:213], v149 offset:23552
	global_load_lds_dwordx4 v132, s[30:31]
	s_add_i32 m0, s55, 0x2000
	s_add_u32 s56, s30, 0x40000
	s_addc_u32 s57, s31, 0
	s_add_i32 s55, s48, s5
	global_load_lds_dwordx4 v128, s[30:31]
	s_mov_b32 m0, s55
	s_nop 0
	global_load_lds_dwordx4 v132, s[56:57]
	s_add_i32 m0, s55, 0x2000
	s_nop 0
	global_load_lds_dwordx4 v128, s[56:57]
	s_waitcnt vmcnt(6)
	s_waitcnt lgkmcnt(0)
	s_setprio 1
	s_barrier
	v_mfma_f32_16x16x32_bf16 v[60:63], v[150:153], v[182:185], v[60:63]
	v_mfma_f32_16x16x32_bf16 v[56:59], v[158:161], v[182:185], v[56:59]
	v_mfma_f32_16x16x32_bf16 v[44:47], v[150:153], v[190:193], v[44:47]
	v_mfma_f32_16x16x32_bf16 v[40:43], v[158:161], v[190:193], v[40:43]
	v_mfma_f32_16x16x32_bf16 v[28:31], v[150:153], v[198:201], v[28:31]
	v_mfma_f32_16x16x32_bf16 v[24:27], v[158:161], v[198:201], v[24:27]
	v_mfma_f32_16x16x32_bf16 v[12:15], v[150:153], v[206:209], v[12:15]
	v_mfma_f32_16x16x32_bf16 v[8:11], v[158:161], v[206:209], v[8:11]
	v_mfma_f32_16x16x32_bf16 v[60:63], v[154:157], v[186:189], v[60:63]
	v_mfma_f32_16x16x32_bf16 v[56:59], v[162:165], v[186:189], v[56:59]
	v_mfma_f32_16x16x32_bf16 v[44:47], v[154:157], v[194:197], v[44:47]
	v_mfma_f32_16x16x32_bf16 v[40:43], v[162:165], v[194:197], v[40:43]
	v_mfma_f32_16x16x32_bf16 v[28:31], v[154:157], v[202:205], v[28:31]
	v_mfma_f32_16x16x32_bf16 v[24:27], v[162:165], v[202:205], v[24:27]
	v_mfma_f32_16x16x32_bf16 v[12:15], v[154:157], v[210:213], v[12:15]
	v_mfma_f32_16x16x32_bf16 v[8:11], v[162:165], v[210:213], v[8:11]
	v_mfma_f32_16x16x32_bf16 v[52:55], v[166:169], v[182:185], v[52:55]
	v_mfma_f32_16x16x32_bf16 v[48:51], v[174:177], v[182:185], v[48:51]
	v_mfma_f32_16x16x32_bf16 v[36:39], v[166:169], v[190:193], v[36:39]
	v_mfma_f32_16x16x32_bf16 v[32:35], v[174:177], v[190:193], v[32:35]
	v_mfma_f32_16x16x32_bf16 v[20:23], v[166:169], v[198:201], v[20:23]
	v_mfma_f32_16x16x32_bf16 v[16:19], v[174:177], v[198:201], v[16:19]
	v_mfma_f32_16x16x32_bf16 v[4:7], v[166:169], v[206:209], v[4:7]
	v_mfma_f32_16x16x32_bf16 v[0:3], v[174:177], v[206:209], v[0:3]
	v_mfma_f32_16x16x32_bf16 v[52:55], v[170:173], v[186:189], v[52:55]
	v_mfma_f32_16x16x32_bf16 v[48:51], v[178:181], v[186:189], v[48:51]
	v_mfma_f32_16x16x32_bf16 v[36:39], v[170:173], v[194:197], v[36:39]
	v_mfma_f32_16x16x32_bf16 v[32:35], v[178:181], v[194:197], v[32:35]
	v_mfma_f32_16x16x32_bf16 v[20:23], v[170:173], v[202:205], v[20:23]
	v_mfma_f32_16x16x32_bf16 v[16:19], v[178:181], v[202:205], v[16:19]
	v_mfma_f32_16x16x32_bf16 v[4:7], v[170:173], v[210:213], v[4:7]
	v_mfma_f32_16x16x32_bf16 v[0:3], v[178:181], v[210:213], v[0:3]
	s_barrier
; #define PG8_STAGE(bufoff, gbase, voff) do { _Pragma("unroll") for (int _i = 0; _i < 2; ++_i) \
;         __builtin_amdgcn_global_load_lds((const unsigned*)((const char*)(gbase) + (voff)[_i]), (LAS unsigned*)(lds + (bufoff) + ldsw + _i * 8192), 16, 0, ((voff) == voffA ? AUXA : 0)); } while (0)
; #define PG8_LDA(dst, b, h) do { _Pragma("unroll") for (int m = 0; m < 4; ++m) _Pragma("unroll") for (int k = 0; k < 2; ++k) dst[m][k] = *(const LAS bf16x8*)(lds + PG8_SA(b, h) + aoff + m * 2048 + k * 1024); } while (0)
; #define PG8_LDB(dst, b, h) do { _Pragma("unroll") for (int n = 0; n < 2; ++n) _Pragma("unroll") for (int k = 0; k < 2; ++k) dst[n][k] = *(const LAS bf16x8*)(lds + PG8_SB(b, h) + boff + n * 2048 + k * 1024); } while (0)
; #define PG8_MMA(ai, bj, At, Bt) do { __builtin_amdgcn_s_setprio(1); _Pragma("unroll") for (int m = 0; m < 4; ++m) _Pragma("unroll") for (int n = 0; n < 2; ++n) _Pragma("unroll") for (int k = 0; k < 2; ++k) \
;         acc[ai][bj][m][n] = __builtin_amdgcn_mfma_f32_16x16x32_bf16(Bt[n][k], At[m][k], acc[ai][bj][m][n], 0, 0, 0); __builtin_amdgcn_s_setprio(0); } while (0)
; #define PG8_WAIT_V(n) asm volatile("s_waitcnt vmcnt(" #n ")" ::: "memory")
; #define PG8_WAIT_L(n) asm volatile("s_waitcnt lgkmcnt(" #n ")" ::: "memory")
; #define PG8_BAR __builtin_amdgcn_s_barrier()
; #define PG8_SCHED __builtin_amdgcn_sched_barrier(0)
;     ...
;             PG8_WAIT_L(0); PG8_BAR; PG8_MMA(1, 0, At, B0); PG8_MMA(1, 1, At, B1); PG8_BAR; PG8_SCHED;
;             PG8_LDB(B0, 1, 0); PG8_LDB(B1, 1, 1); PG8_SCHED; PG8_LDA(At, 1, 0); PG8_STAGE(PG8_SA(0, 1), a2 + hsA, voffA);
;             PG8_WAIT_V(8); PG8_WAIT_L(0); PG8_BAR; PG8_MMA(0, 0, At, B0); PG8_MMA(0, 1, At, B1); PG8_BAR; PG8_SCHED;
;             PG8_LDA(At, 1, 1); PG8_STAGE(PG8_SB(1, 0), b3, voffB); PG8_STAGE(PG8_SB(1, 1), b3 + hsB, voffB); PG8_STAGE(PG8_SA(1, 0), a3, voffA);
;             PG8_WAIT_V(8); PG8_WAIT_L(0); PG8_BAR; PG8_MMA(1, 0, At, B0); PG8_MMA(1, 1, At, B1); PG8_BAR; PG8_SCHED;
;         }
	s_mov_b32 m0, s19
	s_nop 0
	global_load_lds_dwordx4 v134, s[34:35]
	s_mov_b32 m0, s38
	s_nop 0
	global_load_lds_dwordx4 v130, s[34:35]
	s_setprio 0
	s_add_i32 s55, 0, 0x18000
	s_add_i32 s56, 0, 0x1c000
	v_add_u32_e32 v162, s55, v145
	v_add_u32_e32 v178, s56, v145
	ds_read_b128 v[150:153], v162
	ds_read_b128 v[154:157], v162 offset:1024
	ds_read_b128 v[158:161], v162 offset:2048
	ds_read_b128 v[162:165], v162 offset:3072
	ds_read_b128 v[166:169], v178
	ds_read_b128 v[170:173], v178 offset:1024
	ds_read_b128 v[174:177], v178 offset:2048
	ds_read_b128 v[178:181], v178 offset:3072
	s_add_u32 s34, s34, 0x40000
	s_addc_u32 s35, s35, 0
	s_mov_b32 m0, s39
	ds_read_b128 v[182:185], v149 offset:32768
	ds_read_b128 v[186:189], v149 offset:33792
	ds_read_b128 v[190:193], v149 offset:34816
	ds_read_b128 v[194:197], v149 offset:35840
	ds_read_b128 v[198:201], v149 offset:36864
	ds_read_b128 v[202:205], v149 offset:37888
	ds_read_b128 v[206:209], v149 offset:38912
	ds_read_b128 v[210:213], v149 offset:39936
	global_load_lds_dwordx4 v134, s[34:35]
	s_mov_b32 m0, s40
	s_nop 0
	global_load_lds_dwordx4 v130, s[34:35]
	s_waitcnt vmcnt(8)
	s_waitcnt lgkmcnt(0)
	s_setprio 1
	s_barrier
	v_mfma_f32_16x16x32_bf16 v[124:127], v[150:153], v[182:185], v[124:127]
	v_mfma_f32_16x16x32_bf16 v[120:123], v[158:161], v[182:185], v[120:123]
	v_mfma_f32_16x16x32_bf16 v[108:111], v[150:153], v[190:193], v[108:111]
	v_mfma_f32_16x16x32_bf16 v[104:107], v[158:161], v[190:193], v[104:107]
	v_mfma_f32_16x16x32_bf16 v[92:95], v[150:153], v[198:201], v[92:95]
	v_mfma_f32_16x16x32_bf16 v[88:91], v[158:161], v[198:201], v[88:91]
	v_mfma_f32_16x16x32_bf16 v[76:79], v[150:153], v[206:209], v[76:79]
	v_mfma_f32_16x16x32_bf16 v[72:75], v[158:161], v[206:209], v[72:75]
	v_mfma_f32_16x16x32_bf16 v[124:127], v[154:157], v[186:189], v[124:127]
	v_mfma_f32_16x16x32_bf16 v[120:123], v[162:165], v[186:189], v[120:123]
	v_mfma_f32_16x16x32_bf16 v[108:111], v[154:157], v[194:197], v[108:111]
	v_mfma_f32_16x16x32_bf16 v[104:107], v[162:165], v[194:197], v[104:107]
	v_mfma_f32_16x16x32_bf16 v[92:95], v[154:157], v[202:205], v[92:95]
	v_mfma_f32_16x16x32_bf16 v[88:91], v[162:165], v[202:205], v[88:91]
	v_mfma_f32_16x16x32_bf16 v[76:79], v[154:157], v[210:213], v[76:79]
	v_mfma_f32_16x16x32_bf16 v[72:75], v[162:165], v[210:213], v[72:75]
	v_mfma_f32_16x16x32_bf16 v[116:119], v[166:169], v[182:185], v[116:119]
	v_mfma_f32_16x16x32_bf16 v[112:115], v[174:177], v[182:185], v[112:115]
	v_mfma_f32_16x16x32_bf16 v[100:103], v[166:169], v[190:193], v[100:103]
	v_mfma_f32_16x16x32_bf16 v[96:99], v[174:177], v[190:193], v[96:99]
	v_mfma_f32_16x16x32_bf16 v[84:87], v[166:169], v[198:201], v[84:87]
	v_mfma_f32_16x16x32_bf16 v[80:83], v[174:177], v[198:201], v[80:83]
	v_mfma_f32_16x16x32_bf16 v[68:71], v[166:169], v[206:209], v[68:71]
	v_mfma_f32_16x16x32_bf16 v[64:67], v[174:177], v[206:209], v[64:67]
	v_mfma_f32_16x16x32_bf16 v[116:119], v[170:173], v[186:189], v[116:119]
	v_mfma_f32_16x16x32_bf16 v[112:115], v[178:181], v[186:189], v[112:115]
	v_mfma_f32_16x16x32_bf16 v[100:103], v[170:173], v[194:197], v[100:103]
	v_mfma_f32_16x16x32_bf16 v[96:99], v[178:181], v[194:197], v[96:99]
	v_mfma_f32_16x16x32_bf16 v[84:87], v[170:173], v[202:205], v[84:87]
	v_mfma_f32_16x16x32_bf16 v[80:83], v[178:181], v[202:205], v[80:83]
	v_mfma_f32_16x16x32_bf16 v[68:71], v[170:173], v[210:213], v[68:71]
	v_mfma_f32_16x16x32_bf16 v[64:67], v[178:181], v[210:213], v[64:67]
	s_barrier
	s_setprio 0
	s_add_i32 s34, s55, s5
	s_mov_b32 m0, s34
	ds_read_b128 v[182:185], v149 offset:49152
	ds_read_b128 v[186:189], v149 offset:50176
	ds_read_b128 v[190:193], v149 offset:51200
	ds_read_b128 v[194:197], v149 offset:52224
	ds_read_b128 v[198:201], v149 offset:53248
	ds_read_b128 v[202:205], v149 offset:54272
	ds_read_b128 v[206:209], v149 offset:55296
	ds_read_b128 v[210:213], v149 offset:56320
	global_load_lds_dwordx4 v132, s[98:99]
	s_add_i32 m0, s34, 0x2000
	s_add_u32 s30, s30, 0x40080
	s_addc_u32 s31, s31, 0
	s_add_i32 s34, s56, s5
	global_load_lds_dwordx4 v128, s[98:99]
	s_mov_b32 m0, s34
	s_nop 0
	global_load_lds_dwordx4 v132, s[30:31]
	s_add_i32 m0, s34, 0x2000
	s_nop 0
	global_load_lds_dwordx4 v128, s[30:31]
	s_waitcnt vmcnt(6)
	s_waitcnt lgkmcnt(0)
	s_setprio 1
	s_barrier
	v_mfma_f32_16x16x32_bf16 v[60:63], v[150:153], v[182:185], v[60:63]
	v_mfma_f32_16x16x32_bf16 v[56:59], v[158:161], v[182:185], v[56:59]
	v_mfma_f32_16x16x32_bf16 v[44:47], v[150:153], v[190:193], v[44:47]
	v_mfma_f32_16x16x32_bf16 v[40:43], v[158:161], v[190:193], v[40:43]
	v_mfma_f32_16x16x32_bf16 v[28:31], v[150:153], v[198:201], v[28:31]
	v_mfma_f32_16x16x32_bf16 v[24:27], v[158:161], v[198:201], v[24:27]
	v_mfma_f32_16x16x32_bf16 v[12:15], v[150:153], v[206:209], v[12:15]
	v_mfma_f32_16x16x32_bf16 v[8:11], v[158:161], v[206:209], v[8:11]
	v_mfma_f32_16x16x32_bf16 v[60:63], v[154:157], v[186:189], v[60:63]
	v_mfma_f32_16x16x32_bf16 v[56:59], v[162:165], v[186:189], v[56:59]
	v_mfma_f32_16x16x32_bf16 v[44:47], v[154:157], v[194:197], v[44:47]
	v_mfma_f32_16x16x32_bf16 v[40:43], v[162:165], v[194:197], v[40:43]
	v_mfma_f32_16x16x32_bf16 v[28:31], v[154:157], v[202:205], v[28:31]
	v_mfma_f32_16x16x32_bf16 v[24:27], v[162:165], v[202:205], v[24:27]
	v_mfma_f32_16x16x32_bf16 v[12:15], v[154:157], v[210:213], v[12:15]
	v_mfma_f32_16x16x32_bf16 v[8:11], v[162:165], v[210:213], v[8:11]
	v_mfma_f32_16x16x32_bf16 v[52:55], v[166:169], v[182:185], v[52:55]
	v_mfma_f32_16x16x32_bf16 v[48:51], v[174:177], v[182:185], v[48:51]
	v_mfma_f32_16x16x32_bf16 v[36:39], v[166:169], v[190:193], v[36:39]
	v_mfma_f32_16x16x32_bf16 v[32:35], v[174:177], v[190:193], v[32:35]
	v_mfma_f32_16x16x32_bf16 v[20:23], v[166:169], v[198:201], v[20:23]
	v_mfma_f32_16x16x32_bf16 v[16:19], v[174:177], v[198:201], v[16:19]
	v_mfma_f32_16x16x32_bf16 v[4:7], v[166:169], v[206:209], v[4:7]
	v_mfma_f32_16x16x32_bf16 v[0:3], v[174:177], v[206:209], v[0:3]
	v_mfma_f32_16x16x32_bf16 v[52:55], v[170:173], v[186:189], v[52:55]
	v_mfma_f32_16x16x32_bf16 v[48:51], v[178:181], v[186:189], v[48:51]
	v_mfma_f32_16x16x32_bf16 v[36:39], v[170:173], v[194:197], v[36:39]
	v_mfma_f32_16x16x32_bf16 v[32:35], v[178:181], v[194:197], v[32:35]
	v_mfma_f32_16x16x32_bf16 v[20:23], v[170:173], v[202:205], v[20:23]
	v_mfma_f32_16x16x32_bf16 v[16:19], v[178:181], v[202:205], v[16:19]
	v_mfma_f32_16x16x32_bf16 v[4:7], v[170:173], v[210:213], v[4:7]
	v_mfma_f32_16x16x32_bf16 v[0:3], v[178:181], v[210:213], v[0:3]
	s_barrier
	s_setprio 0
	s_add_u32 s28, s28, 0x100
	s_addc_u32 s29, s29, 0
	s_add_u32 s52, s52, 0x100
	s_addc_u32 s53, s53, 0
	s_cmp_ge_i32 s54, s42
	s_mov_b32 s30, s54
	s_cbranch_scc0 .LBB0_1112

; #define PG8_STAGE(bufoff, gbase, voff) do { _Pragma("unroll") for (int _i = 0; _i < 2; ++_i) \
;         __builtin_amdgcn_global_load_lds((const unsigned*)((const char*)(gbase) + (voff)[_i]), (LAS unsigned*)(lds + (bufoff) + ldsw + _i * 8192), 16, 0, ((voff) == voffA ? AUXA : 0)); } while (0)
; #define PG8_LDA(dst, b, h) do { _Pragma("unroll") for (int m = 0; m < 4; ++m) _Pragma("unroll") for (int k = 0; k < 2; ++k) dst[m][k] = *(const LAS bf16x8*)(lds + PG8_SA(b, h) + aoff + m * 2048 + k * 1024); } while (0)
; #define PG8_LDB(dst, b, h) do { _Pragma("unroll") for (int n = 0; n < 2; ++n) _Pragma("unroll") for (int k = 0; k < 2; ++k) dst[n][k] = *(const LAS bf16x8*)(lds + PG8_SB(b, h) + boff + n * 2048 + k * 1024); } while (0)
; #define PG8_MMA(ai, bj, At, Bt) do { __builtin_amdgcn_s_setprio(1); _Pragma("unroll") for (int m = 0; m < 4; ++m) _Pragma("unroll") for (int n = 0; n < 2; ++n) _Pragma("unroll") for (int k = 0; k < 2; ++k) \
;         acc[ai][bj][m][n] = __builtin_amdgcn_mfma_f32_16x16x32_bf16(Bt[n][k], At[m][k], acc[ai][bj][m][n], 0, 0, 0); __builtin_amdgcn_s_setprio(0); } while (0)
; #define PG8_WAIT_V(n) asm volatile("s_waitcnt vmcnt(" #n ")" ::: "memory")
; #define PG8_WAIT_L(n) asm volatile("s_waitcnt lgkmcnt(" #n ")" ::: "memory")
; #define PG8_BAR __builtin_amdgcn_s_barrier()
; #define PG8_SCHED __builtin_amdgcn_sched_barrier(0)
;     ...
;             PG8_LDA(At, 0, 1); PG8_STAGE(PG8_SB(0, 0), b2, voffB); PG8_STAGE(PG8_SB(0, 1), b2 + hsB, voffB); PG8_STAGE(PG8_SA(0, 0), a2, voffA);
;             if (Epi::NPRE != 0 && last) { PG8_WAIT_V(16); } else { PG8_WAIT_V(8); }
;             PG8_WAIT_L(0); PG8_BAR; PG8_MMA(1, 0, At, B0); PG8_MMA(1, 1, At, B1); PG8_BAR; PG8_SCHED;
;             PG8_LDB(B0, 1, 0); PG8_LDB(B1, 1, 1); PG8_SCHED; PG8_LDA(At, 1, 0); PG8_STAGE(PG8_SA(0, 1), a2 + hsA, voffA);
;             PG8_WAIT_V(8); PG8_WAIT_L(0); PG8_BAR; PG8_MMA(0, 0, At, B0); PG8_MMA(0, 1, At, B1); PG8_BAR; PG8_SCHED;
.LBB0_1184:
	s_waitcnt lgkmcnt(0)
	s_add_i32 s62, s62, 2
	s_setprio 1
	s_barrier
	v_mfma_f32_16x16x32_bf16 v[60:63], v[144:147], v[184:187], v[60:63]
	v_mfma_f32_16x16x32_bf16 v[52:55], v[152:155], v[184:187], v[52:55]
	v_mfma_f32_16x16x32_bf16 v[44:47], v[144:147], v[176:179], v[44:47]
	v_mfma_f32_16x16x32_bf16 v[36:39], v[152:155], v[176:179], v[36:39]
	v_mfma_f32_16x16x32_bf16 v[28:31], v[144:147], v[168:171], v[28:31]
	v_mfma_f32_16x16x32_bf16 v[20:23], v[152:155], v[168:171], v[20:23]
	v_mfma_f32_16x16x32_bf16 v[12:15], v[144:147], v[160:163], v[12:15]
	v_mfma_f32_16x16x32_bf16 v[4:7], v[152:155], v[160:163], v[4:7]
	v_mfma_f32_16x16x32_bf16 v[60:63], v[148:151], v[188:191], v[60:63]
	v_mfma_f32_16x16x32_bf16 v[52:55], v[156:159], v[188:191], v[52:55]
	v_mfma_f32_16x16x32_bf16 v[44:47], v[148:151], v[180:183], v[44:47]
	v_mfma_f32_16x16x32_bf16 v[36:39], v[156:159], v[180:183], v[36:39]
	v_mfma_f32_16x16x32_bf16 v[28:31], v[148:151], v[172:175], v[28:31]
	v_mfma_f32_16x16x32_bf16 v[20:23], v[156:159], v[172:175], v[20:23]
	v_mfma_f32_16x16x32_bf16 v[12:15], v[148:151], v[164:167], v[12:15]
	v_mfma_f32_16x16x32_bf16 v[4:7], v[156:159], v[164:167], v[4:7]
	v_mfma_f32_16x16x32_bf16 v[56:59], v[128:131], v[184:187], v[56:59]
	v_mfma_f32_16x16x32_bf16 v[48:51], v[136:139], v[184:187], v[48:51]
	v_mfma_f32_16x16x32_bf16 v[40:43], v[128:131], v[176:179], v[40:43]
	v_mfma_f32_16x16x32_bf16 v[32:35], v[136:139], v[176:179], v[32:35]
	v_mfma_f32_16x16x32_bf16 v[24:27], v[128:131], v[168:171], v[24:27]
	v_mfma_f32_16x16x32_bf16 v[16:19], v[136:139], v[168:171], v[16:19]
	v_mfma_f32_16x16x32_bf16 v[8:11], v[128:131], v[160:163], v[8:11]
	v_mfma_f32_16x16x32_bf16 v[0:3], v[136:139], v[160:163], v[0:3]
	v_mfma_f32_16x16x32_bf16 v[56:59], v[132:135], v[188:191], v[56:59]
	v_mfma_f32_16x16x32_bf16 v[48:51], v[140:143], v[188:191], v[48:51]
	v_mfma_f32_16x16x32_bf16 v[40:43], v[132:135], v[180:183], v[40:43]
	v_mfma_f32_16x16x32_bf16 v[32:35], v[140:143], v[180:183], v[32:35]
	v_mfma_f32_16x16x32_bf16 v[24:27], v[132:135], v[172:175], v[24:27]
	v_mfma_f32_16x16x32_bf16 v[16:19], v[140:143], v[172:175], v[16:19]
	v_mfma_f32_16x16x32_bf16 v[8:11], v[132:135], v[164:167], v[8:11]
	v_mfma_f32_16x16x32_bf16 v[0:3], v[140:143], v[164:167], v[0:3]
	s_barrier
	s_mov_b32 m0, s42
	s_nop 0
	global_load_lds_dwordx4 v198, s[34:35]
	s_mov_b32 m0, s47
	s_nop 0
	global_load_lds_dwordx4 v194, s[34:35]
	s_setprio 0
	s_add_i32 s36, 0, 0x18000
	s_add_i32 s37, 0, 0x1c000
	v_add_u32_e32 v140, s36, v221
	v_add_u32_e32 v156, s37, v221
	ds_read_b128 v[128:131], v140
	ds_read_b128 v[132:135], v140 offset:1024
	ds_read_b128 v[136:139], v140 offset:2048
	ds_read_b128 v[140:143], v140 offset:3072
	ds_read_b128 v[144:147], v156
	ds_read_b128 v[148:151], v156 offset:1024
	ds_read_b128 v[152:155], v156 offset:2048
	ds_read_b128 v[156:159], v156 offset:3072
	s_add_u32 s34, s34, 0x80000
	s_addc_u32 s35, s35, 0
	s_mov_b32 m0, s48
	ds_read_b128 v[160:163], v225 offset:32768
	ds_read_b128 v[164:167], v225 offset:33792
	ds_read_b128 v[168:171], v225 offset:34816
	ds_read_b128 v[172:175], v225 offset:35840
	ds_read_b128 v[176:179], v225 offset:36864
	ds_read_b128 v[180:183], v225 offset:37888
	ds_read_b128 v[184:187], v225 offset:38912
	ds_read_b128 v[188:191], v225 offset:39936
	global_load_lds_dwordx4 v198, s[34:35]
	s_mov_b32 m0, s49
	s_nop 0
	global_load_lds_dwordx4 v194, s[34:35]
	s_waitcnt vmcnt(8)
	s_waitcnt lgkmcnt(0)
	s_setprio 1
	s_barrier
	v_mfma_f32_16x16x32_bf16 v[124:127], v[128:131], v[160:163], v[124:127]
	v_mfma_f32_16x16x32_bf16 v[116:119], v[136:139], v[160:163], v[116:119]
	v_mfma_f32_16x16x32_bf16 v[108:111], v[128:131], v[168:171], v[108:111]
	v_mfma_f32_16x16x32_bf16 v[100:103], v[136:139], v[168:171], v[100:103]
	v_mfma_f32_16x16x32_bf16 v[92:95], v[128:131], v[176:179], v[92:95]
	v_mfma_f32_16x16x32_bf16 v[84:87], v[136:139], v[176:179], v[84:87]
	v_mfma_f32_16x16x32_bf16 v[76:79], v[128:131], v[184:187], v[76:79]
	v_mfma_f32_16x16x32_bf16 v[68:71], v[136:139], v[184:187], v[68:71]
	v_mfma_f32_16x16x32_bf16 v[124:127], v[132:135], v[164:167], v[124:127]
	v_mfma_f32_16x16x32_bf16 v[116:119], v[140:143], v[164:167], v[116:119]
	v_mfma_f32_16x16x32_bf16 v[108:111], v[132:135], v[172:175], v[108:111]
	v_mfma_f32_16x16x32_bf16 v[100:103], v[140:143], v[172:175], v[100:103]
	v_mfma_f32_16x16x32_bf16 v[92:95], v[132:135], v[180:183], v[92:95]
	v_mfma_f32_16x16x32_bf16 v[84:87], v[140:143], v[180:183], v[84:87]
	v_mfma_f32_16x16x32_bf16 v[76:79], v[132:135], v[188:191], v[76:79]
	v_mfma_f32_16x16x32_bf16 v[68:71], v[140:143], v[188:191], v[68:71]
	v_mfma_f32_16x16x32_bf16 v[120:123], v[144:147], v[160:163], v[120:123]
	v_mfma_f32_16x16x32_bf16 v[112:115], v[152:155], v[160:163], v[112:115]
	v_mfma_f32_16x16x32_bf16 v[104:107], v[144:147], v[168:171], v[104:107]
	v_mfma_f32_16x16x32_bf16 v[96:99], v[152:155], v[168:171], v[96:99]
	v_mfma_f32_16x16x32_bf16 v[88:91], v[144:147], v[176:179], v[88:91]
	v_mfma_f32_16x16x32_bf16 v[80:83], v[152:155], v[176:179], v[80:83]
	v_mfma_f32_16x16x32_bf16 v[72:75], v[144:147], v[184:187], v[72:75]
	v_mfma_f32_16x16x32_bf16 v[64:67], v[152:155], v[184:187], v[64:67]
	v_mfma_f32_16x16x32_bf16 v[120:123], v[148:151], v[164:167], v[120:123]
	v_mfma_f32_16x16x32_bf16 v[112:115], v[156:159], v[164:167], v[112:115]
	v_mfma_f32_16x16x32_bf16 v[104:107], v[148:151], v[172:175], v[104:107]
	v_mfma_f32_16x16x32_bf16 v[96:99], v[156:159], v[172:175], v[96:99]
	v_mfma_f32_16x16x32_bf16 v[88:91], v[148:151], v[180:183], v[88:91]
	v_mfma_f32_16x16x32_bf16 v[80:83], v[156:159], v[180:183], v[80:83]
	v_mfma_f32_16x16x32_bf16 v[72:75], v[148:151], v[188:191], v[72:75]
	v_mfma_f32_16x16x32_bf16 v[64:67], v[156:159], v[188:191], v[64:67]
	s_barrier
; #define PG8_STAGE(bufoff, gbase, voff) do { _Pragma("unroll") for (int _i = 0; _i < 2; ++_i) \
;         __builtin_amdgcn_global_load_lds((const unsigned*)((const char*)(gbase) + (voff)[_i]), (LAS unsigned*)(lds + (bufoff) + ldsw + _i * 8192), 16, 0, ((voff) == voffA ? AUXA : 0)); } while (0)
; #define PG8_LDA(dst, b, h) do { _Pragma("unroll") for (int m = 0; m < 4; ++m) _Pragma("unroll") for (int k = 0; k < 2; ++k) dst[m][k] = *(const LAS bf16x8*)(lds + PG8_SA(b, h) + aoff + m * 2048 + k * 1024); } while (0)
; #define PG8_LDB(dst, b, h) do { _Pragma("unroll") for (int n = 0; n < 2; ++n) _Pragma("unroll") for (int k = 0; k < 2; ++k) dst[n][k] = *(const LAS bf16x8*)(lds + PG8_SB(b, h) + boff + n * 2048 + k * 1024); } while (0)
; #define PG8_MMA(ai, bj, At, Bt) do { __builtin_amdgcn_s_setprio(1); _Pragma("unroll") for (int m = 0; m < 4; ++m) _Pragma("unroll") for (int n = 0; n < 2; ++n) _Pragma("unroll") for (int k = 0; k < 2; ++k) \
;         acc[ai][bj][m][n] = __builtin_amdgcn_mfma_f32_16x16x32_bf16(Bt[n][k], At[m][k], acc[ai][bj][m][n], 0, 0, 0); __builtin_amdgcn_s_setprio(0); } while (0)
; #define PG8_WAIT_V(n) asm volatile("s_waitcnt vmcnt(" #n ")" ::: "memory")
;     ...
;             PG8_LDB(B0, 0, 0); PG8_LDB(B1, 0, 1); PG8_SCHED; PG8_LDA(At, 0, 0); PG8_STAGE(PG8_SA(1, 1), a1 + hsA, voffA);
;             if (Epi::NPRE != 0 && last) { E.pre(sv, cur, wr, fr); PG8_WAIT_V(16); } else { PG8_WAIT_V(8); }
;             PG8_WAIT_L(0); PG8_BAR; PG8_MMA(0, 0, At, B0); PG8_MMA(0, 1, At, B1); PG8_BAR; PG8_SCHED;
;             PG8_LDA(At, 0, 1); PG8_STAGE(PG8_SB(0, 0), b2, voffB); PG8_STAGE(PG8_SB(0, 1), b2 + hsB, voffB); PG8_STAGE(PG8_SA(0, 0), a2, voffA);
;             if (Epi::NPRE != 0 && last) { PG8_WAIT_V(16); } else { PG8_WAIT_V(8); }
;             PG8_WAIT_L(0); PG8_BAR; PG8_MMA(1, 0, At, B0); PG8_MMA(1, 1, At, B1); PG8_BAR; PG8_SCHED;
;             PG8_LDB(B0, 1, 0); PG8_LDB(B1, 1, 1); PG8_SCHED; PG8_LDA(At, 1, 0); PG8_STAGE(PG8_SA(0, 1), a2 + hsA, voffA);
;             PG8_WAIT_V(8); PG8_WAIT_L(0); PG8_BAR; PG8_MMA(0, 0, At, B0); PG8_MMA(0, 1, At, B1); PG8_BAR; PG8_SCHED;
;             PG8_LDA(At, 1, 1); PG8_STAGE(PG8_SB(1, 0), b3, voffB); PG8_STAGE(PG8_SB(1, 1), b3 + hsB, voffB); PG8_STAGE(PG8_SA(1, 0), a3, voffA);
;             PG8_WAIT_V(8); PG8_WAIT_L(0); PG8_BAR; PG8_MMA(1, 0, At, B0); PG8_MMA(1, 1, At, B1); PG8_BAR; PG8_SCHED;
	s_setprio 0
	s_add_i32 s34, s36, s5
	s_mov_b32 m0, s34
	ds_read_b128 v[160:163], v225 offset:49152
	ds_read_b128 v[164:167], v225 offset:50176
	ds_read_b128 v[168:171], v225 offset:51200
	ds_read_b128 v[172:175], v225 offset:52224
	ds_read_b128 v[176:179], v225 offset:53248
	ds_read_b128 v[180:183], v225 offset:54272
	ds_read_b128 v[184:187], v225 offset:55296
	ds_read_b128 v[188:191], v225 offset:56320
	global_load_lds_dwordx4 v196, s[98:99]
	s_add_i32 m0, s34, 0x2000
	s_add_u32 s30, s30, 0x80080
	s_addc_u32 s31, s31, 0
	s_add_i32 s34, s37, s5
	global_load_lds_dwordx4 v192, s[98:99]
	s_mov_b32 m0, s34
	s_nop 0
	global_load_lds_dwordx4 v196, s[30:31]
	s_add_i32 m0, s34, 0x2000
	s_nop 0
	global_load_lds_dwordx4 v192, s[30:31]
	s_waitcnt vmcnt(6)
	s_waitcnt lgkmcnt(0)
	s_setprio 1
	s_barrier
	v_mfma_f32_16x16x32_bf16 v[60:63], v[128:131], v[160:163], v[60:63]
	v_mfma_f32_16x16x32_bf16 v[52:55], v[136:139], v[160:163], v[52:55]
	v_mfma_f32_16x16x32_bf16 v[44:47], v[128:131], v[168:171], v[44:47]
	v_mfma_f32_16x16x32_bf16 v[36:39], v[136:139], v[168:171], v[36:39]
	v_mfma_f32_16x16x32_bf16 v[28:31], v[128:131], v[176:179], v[28:31]
	v_mfma_f32_16x16x32_bf16 v[20:23], v[136:139], v[176:179], v[20:23]
	v_mfma_f32_16x16x32_bf16 v[12:15], v[128:131], v[184:187], v[12:15]
	v_mfma_f32_16x16x32_bf16 v[4:7], v[136:139], v[184:187], v[4:7]
	v_mfma_f32_16x16x32_bf16 v[60:63], v[132:135], v[164:167], v[60:63]
	v_mfma_f32_16x16x32_bf16 v[52:55], v[140:143], v[164:167], v[52:55]
	v_mfma_f32_16x16x32_bf16 v[44:47], v[132:135], v[172:175], v[44:47]
	v_mfma_f32_16x16x32_bf16 v[36:39], v[140:143], v[172:175], v[36:39]
	v_mfma_f32_16x16x32_bf16 v[28:31], v[132:135], v[180:183], v[28:31]
	v_mfma_f32_16x16x32_bf16 v[20:23], v[140:143], v[180:183], v[20:23]
	v_mfma_f32_16x16x32_bf16 v[12:15], v[132:135], v[188:191], v[12:15]
	v_mfma_f32_16x16x32_bf16 v[4:7], v[140:143], v[188:191], v[4:7]
	v_mfma_f32_16x16x32_bf16 v[56:59], v[144:147], v[160:163], v[56:59]
	v_mfma_f32_16x16x32_bf16 v[48:51], v[152:155], v[160:163], v[48:51]
	v_mfma_f32_16x16x32_bf16 v[40:43], v[144:147], v[168:171], v[40:43]
	v_mfma_f32_16x16x32_bf16 v[32:35], v[152:155], v[168:171], v[32:35]
	v_mfma_f32_16x16x32_bf16 v[24:27], v[144:147], v[176:179], v[24:27]
	v_mfma_f32_16x16x32_bf16 v[16:19], v[152:155], v[176:179], v[16:19]
	v_mfma_f32_16x16x32_bf16 v[8:11], v[144:147], v[184:187], v[8:11]
	v_mfma_f32_16x16x32_bf16 v[0:3], v[152:155], v[184:187], v[0:3]
	v_mfma_f32_16x16x32_bf16 v[56:59], v[148:151], v[164:167], v[56:59]
	v_mfma_f32_16x16x32_bf16 v[48:51], v[156:159], v[164:167], v[48:51]
	v_mfma_f32_16x16x32_bf16 v[40:43], v[148:151], v[172:175], v[40:43]
	v_mfma_f32_16x16x32_bf16 v[32:35], v[156:159], v[172:175], v[32:35]
	v_mfma_f32_16x16x32_bf16 v[24:27], v[148:151], v[180:183], v[24:27]
	v_mfma_f32_16x16x32_bf16 v[16:19], v[156:159], v[180:183], v[16:19]
	v_mfma_f32_16x16x32_bf16 v[8:11], v[148:151], v[188:191], v[8:11]
	v_mfma_f32_16x16x32_bf16 v[0:3], v[156:159], v[188:191], v[0:3]
	s_barrier
	s_setprio 0
	s_add_u32 s28, s28, 0x100
	s_addc_u32 s29, s29, 0
	s_add_u32 s60, s60, 0x100
	s_addc_u32 s61, s61, 0
	s_cmp_ge_i32 s62, s51
	s_cbranch_scc1 .LBB0_1194
.LBB0_1185:
	s_add_u32 s98, s28, 0xfff80000
	s_addc_u32 s99, s29, -1
	s_mov_b32 m0, s52
	s_nop 0
	global_load_lds_dwordx4 v198, s[98:99]
	s_mov_b32 m0, s53
	s_nop 0
	global_load_lds_dwordx4 v194, s[98:99]
	ds_read_b128 v[144:147], v223
	ds_read_b128 v[148:151], v223 offset:1024
	ds_read_b128 v[152:155], v223 offset:2048
	ds_read_b128 v[156:159], v223 offset:3072
	ds_read_b128 v[128:131], v224
	ds_read_b128 v[132:135], v224 offset:1024
	ds_read_b128 v[136:139], v224 offset:2048
	ds_read_b128 v[140:143], v224 offset:3072
	s_cmp_eq_u32 s54, s62
	s_cselect_b64 s[30:31], -1, 0
	s_cmp_lg_u32 s54, s62
	s_cselect_b64 s[36:37], -1, 0
	s_add_i32 m0, s42, 0xc000
	ds_read_b128 v[184:187], v225
	ds_read_b128 v[188:191], v225 offset:1024
	ds_read_b128 v[176:179], v225 offset:2048
	ds_read_b128 v[180:183], v225 offset:3072
	ds_read_b128 v[168:171], v225 offset:4096
	ds_read_b128 v[172:175], v225 offset:5120
	ds_read_b128 v[160:163], v225 offset:6144
	ds_read_b128 v[164:167], v225 offset:7168
	global_load_lds_dwordx4 v200, s[28:29]
	s_add_i32 m0, s42, 0xe000
	s_mov_b64 s[34:35], -1
	global_load_lds_dwordx4 v202, s[28:29]
	s_and_b64 vcc, exec, s[36:37]
	s_cbranch_vccz .LBB0_1187
	s_waitcnt vmcnt(8)
	s_mov_b64 s[34:35], 0

; #define PG8_STAGE(bufoff, gbase, voff) do { _Pragma("unroll") for (int _i = 0; _i < 2; ++_i) \
;         __builtin_amdgcn_global_load_lds((const unsigned*)((const char*)(gbase) + (voff)[_i]), (LAS unsigned*)(lds + (bufoff) + ldsw + _i * 8192), 16, 0, ((voff) == voffA ? AUXA : 0)); } while (0)
; #define PG8_LDA(dst, b, h) do { _Pragma("unroll") for (int m = 0; m < 4; ++m) _Pragma("unroll") for (int k = 0; k < 2; ++k) dst[m][k] = *(const LAS bf16x8*)(lds + PG8_SA(b, h) + aoff + m * 2048 + k * 1024); } while (0)
; #define PG8_MMA(ai, bj, At, Bt) do { __builtin_amdgcn_s_setprio(1); _Pragma("unroll") for (int m = 0; m < 4; ++m) _Pragma("unroll") for (int n = 0; n < 2; ++n) _Pragma("unroll") for (int k = 0; k < 2; ++k) \
;         acc[ai][bj][m][n] = __builtin_amdgcn_mfma_f32_16x16x32_bf16(Bt[n][k], At[m][k], acc[ai][bj][m][n], 0, 0, 0); __builtin_amdgcn_s_setprio(0); } while (0)
; #define PG8_WAIT_V(n) asm volatile("s_waitcnt vmcnt(" #n ")" ::: "memory")
; #define PG8_WAIT_L(n) asm volatile("s_waitcnt lgkmcnt(" #n ")" ::: "memory")
; #define PG8_BAR __builtin_amdgcn_s_barrier()
; #define PG8_SCHED __builtin_amdgcn_sched_barrier(0)
;     ...
;             if (Epi::NPRE != 0 && last) { E.pre(sv, cur, wr, fr); PG8_WAIT_V(16); } else { PG8_WAIT_V(8); }
;             PG8_WAIT_L(0); PG8_BAR; PG8_MMA(0, 0, At, B0); PG8_MMA(0, 1, At, B1); PG8_BAR; PG8_SCHED;
;             PG8_LDA(At, 0, 1); PG8_STAGE(PG8_SB(0, 0), b2, voffB); PG8_STAGE(PG8_SB(0, 1), b2 + hsB, voffB); PG8_STAGE(PG8_SA(0, 0), a2, voffA);
;             if (Epi::NPRE != 0 && last) { PG8_WAIT_V(16); } else { PG8_WAIT_V(8); }
;             PG8_WAIT_L(0); PG8_BAR; PG8_MMA(1, 0, At, B0); PG8_MMA(1, 1, At, B1); PG8_BAR; PG8_SCHED;
.LBB0_1189:
	s_add_u32 s34, s28, 0xfff80080
	s_addc_u32 s35, s29, -1
	s_waitcnt lgkmcnt(0)
	s_and_b64 s[30:31], s[30:31], exec
	s_cselect_b32 s35, s21, s35
	s_cselect_b32 s34, s23, s34
	s_cselect_b32 s31, s58, s61
	s_cselect_b32 s30, s59, s60
	s_setprio 1
	s_barrier
	v_mfma_f32_16x16x32_bf16 v[124:127], v[144:147], v[184:187], v[124:127]
	v_mfma_f32_16x16x32_bf16 v[116:119], v[152:155], v[184:187], v[116:119]
	v_mfma_f32_16x16x32_bf16 v[108:111], v[144:147], v[176:179], v[108:111]
	v_mfma_f32_16x16x32_bf16 v[100:103], v[152:155], v[176:179], v[100:103]
	v_mfma_f32_16x16x32_bf16 v[92:95], v[144:147], v[168:171], v[92:95]
	v_mfma_f32_16x16x32_bf16 v[84:87], v[152:155], v[168:171], v[84:87]
	v_mfma_f32_16x16x32_bf16 v[76:79], v[144:147], v[160:163], v[76:79]
	v_mfma_f32_16x16x32_bf16 v[68:71], v[152:155], v[160:163], v[68:71]
	v_mfma_f32_16x16x32_bf16 v[124:127], v[148:151], v[188:191], v[124:127]
	v_mfma_f32_16x16x32_bf16 v[116:119], v[156:159], v[188:191], v[116:119]
	v_mfma_f32_16x16x32_bf16 v[108:111], v[148:151], v[180:183], v[108:111]
	v_mfma_f32_16x16x32_bf16 v[100:103], v[156:159], v[180:183], v[100:103]
	v_mfma_f32_16x16x32_bf16 v[92:95], v[148:151], v[172:175], v[92:95]
	v_mfma_f32_16x16x32_bf16 v[84:87], v[156:159], v[172:175], v[84:87]
	v_mfma_f32_16x16x32_bf16 v[76:79], v[148:151], v[164:167], v[76:79]
	v_mfma_f32_16x16x32_bf16 v[68:71], v[156:159], v[164:167], v[68:71]
	v_mfma_f32_16x16x32_bf16 v[120:123], v[128:131], v[184:187], v[120:123]
	v_mfma_f32_16x16x32_bf16 v[112:115], v[136:139], v[184:187], v[112:115]
	v_mfma_f32_16x16x32_bf16 v[104:107], v[128:131], v[176:179], v[104:107]
	v_mfma_f32_16x16x32_bf16 v[96:99], v[136:139], v[176:179], v[96:99]
	v_mfma_f32_16x16x32_bf16 v[88:91], v[128:131], v[168:171], v[88:91]
	v_mfma_f32_16x16x32_bf16 v[80:83], v[136:139], v[168:171], v[80:83]
	v_mfma_f32_16x16x32_bf16 v[72:75], v[128:131], v[160:163], v[72:75]
	v_mfma_f32_16x16x32_bf16 v[64:67], v[136:139], v[160:163], v[64:67]
	v_mfma_f32_16x16x32_bf16 v[120:123], v[132:135], v[188:191], v[120:123]
	v_mfma_f32_16x16x32_bf16 v[112:115], v[140:143], v[188:191], v[112:115]
	v_mfma_f32_16x16x32_bf16 v[104:107], v[132:135], v[180:183], v[104:107]
	v_mfma_f32_16x16x32_bf16 v[96:99], v[140:143], v[180:183], v[96:99]
	v_mfma_f32_16x16x32_bf16 v[88:91], v[132:135], v[172:175], v[88:91]
	v_mfma_f32_16x16x32_bf16 v[80:83], v[140:143], v[172:175], v[80:83]
	v_mfma_f32_16x16x32_bf16 v[72:75], v[132:135], v[164:167], v[72:75]
	v_mfma_f32_16x16x32_bf16 v[64:67], v[140:143], v[164:167], v[64:67]
	s_barrier
	s_setprio 0
	s_add_u32 s98, s30, s16
	s_addc_u32 s99, s31, s17
	s_add_u32 s100, s34, s16
	s_addc_u32 s101, s35, s17
	s_mov_b32 m0, s43
	s_add_u32 s38, s30, 0x80000
	ds_read_b128 v[184:187], v225 offset:16384
	ds_read_b128 v[188:191], v225 offset:17408
	ds_read_b128 v[176:179], v225 offset:18432
	ds_read_b128 v[180:183], v225 offset:19456
	ds_read_b128 v[168:171], v225 offset:20480
	ds_read_b128 v[172:175], v225 offset:21504
	ds_read_b128 v[160:163], v225 offset:22528
	ds_read_b128 v[164:167], v225 offset:23552
	global_load_lds_dwordx4 v196, s[30:31]
	s_mov_b32 m0, s44
	s_addc_u32 s39, s31, 0
	global_load_lds_dwordx4 v192, s[30:31]
	s_mov_b32 m0, s45
	s_nop 0
	global_load_lds_dwordx4 v196, s[38:39]
	s_mov_b32 m0, s46
	s_nop 0
	global_load_lds_dwordx4 v192, s[38:39]
	s_mov_b64 s[38:39], -1
	s_and_b64 vcc, exec, s[36:37]
	s_cbranch_vccz .LBB0_1191
	s_waitcnt vmcnt(6)
	s_mov_b64 s[38:39], 0

; #define PG8_STAGE(bufoff, gbase, voff) do { _Pragma("unroll") for (int _i = 0; _i < 2; ++_i) \
;         __builtin_amdgcn_global_load_lds((const unsigned*)((const char*)(gbase) + (voff)[_i]), (LAS unsigned*)(lds + (bufoff) + ldsw + _i * 8192), 16, 0, ((voff) == voffA ? AUXA : 0)); } while (0)
; #define PG8_LDA(dst, b, h) do { _Pragma("unroll") for (int m = 0; m < 4; ++m) _Pragma("unroll") for (int k = 0; k < 2; ++k) dst[m][k] = *(const LAS bf16x8*)(lds + PG8_SA(b, h) + aoff + m * 2048 + k * 1024); } while (0)
; #define PG8_LDB(dst, b, h) do { _Pragma("unroll") for (int n = 0; n < 2; ++n) _Pragma("unroll") for (int k = 0; k < 2; ++k) dst[n][k] = *(const LAS bf16x8*)(lds + PG8_SB(b, h) + boff + n * 2048 + k * 1024); } while (0)
; #define PG8_MMA(ai, bj, At, Bt) do { __builtin_amdgcn_s_setprio(1); _Pragma("unroll") for (int m = 0; m < 4; ++m) _Pragma("unroll") for (int n = 0; n < 2; ++n) _Pragma("unroll") for (int k = 0; k < 2; ++k) \
;         acc[ai][bj][m][n] = __builtin_amdgcn_mfma_f32_16x16x32_bf16(Bt[n][k], At[m][k], acc[ai][bj][m][n], 0, 0, 0); __builtin_amdgcn_s_setprio(0); } while (0)
; #define PG8_WAIT_V(n) asm volatile("s_waitcnt vmcnt(" #n ")" ::: "memory")
; #define PG8_WAIT_L(n) asm volatile("s_waitcnt lgkmcnt(" #n ")" ::: "memory")
; #define PG8_BAR __builtin_amdgcn_s_barrier()
; #define PG8_SCHED __builtin_amdgcn_sched_barrier(0)
;     ...
;         for (int t = 0; t < nt; t += 2) {
;             const bool last = (t == nt - 2);
;             const char* a1 = cA + (size_t)(t + 1) * kstep;
;             const char* a2 = last ? nA : cA + (size_t)(t + 2) * kstep; const char* b2 = last ? nB : cB + (size_t)(t + 2) * kstep;
;             const char* a3 = a2 + kstep; const char* b3 = b2 + kstep;
;             PG8_LDB(B0, 0, 0); PG8_LDB(B1, 0, 1); PG8_SCHED; PG8_LDA(At, 0, 0); PG8_STAGE(PG8_SA(1, 1), a1 + hsA, voffA);
;             if (Epi::NPRE != 0 && last) { E.pre(sv, cur, wr, fr); PG8_WAIT_V(16); } else { PG8_WAIT_V(8); }
;             PG8_WAIT_L(0); PG8_BAR; PG8_MMA(0, 0, At, B0); PG8_MMA(0, 1, At, B1); PG8_BAR; PG8_SCHED;
;             PG8_LDA(At, 0, 1); PG8_STAGE(PG8_SB(0, 0), b2, voffB); PG8_STAGE(PG8_SB(0, 1), b2 + hsB, voffB); PG8_STAGE(PG8_SA(0, 0), a2, voffA);
;             if (Epi::NPRE != 0 && last) { PG8_WAIT_V(16); } else { PG8_WAIT_V(8); }
;             PG8_WAIT_L(0); PG8_BAR; PG8_MMA(1, 0, At, B0); PG8_MMA(1, 1, At, B1); PG8_BAR; PG8_SCHED;
.LBB0_1267:
	s_add_u32 s98, s34, 0xfff80000
	s_addc_u32 s99, s35, -1
	s_mov_b32 m0, s47
	s_nop 0
	global_load_lds_dwordx4 v152, s[98:99]
	s_mov_b32 m0, s48
	s_nop 0
	global_load_lds_dwordx4 v156, s[98:99]
	ds_read_b128 v[128:131], v189
	ds_read_b128 v[132:135], v189 offset:1024
	ds_read_b128 v[136:139], v189 offset:2048
	ds_read_b128 v[140:143], v189 offset:3072
	ds_read_b128 v[144:147], v190
	ds_read_b128 v[148:151], v190 offset:1024
	ds_read_b128 v[168:171], v190 offset:2048
	ds_read_b128 v[172:175], v190 offset:3072
	s_add_i32 s58, s36, 2
	s_add_u32 s37, s34, 0xfff80080
	s_addc_u32 s38, s35, -1
	s_cmp_eq_u32 s49, s36
	s_cselect_b32 s36, s55, s56
	s_cselect_b32 s39, s21, s38
	s_cselect_b32 s38, s23, s37
	s_cselect_b32 s37, s29, s57
	s_add_i32 m0, s31, 0xc000
	ds_read_b128 v[176:179], v191
	ds_read_b128 v[180:183], v191 offset:1024
	ds_read_b128 v[194:197], v191 offset:2048
	ds_read_b128 v[198:201], v191 offset:3072
	ds_read_b128 v[202:205], v191 offset:4096
	ds_read_b128 v[206:209], v191 offset:5120
	ds_read_b128 v[210:213], v191 offset:6144
	ds_read_b128 v[214:217], v191 offset:7168
	global_load_lds_dwordx4 v160, s[34:35]
	s_add_i32 m0, s31, 0xe000
	s_nop 0
	global_load_lds_dwordx4 v162, s[34:35]
	s_waitcnt vmcnt(8)
	s_waitcnt lgkmcnt(0)
	s_setprio 1
	s_barrier
	v_mfma_f32_16x16x32_bf16 v[124:127], v[128:131], v[176:179], v[124:127]
	v_mfma_f32_16x16x32_bf16 v[120:123], v[136:139], v[176:179], v[120:123]
	v_mfma_f32_16x16x32_bf16 v[108:111], v[128:131], v[194:197], v[108:111]
	v_mfma_f32_16x16x32_bf16 v[104:107], v[136:139], v[194:197], v[104:107]
	v_mfma_f32_16x16x32_bf16 v[92:95], v[128:131], v[202:205], v[92:95]
	v_mfma_f32_16x16x32_bf16 v[88:91], v[136:139], v[202:205], v[88:91]
	v_mfma_f32_16x16x32_bf16 v[76:79], v[128:131], v[210:213], v[76:79]
	v_mfma_f32_16x16x32_bf16 v[72:75], v[136:139], v[210:213], v[72:75]
	v_mfma_f32_16x16x32_bf16 v[124:127], v[132:135], v[180:183], v[124:127]
	v_mfma_f32_16x16x32_bf16 v[120:123], v[140:143], v[180:183], v[120:123]
	v_mfma_f32_16x16x32_bf16 v[108:111], v[132:135], v[198:201], v[108:111]
	v_mfma_f32_16x16x32_bf16 v[104:107], v[140:143], v[198:201], v[104:107]
	v_mfma_f32_16x16x32_bf16 v[92:95], v[132:135], v[206:209], v[92:95]
	v_mfma_f32_16x16x32_bf16 v[88:91], v[140:143], v[206:209], v[88:91]
	v_mfma_f32_16x16x32_bf16 v[76:79], v[132:135], v[214:217], v[76:79]
	v_mfma_f32_16x16x32_bf16 v[72:75], v[140:143], v[214:217], v[72:75]
	v_mfma_f32_16x16x32_bf16 v[116:119], v[144:147], v[176:179], v[116:119]
	v_mfma_f32_16x16x32_bf16 v[112:115], v[168:171], v[176:179], v[112:115]
	v_mfma_f32_16x16x32_bf16 v[100:103], v[144:147], v[194:197], v[100:103]
	v_mfma_f32_16x16x32_bf16 v[96:99], v[168:171], v[194:197], v[96:99]
	v_mfma_f32_16x16x32_bf16 v[84:87], v[144:147], v[202:205], v[84:87]
	v_mfma_f32_16x16x32_bf16 v[80:83], v[168:171], v[202:205], v[80:83]
	v_mfma_f32_16x16x32_bf16 v[68:71], v[144:147], v[210:213], v[68:71]
	v_mfma_f32_16x16x32_bf16 v[64:67], v[168:171], v[210:213], v[64:67]
	v_mfma_f32_16x16x32_bf16 v[116:119], v[148:151], v[180:183], v[116:119]
	v_mfma_f32_16x16x32_bf16 v[112:115], v[172:175], v[180:183], v[112:115]
	v_mfma_f32_16x16x32_bf16 v[100:103], v[148:151], v[198:201], v[100:103]
	v_mfma_f32_16x16x32_bf16 v[96:99], v[172:175], v[198:201], v[96:99]
	v_mfma_f32_16x16x32_bf16 v[84:87], v[148:151], v[206:209], v[84:87]
	v_mfma_f32_16x16x32_bf16 v[80:83], v[172:175], v[206:209], v[80:83]
	v_mfma_f32_16x16x32_bf16 v[68:71], v[148:151], v[214:217], v[68:71]
	v_mfma_f32_16x16x32_bf16 v[64:67], v[172:175], v[214:217], v[64:67]
	s_barrier
	s_setprio 0
	s_add_u32 s98, s36, s16
	s_addc_u32 s99, s37, s17
	s_add_u32 s100, s38, s16
	s_addc_u32 s101, s39, s17
	s_add_i32 s59, s53, s41
	s_mov_b32 m0, s59
	ds_read_b128 v[176:179], v191 offset:16384
	ds_read_b128 v[180:183], v191 offset:17408
	ds_read_b128 v[194:197], v191 offset:18432
	ds_read_b128 v[198:201], v191 offset:19456
	ds_read_b128 v[202:205], v191 offset:20480
	ds_read_b128 v[206:209], v191 offset:21504
	ds_read_b128 v[210:213], v191 offset:22528
	ds_read_b128 v[214:217], v191 offset:23552
	global_load_lds_dwordx4 v154, s[36:37]
	s_add_i32 m0, s59, 0x2000
	s_add_u32 s60, s36, 0x80000
	s_addc_u32 s61, s37, 0
	s_add_i32 s59, s54, s41
	global_load_lds_dwordx4 v158, s[36:37]
	s_mov_b32 m0, s59
	s_nop 0
	global_load_lds_dwordx4 v154, s[60:61]
	s_add_i32 m0, s59, 0x2000
	s_nop 0
	global_load_lds_dwordx4 v158, s[60:61]
	s_waitcnt vmcnt(6)
	s_waitcnt lgkmcnt(0)
	s_setprio 1
	s_barrier
	v_mfma_f32_16x16x32_bf16 v[60:63], v[128:131], v[176:179], v[60:63]
	v_mfma_f32_16x16x32_bf16 v[56:59], v[136:139], v[176:179], v[56:59]
	v_mfma_f32_16x16x32_bf16 v[44:47], v[128:131], v[194:197], v[44:47]
	v_mfma_f32_16x16x32_bf16 v[40:43], v[136:139], v[194:197], v[40:43]
	v_mfma_f32_16x16x32_bf16 v[28:31], v[128:131], v[202:205], v[28:31]
	v_mfma_f32_16x16x32_bf16 v[24:27], v[136:139], v[202:205], v[24:27]
	v_mfma_f32_16x16x32_bf16 v[12:15], v[128:131], v[210:213], v[12:15]
	v_mfma_f32_16x16x32_bf16 v[8:11], v[136:139], v[210:213], v[8:11]
	v_mfma_f32_16x16x32_bf16 v[60:63], v[132:135], v[180:183], v[60:63]
	v_mfma_f32_16x16x32_bf16 v[56:59], v[140:143], v[180:183], v[56:59]
	v_mfma_f32_16x16x32_bf16 v[44:47], v[132:135], v[198:201], v[44:47]
	v_mfma_f32_16x16x32_bf16 v[40:43], v[140:143], v[198:201], v[40:43]
	v_mfma_f32_16x16x32_bf16 v[28:31], v[132:135], v[206:209], v[28:31]
	v_mfma_f32_16x16x32_bf16 v[24:27], v[140:143], v[206:209], v[24:27]
	v_mfma_f32_16x16x32_bf16 v[12:15], v[132:135], v[214:217], v[12:15]
	v_mfma_f32_16x16x32_bf16 v[8:11], v[140:143], v[214:217], v[8:11]
	v_mfma_f32_16x16x32_bf16 v[52:55], v[144:147], v[176:179], v[52:55]
	v_mfma_f32_16x16x32_bf16 v[48:51], v[168:171], v[176:179], v[48:51]
	v_mfma_f32_16x16x32_bf16 v[36:39], v[144:147], v[194:197], v[36:39]
	v_mfma_f32_16x16x32_bf16 v[32:35], v[168:171], v[194:197], v[32:35]
	v_mfma_f32_16x16x32_bf16 v[20:23], v[144:147], v[202:205], v[20:23]
	v_mfma_f32_16x16x32_bf16 v[16:19], v[168:171], v[202:205], v[16:19]
	v_mfma_f32_16x16x32_bf16 v[4:7], v[144:147], v[210:213], v[4:7]
	v_mfma_f32_16x16x32_bf16 v[0:3], v[168:171], v[210:213], v[0:3]
	v_mfma_f32_16x16x32_bf16 v[52:55], v[148:151], v[180:183], v[52:55]
	v_mfma_f32_16x16x32_bf16 v[48:51], v[172:175], v[180:183], v[48:51]
	v_mfma_f32_16x16x32_bf16 v[36:39], v[148:151], v[198:201], v[36:39]
	v_mfma_f32_16x16x32_bf16 v[32:35], v[172:175], v[198:201], v[32:35]
	v_mfma_f32_16x16x32_bf16 v[20:23], v[148:151], v[206:209], v[20:23]
	v_mfma_f32_16x16x32_bf16 v[16:19], v[172:175], v[206:209], v[16:19]
	v_mfma_f32_16x16x32_bf16 v[4:7], v[148:151], v[214:217], v[4:7]
	v_mfma_f32_16x16x32_bf16 v[0:3], v[172:175], v[214:217], v[0:3]
	s_barrier
; #define PG8_STAGE(bufoff, gbase, voff) do { _Pragma("unroll") for (int _i = 0; _i < 2; ++_i) \
;         __builtin_amdgcn_global_load_lds((const unsigned*)((const char*)(gbase) + (voff)[_i]), (LAS unsigned*)(lds + (bufoff) + ldsw + _i * 8192), 16, 0, ((voff) == voffA ? AUXA : 0)); } while (0)
; #define PG8_LDA(dst, b, h) do { _Pragma("unroll") for (int m = 0; m < 4; ++m) _Pragma("unroll") for (int k = 0; k < 2; ++k) dst[m][k] = *(const LAS bf16x8*)(lds + PG8_SA(b, h) + aoff + m * 2048 + k * 1024); } while (0)
; #define PG8_LDB(dst, b, h) do { _Pragma("unroll") for (int n = 0; n < 2; ++n) _Pragma("unroll") for (int k = 0; k < 2; ++k) dst[n][k] = *(const LAS bf16x8*)(lds + PG8_SB(b, h) + boff + n * 2048 + k * 1024); } while (0)
; #define PG8_MMA(ai, bj, At, Bt) do { __builtin_amdgcn_s_setprio(1); _Pragma("unroll") for (int m = 0; m < 4; ++m) _Pragma("unroll") for (int n = 0; n < 2; ++n) _Pragma("unroll") for (int k = 0; k < 2; ++k) \
;         acc[ai][bj][m][n] = __builtin_amdgcn_mfma_f32_16x16x32_bf16(Bt[n][k], At[m][k], acc[ai][bj][m][n], 0, 0, 0); __builtin_amdgcn_s_setprio(0); } while (0)
; #define PG8_WAIT_V(n) asm volatile("s_waitcnt vmcnt(" #n ")" ::: "memory")
; #define PG8_WAIT_L(n) asm volatile("s_waitcnt lgkmcnt(" #n ")" ::: "memory")
; #define PG8_BAR __builtin_amdgcn_s_barrier()
; #define PG8_SCHED __builtin_amdgcn_sched_barrier(0)
;     ...
;             PG8_WAIT_L(0); PG8_BAR; PG8_MMA(1, 0, At, B0); PG8_MMA(1, 1, At, B1); PG8_BAR; PG8_SCHED;
;             PG8_LDB(B0, 1, 0); PG8_LDB(B1, 1, 1); PG8_SCHED; PG8_LDA(At, 1, 0); PG8_STAGE(PG8_SA(0, 1), a2 + hsA, voffA);
;             PG8_WAIT_V(8); PG8_WAIT_L(0); PG8_BAR; PG8_MMA(0, 0, At, B0); PG8_MMA(0, 1, At, B1); PG8_BAR; PG8_SCHED;
;             PG8_LDA(At, 1, 1); PG8_STAGE(PG8_SB(1, 0), b3, voffB); PG8_STAGE(PG8_SB(1, 1), b3 + hsB, voffB); PG8_STAGE(PG8_SA(1, 0), a3, voffA);
;             PG8_WAIT_V(8); PG8_WAIT_L(0); PG8_BAR; PG8_MMA(1, 0, At, B0); PG8_MMA(1, 1, At, B1); PG8_BAR; PG8_SCHED;
;         }
	s_mov_b32 m0, s31
	s_nop 0
	global_load_lds_dwordx4 v152, s[38:39]
	s_mov_b32 m0, s42
	s_nop 0
	global_load_lds_dwordx4 v156, s[38:39]
	s_setprio 0
	s_add_i32 s59, 0, 0x18000
	s_add_i32 s60, 0, 0x1c000
	v_add_u32_e32 v140, s59, v187
	v_add_u32_e32 v172, s60, v187
	ds_read_b128 v[128:131], v140
	ds_read_b128 v[132:135], v140 offset:1024
	ds_read_b128 v[136:139], v140 offset:2048
	ds_read_b128 v[140:143], v140 offset:3072
	ds_read_b128 v[144:147], v172
	ds_read_b128 v[148:151], v172 offset:1024
	ds_read_b128 v[168:171], v172 offset:2048
	ds_read_b128 v[172:175], v172 offset:3072
	s_add_u32 s38, s38, 0x80000
	s_addc_u32 s39, s39, 0
	s_mov_b32 m0, s43
	ds_read_b128 v[176:179], v191 offset:32768
	ds_read_b128 v[180:183], v191 offset:33792
	ds_read_b128 v[194:197], v191 offset:34816
	ds_read_b128 v[198:201], v191 offset:35840
	ds_read_b128 v[202:205], v191 offset:36864
	ds_read_b128 v[206:209], v191 offset:37888
	ds_read_b128 v[210:213], v191 offset:38912
	ds_read_b128 v[214:217], v191 offset:39936
	global_load_lds_dwordx4 v152, s[38:39]
	s_mov_b32 m0, s44
	s_nop 0
	global_load_lds_dwordx4 v156, s[38:39]
	s_waitcnt vmcnt(8)
	s_waitcnt lgkmcnt(0)
	s_setprio 1
	s_barrier
	v_mfma_f32_16x16x32_bf16 v[124:127], v[128:131], v[176:179], v[124:127]
	v_mfma_f32_16x16x32_bf16 v[120:123], v[136:139], v[176:179], v[120:123]
	v_mfma_f32_16x16x32_bf16 v[108:111], v[128:131], v[194:197], v[108:111]
	v_mfma_f32_16x16x32_bf16 v[104:107], v[136:139], v[194:197], v[104:107]
	v_mfma_f32_16x16x32_bf16 v[92:95], v[128:131], v[202:205], v[92:95]
	v_mfma_f32_16x16x32_bf16 v[88:91], v[136:139], v[202:205], v[88:91]
	v_mfma_f32_16x16x32_bf16 v[76:79], v[128:131], v[210:213], v[76:79]
	v_mfma_f32_16x16x32_bf16 v[72:75], v[136:139], v[210:213], v[72:75]
	v_mfma_f32_16x16x32_bf16 v[124:127], v[132:135], v[180:183], v[124:127]
	v_mfma_f32_16x16x32_bf16 v[120:123], v[140:143], v[180:183], v[120:123]
	v_mfma_f32_16x16x32_bf16 v[108:111], v[132:135], v[198:201], v[108:111]
	v_mfma_f32_16x16x32_bf16 v[104:107], v[140:143], v[198:201], v[104:107]
	v_mfma_f32_16x16x32_bf16 v[92:95], v[132:135], v[206:209], v[92:95]
	v_mfma_f32_16x16x32_bf16 v[88:91], v[140:143], v[206:209], v[88:91]
	v_mfma_f32_16x16x32_bf16 v[76:79], v[132:135], v[214:217], v[76:79]
	v_mfma_f32_16x16x32_bf16 v[72:75], v[140:143], v[214:217], v[72:75]
	v_mfma_f32_16x16x32_bf16 v[116:119], v[144:147], v[176:179], v[116:119]
	v_mfma_f32_16x16x32_bf16 v[112:115], v[168:171], v[176:179], v[112:115]
	v_mfma_f32_16x16x32_bf16 v[100:103], v[144:147], v[194:197], v[100:103]
	v_mfma_f32_16x16x32_bf16 v[96:99], v[168:171], v[194:197], v[96:99]
	v_mfma_f32_16x16x32_bf16 v[84:87], v[144:147], v[202:205], v[84:87]
	v_mfma_f32_16x16x32_bf16 v[80:83], v[168:171], v[202:205], v[80:83]
	v_mfma_f32_16x16x32_bf16 v[68:71], v[144:147], v[210:213], v[68:71]
	v_mfma_f32_16x16x32_bf16 v[64:67], v[168:171], v[210:213], v[64:67]
	v_mfma_f32_16x16x32_bf16 v[116:119], v[148:151], v[180:183], v[116:119]
	v_mfma_f32_16x16x32_bf16 v[112:115], v[172:175], v[180:183], v[112:115]
	v_mfma_f32_16x16x32_bf16 v[100:103], v[148:151], v[198:201], v[100:103]
	v_mfma_f32_16x16x32_bf16 v[96:99], v[172:175], v[198:201], v[96:99]
	v_mfma_f32_16x16x32_bf16 v[84:87], v[148:151], v[206:209], v[84:87]
	v_mfma_f32_16x16x32_bf16 v[80:83], v[172:175], v[206:209], v[80:83]
	v_mfma_f32_16x16x32_bf16 v[68:71], v[148:151], v[214:217], v[68:71]
	v_mfma_f32_16x16x32_bf16 v[64:67], v[172:175], v[214:217], v[64:67]
	s_barrier
	s_setprio 0
	s_add_i32 s38, s59, s41
	s_mov_b32 m0, s38
	ds_read_b128 v[176:179], v191 offset:49152
	ds_read_b128 v[180:183], v191 offset:50176
	ds_read_b128 v[194:197], v191 offset:51200
	ds_read_b128 v[198:201], v191 offset:52224
	ds_read_b128 v[202:205], v191 offset:53248
	ds_read_b128 v[206:209], v191 offset:54272
	ds_read_b128 v[210:213], v191 offset:55296
	ds_read_b128 v[214:217], v191 offset:56320
	global_load_lds_dwordx4 v154, s[98:99]
	s_add_i32 m0, s38, 0x2000
	s_add_u32 s36, s36, 0x80080
	s_addc_u32 s37, s37, 0
	s_add_i32 s38, s60, s41
	global_load_lds_dwordx4 v158, s[98:99]
	s_mov_b32 m0, s38
	s_nop 0
	global_load_lds_dwordx4 v154, s[36:37]
	s_add_i32 m0, s38, 0x2000
	s_nop 0
	global_load_lds_dwordx4 v158, s[36:37]
	s_waitcnt vmcnt(6)
	s_waitcnt lgkmcnt(0)
	s_setprio 1
	s_barrier
	v_mfma_f32_16x16x32_bf16 v[60:63], v[128:131], v[176:179], v[60:63]
	v_mfma_f32_16x16x32_bf16 v[56:59], v[136:139], v[176:179], v[56:59]
	v_mfma_f32_16x16x32_bf16 v[44:47], v[128:131], v[194:197], v[44:47]
	v_mfma_f32_16x16x32_bf16 v[40:43], v[136:139], v[194:197], v[40:43]
	v_mfma_f32_16x16x32_bf16 v[28:31], v[128:131], v[202:205], v[28:31]
	v_mfma_f32_16x16x32_bf16 v[24:27], v[136:139], v[202:205], v[24:27]
	v_mfma_f32_16x16x32_bf16 v[12:15], v[128:131], v[210:213], v[12:15]
	v_mfma_f32_16x16x32_bf16 v[8:11], v[136:139], v[210:213], v[8:11]
	v_mfma_f32_16x16x32_bf16 v[60:63], v[132:135], v[180:183], v[60:63]
	v_mfma_f32_16x16x32_bf16 v[56:59], v[140:143], v[180:183], v[56:59]
	v_mfma_f32_16x16x32_bf16 v[44:47], v[132:135], v[198:201], v[44:47]
	v_mfma_f32_16x16x32_bf16 v[40:43], v[140:143], v[198:201], v[40:43]
	v_mfma_f32_16x16x32_bf16 v[28:31], v[132:135], v[206:209], v[28:31]
	v_mfma_f32_16x16x32_bf16 v[24:27], v[140:143], v[206:209], v[24:27]
	v_mfma_f32_16x16x32_bf16 v[12:15], v[132:135], v[214:217], v[12:15]
	v_mfma_f32_16x16x32_bf16 v[8:11], v[140:143], v[214:217], v[8:11]
	v_mfma_f32_16x16x32_bf16 v[52:55], v[144:147], v[176:179], v[52:55]
	v_mfma_f32_16x16x32_bf16 v[48:51], v[168:171], v[176:179], v[48:51]
	v_mfma_f32_16x16x32_bf16 v[36:39], v[144:147], v[194:197], v[36:39]
	v_mfma_f32_16x16x32_bf16 v[32:35], v[168:171], v[194:197], v[32:35]
	v_mfma_f32_16x16x32_bf16 v[20:23], v[144:147], v[202:205], v[20:23]
	v_mfma_f32_16x16x32_bf16 v[16:19], v[168:171], v[202:205], v[16:19]
	v_mfma_f32_16x16x32_bf16 v[4:7], v[144:147], v[210:213], v[4:7]
	v_mfma_f32_16x16x32_bf16 v[0:3], v[168:171], v[210:213], v[0:3]
	v_mfma_f32_16x16x32_bf16 v[52:55], v[148:151], v[180:183], v[52:55]
	v_mfma_f32_16x16x32_bf16 v[48:51], v[172:175], v[180:183], v[48:51]
	v_mfma_f32_16x16x32_bf16 v[36:39], v[148:151], v[198:201], v[36:39]
	v_mfma_f32_16x16x32_bf16 v[32:35], v[172:175], v[198:201], v[32:35]
	v_mfma_f32_16x16x32_bf16 v[20:23], v[148:151], v[206:209], v[20:23]
	v_mfma_f32_16x16x32_bf16 v[16:19], v[172:175], v[206:209], v[16:19]
	v_mfma_f32_16x16x32_bf16 v[4:7], v[148:151], v[214:217], v[4:7]
	v_mfma_f32_16x16x32_bf16 v[0:3], v[172:175], v[214:217], v[0:3]
	s_barrier
	s_setprio 0
	s_add_u32 s34, s34, 0x100
	s_addc_u32 s35, s35, 0
	s_add_u32 s56, s56, 0x100
	s_addc_u32 s57, s57, 0
	s_cmp_ge_i32 s58, s46
	s_mov_b32 s36, s58
	s_cbranch_scc0 .LBB0_1267

; #define PG8_STAGE(bufoff, gbase, voff) do { _Pragma("unroll") for (int _i = 0; _i < 2; ++_i) \
;         __builtin_amdgcn_global_load_lds((const unsigned*)((const char*)(gbase) + (voff)[_i]), (LAS unsigned*)(lds + (bufoff) + ldsw + _i * 8192), 16, 0, ((voff) == voffA ? AUXA : 0)); } while (0)
; #define PG8_LDA(dst, b, h) do { _Pragma("unroll") for (int m = 0; m < 4; ++m) _Pragma("unroll") for (int k = 0; k < 2; ++k) dst[m][k] = *(const LAS bf16x8*)(lds + PG8_SA(b, h) + aoff + m * 2048 + k * 1024); } while (0)
; #define PG8_LDB(dst, b, h) do { _Pragma("unroll") for (int n = 0; n < 2; ++n) _Pragma("unroll") for (int k = 0; k < 2; ++k) dst[n][k] = *(const LAS bf16x8*)(lds + PG8_SB(b, h) + boff + n * 2048 + k * 1024); } while (0)
; #define PG8_MMA(ai, bj, At, Bt) do { __builtin_amdgcn_s_setprio(1); _Pragma("unroll") for (int m = 0; m < 4; ++m) _Pragma("unroll") for (int n = 0; n < 2; ++n) _Pragma("unroll") for (int k = 0; k < 2; ++k) \
;         acc[ai][bj][m][n] = __builtin_amdgcn_mfma_f32_16x16x32_bf16(Bt[n][k], At[m][k], acc[ai][bj][m][n], 0, 0, 0); __builtin_amdgcn_s_setprio(0); } while (0)
; #define PG8_WAIT_V(n) asm volatile("s_waitcnt vmcnt(" #n ")" ::: "memory")
; #define PG8_WAIT_L(n) asm volatile("s_waitcnt lgkmcnt(" #n ")" ::: "memory")
; #define PG8_BAR __builtin_amdgcn_s_barrier()
; #define PG8_SCHED __builtin_amdgcn_sched_barrier(0)
;     ...
;             PG8_LDA(At, 0, 1); PG8_STAGE(PG8_SB(0, 0), b2, voffB); PG8_STAGE(PG8_SB(0, 1), b2 + hsB, voffB); PG8_STAGE(PG8_SA(0, 0), a2, voffA);
;             if (Epi::NPRE != 0 && last) { PG8_WAIT_V(16); } else { PG8_WAIT_V(8); }
;             PG8_WAIT_L(0); PG8_BAR; PG8_MMA(1, 0, At, B0); PG8_MMA(1, 1, At, B1); PG8_BAR; PG8_SCHED;
;             PG8_LDB(B0, 1, 0); PG8_LDB(B1, 1, 1); PG8_SCHED; PG8_LDA(At, 1, 0); PG8_STAGE(PG8_SA(0, 1), a2 + hsA, voffA);
;             PG8_WAIT_V(8); PG8_WAIT_L(0); PG8_BAR; PG8_MMA(0, 0, At, B0); PG8_MMA(0, 1, At, B1); PG8_BAR; PG8_SCHED;
.LBB0_1355:
	s_waitcnt lgkmcnt(0)
	s_add_i32 s61, s61, 2
	s_setprio 1
	s_barrier
	v_mfma_f32_16x16x32_bf16 v[60:63], v[144:147], v[184:187], v[60:63]
	v_mfma_f32_16x16x32_bf16 v[52:55], v[152:155], v[184:187], v[52:55]
	v_mfma_f32_16x16x32_bf16 v[44:47], v[144:147], v[176:179], v[44:47]
	v_mfma_f32_16x16x32_bf16 v[36:39], v[152:155], v[176:179], v[36:39]
	v_mfma_f32_16x16x32_bf16 v[28:31], v[144:147], v[168:171], v[28:31]
	v_mfma_f32_16x16x32_bf16 v[20:23], v[152:155], v[168:171], v[20:23]
	v_mfma_f32_16x16x32_bf16 v[12:15], v[144:147], v[160:163], v[12:15]
	v_mfma_f32_16x16x32_bf16 v[4:7], v[152:155], v[160:163], v[4:7]
	v_mfma_f32_16x16x32_bf16 v[60:63], v[148:151], v[188:191], v[60:63]
	v_mfma_f32_16x16x32_bf16 v[52:55], v[156:159], v[188:191], v[52:55]
	v_mfma_f32_16x16x32_bf16 v[44:47], v[148:151], v[180:183], v[44:47]
	v_mfma_f32_16x16x32_bf16 v[36:39], v[156:159], v[180:183], v[36:39]
	v_mfma_f32_16x16x32_bf16 v[28:31], v[148:151], v[172:175], v[28:31]
	v_mfma_f32_16x16x32_bf16 v[20:23], v[156:159], v[172:175], v[20:23]
	v_mfma_f32_16x16x32_bf16 v[12:15], v[148:151], v[164:167], v[12:15]
	v_mfma_f32_16x16x32_bf16 v[4:7], v[156:159], v[164:167], v[4:7]
	v_mfma_f32_16x16x32_bf16 v[56:59], v[128:131], v[184:187], v[56:59]
	v_mfma_f32_16x16x32_bf16 v[48:51], v[136:139], v[184:187], v[48:51]
	v_mfma_f32_16x16x32_bf16 v[40:43], v[128:131], v[176:179], v[40:43]
	v_mfma_f32_16x16x32_bf16 v[32:35], v[136:139], v[176:179], v[32:35]
	v_mfma_f32_16x16x32_bf16 v[24:27], v[128:131], v[168:171], v[24:27]
	v_mfma_f32_16x16x32_bf16 v[16:19], v[136:139], v[168:171], v[16:19]
	v_mfma_f32_16x16x32_bf16 v[8:11], v[128:131], v[160:163], v[8:11]
	v_mfma_f32_16x16x32_bf16 v[0:3], v[136:139], v[160:163], v[0:3]
	v_mfma_f32_16x16x32_bf16 v[56:59], v[132:135], v[188:191], v[56:59]
	v_mfma_f32_16x16x32_bf16 v[48:51], v[140:143], v[188:191], v[48:51]
	v_mfma_f32_16x16x32_bf16 v[40:43], v[132:135], v[180:183], v[40:43]
	v_mfma_f32_16x16x32_bf16 v[32:35], v[140:143], v[180:183], v[32:35]
	v_mfma_f32_16x16x32_bf16 v[24:27], v[132:135], v[172:175], v[24:27]
	v_mfma_f32_16x16x32_bf16 v[16:19], v[140:143], v[172:175], v[16:19]
	v_mfma_f32_16x16x32_bf16 v[8:11], v[132:135], v[164:167], v[8:11]
	v_mfma_f32_16x16x32_bf16 v[0:3], v[140:143], v[164:167], v[0:3]
	s_barrier
	s_mov_b32 m0, s40
	s_nop 0
	global_load_lds_dwordx4 v198, s[30:31]
	s_mov_b32 m0, s45
	s_nop 0
	global_load_lds_dwordx4 v194, s[30:31]
	s_setprio 0
	s_add_i32 s34, 0, 0x18000
	s_add_i32 s35, 0, 0x1c000
	v_add_u32_e32 v140, s34, v221
	v_add_u32_e32 v156, s35, v221
	ds_read_b128 v[128:131], v140
	ds_read_b128 v[132:135], v140 offset:1024
	ds_read_b128 v[136:139], v140 offset:2048
	ds_read_b128 v[140:143], v140 offset:3072
	ds_read_b128 v[144:147], v156
	ds_read_b128 v[148:151], v156 offset:1024
	ds_read_b128 v[152:155], v156 offset:2048
	ds_read_b128 v[156:159], v156 offset:3072
	s_add_u32 s30, s30, 0x80000
	s_addc_u32 s31, s31, 0
	s_mov_b32 m0, s46
	ds_read_b128 v[160:163], v225 offset:32768
	ds_read_b128 v[164:167], v225 offset:33792
	ds_read_b128 v[168:171], v225 offset:34816
	ds_read_b128 v[172:175], v225 offset:35840
	ds_read_b128 v[176:179], v225 offset:36864
	ds_read_b128 v[180:183], v225 offset:37888
	ds_read_b128 v[184:187], v225 offset:38912
	ds_read_b128 v[188:191], v225 offset:39936
	global_load_lds_dwordx4 v198, s[30:31]
	s_mov_b32 m0, s47
	s_nop 0
	global_load_lds_dwordx4 v194, s[30:31]
	s_waitcnt vmcnt(8)
	s_waitcnt lgkmcnt(0)
	s_setprio 1
	s_barrier
	v_mfma_f32_16x16x32_bf16 v[124:127], v[128:131], v[160:163], v[124:127]
	v_mfma_f32_16x16x32_bf16 v[116:119], v[136:139], v[160:163], v[116:119]
	v_mfma_f32_16x16x32_bf16 v[108:111], v[128:131], v[168:171], v[108:111]
	v_mfma_f32_16x16x32_bf16 v[100:103], v[136:139], v[168:171], v[100:103]
	v_mfma_f32_16x16x32_bf16 v[92:95], v[128:131], v[176:179], v[92:95]
	v_mfma_f32_16x16x32_bf16 v[84:87], v[136:139], v[176:179], v[84:87]
	v_mfma_f32_16x16x32_bf16 v[76:79], v[128:131], v[184:187], v[76:79]
	v_mfma_f32_16x16x32_bf16 v[68:71], v[136:139], v[184:187], v[68:71]
	v_mfma_f32_16x16x32_bf16 v[124:127], v[132:135], v[164:167], v[124:127]
	v_mfma_f32_16x16x32_bf16 v[116:119], v[140:143], v[164:167], v[116:119]
	v_mfma_f32_16x16x32_bf16 v[108:111], v[132:135], v[172:175], v[108:111]
	v_mfma_f32_16x16x32_bf16 v[100:103], v[140:143], v[172:175], v[100:103]
	v_mfma_f32_16x16x32_bf16 v[92:95], v[132:135], v[180:183], v[92:95]
	v_mfma_f32_16x16x32_bf16 v[84:87], v[140:143], v[180:183], v[84:87]
	v_mfma_f32_16x16x32_bf16 v[76:79], v[132:135], v[188:191], v[76:79]
	v_mfma_f32_16x16x32_bf16 v[68:71], v[140:143], v[188:191], v[68:71]
	v_mfma_f32_16x16x32_bf16 v[120:123], v[144:147], v[160:163], v[120:123]
	v_mfma_f32_16x16x32_bf16 v[112:115], v[152:155], v[160:163], v[112:115]
	v_mfma_f32_16x16x32_bf16 v[104:107], v[144:147], v[168:171], v[104:107]
	v_mfma_f32_16x16x32_bf16 v[96:99], v[152:155], v[168:171], v[96:99]
	v_mfma_f32_16x16x32_bf16 v[88:91], v[144:147], v[176:179], v[88:91]
	v_mfma_f32_16x16x32_bf16 v[80:83], v[152:155], v[176:179], v[80:83]
	v_mfma_f32_16x16x32_bf16 v[72:75], v[144:147], v[184:187], v[72:75]
	v_mfma_f32_16x16x32_bf16 v[64:67], v[152:155], v[184:187], v[64:67]
	v_mfma_f32_16x16x32_bf16 v[120:123], v[148:151], v[164:167], v[120:123]
	v_mfma_f32_16x16x32_bf16 v[112:115], v[156:159], v[164:167], v[112:115]
	v_mfma_f32_16x16x32_bf16 v[104:107], v[148:151], v[172:175], v[104:107]
	v_mfma_f32_16x16x32_bf16 v[96:99], v[156:159], v[172:175], v[96:99]
	v_mfma_f32_16x16x32_bf16 v[88:91], v[148:151], v[180:183], v[88:91]
	v_mfma_f32_16x16x32_bf16 v[80:83], v[156:159], v[180:183], v[80:83]
	v_mfma_f32_16x16x32_bf16 v[72:75], v[148:151], v[188:191], v[72:75]
	v_mfma_f32_16x16x32_bf16 v[64:67], v[156:159], v[188:191], v[64:67]
	s_barrier
; #define PG8_STAGE(bufoff, gbase, voff) do { _Pragma("unroll") for (int _i = 0; _i < 2; ++_i) \
;         __builtin_amdgcn_global_load_lds((const unsigned*)((const char*)(gbase) + (voff)[_i]), (LAS unsigned*)(lds + (bufoff) + ldsw + _i * 8192), 16, 0, ((voff) == voffA ? AUXA : 0)); } while (0)
; #define PG8_LDA(dst, b, h) do { _Pragma("unroll") for (int m = 0; m < 4; ++m) _Pragma("unroll") for (int k = 0; k < 2; ++k) dst[m][k] = *(const LAS bf16x8*)(lds + PG8_SA(b, h) + aoff + m * 2048 + k * 1024); } while (0)
; #define PG8_LDB(dst, b, h) do { _Pragma("unroll") for (int n = 0; n < 2; ++n) _Pragma("unroll") for (int k = 0; k < 2; ++k) dst[n][k] = *(const LAS bf16x8*)(lds + PG8_SB(b, h) + boff + n * 2048 + k * 1024); } while (0)
; #define PG8_MMA(ai, bj, At, Bt) do { __builtin_amdgcn_s_setprio(1); _Pragma("unroll") for (int m = 0; m < 4; ++m) _Pragma("unroll") for (int n = 0; n < 2; ++n) _Pragma("unroll") for (int k = 0; k < 2; ++k) \
;         acc[ai][bj][m][n] = __builtin_amdgcn_mfma_f32_16x16x32_bf16(Bt[n][k], At[m][k], acc[ai][bj][m][n], 0, 0, 0); __builtin_amdgcn_s_setprio(0); } while (0)
; #define PG8_WAIT_V(n) asm volatile("s_waitcnt vmcnt(" #n ")" ::: "memory")
;     ...
;             PG8_LDB(B0, 0, 0); PG8_LDB(B1, 0, 1); PG8_SCHED; PG8_LDA(At, 0, 0); PG8_STAGE(PG8_SA(1, 1), a1 + hsA, voffA);
;             if (Epi::NPRE != 0 && last) { E.pre(sv, cur, wr, fr); PG8_WAIT_V(16); } else { PG8_WAIT_V(8); }
;             PG8_WAIT_L(0); PG8_BAR; PG8_MMA(0, 0, At, B0); PG8_MMA(0, 1, At, B1); PG8_BAR; PG8_SCHED;
;             PG8_LDA(At, 0, 1); PG8_STAGE(PG8_SB(0, 0), b2, voffB); PG8_STAGE(PG8_SB(0, 1), b2 + hsB, voffB); PG8_STAGE(PG8_SA(0, 0), a2, voffA);
;             if (Epi::NPRE != 0 && last) { PG8_WAIT_V(16); } else { PG8_WAIT_V(8); }
;             PG8_WAIT_L(0); PG8_BAR; PG8_MMA(1, 0, At, B0); PG8_MMA(1, 1, At, B1); PG8_BAR; PG8_SCHED;
;             PG8_LDB(B0, 1, 0); PG8_LDB(B1, 1, 1); PG8_SCHED; PG8_LDA(At, 1, 0); PG8_STAGE(PG8_SA(0, 1), a2 + hsA, voffA);
;             PG8_WAIT_V(8); PG8_WAIT_L(0); PG8_BAR; PG8_MMA(0, 0, At, B0); PG8_MMA(0, 1, At, B1); PG8_BAR; PG8_SCHED;
;             PG8_LDA(At, 1, 1); PG8_STAGE(PG8_SB(1, 0), b3, voffB); PG8_STAGE(PG8_SB(1, 1), b3 + hsB, voffB); PG8_STAGE(PG8_SA(1, 0), a3, voffA);
;             PG8_WAIT_V(8); PG8_WAIT_L(0); PG8_BAR; PG8_MMA(1, 0, At, B0); PG8_MMA(1, 1, At, B1); PG8_BAR; PG8_SCHED;
	s_setprio 0
	s_add_i32 s30, s34, s5
	s_mov_b32 m0, s30
	ds_read_b128 v[160:163], v225 offset:49152
	ds_read_b128 v[164:167], v225 offset:50176
	ds_read_b128 v[168:171], v225 offset:51200
	ds_read_b128 v[172:175], v225 offset:52224
	ds_read_b128 v[176:179], v225 offset:53248
	ds_read_b128 v[180:183], v225 offset:54272
	ds_read_b128 v[184:187], v225 offset:55296
	ds_read_b128 v[188:191], v225 offset:56320
	global_load_lds_dwordx4 v196, s[98:99]
	s_add_i32 m0, s30, 0x2000
	s_add_u32 s28, s28, 0x80080
	s_addc_u32 s29, s29, 0
	s_add_i32 s30, s35, s5
	global_load_lds_dwordx4 v192, s[98:99]
	s_mov_b32 m0, s30
	s_nop 0
	global_load_lds_dwordx4 v196, s[28:29]
	s_add_i32 m0, s30, 0x2000
	s_nop 0
	global_load_lds_dwordx4 v192, s[28:29]
	s_waitcnt vmcnt(6)
	s_waitcnt lgkmcnt(0)
	s_setprio 1
	s_barrier
	v_mfma_f32_16x16x32_bf16 v[60:63], v[128:131], v[160:163], v[60:63]
	v_mfma_f32_16x16x32_bf16 v[52:55], v[136:139], v[160:163], v[52:55]
	v_mfma_f32_16x16x32_bf16 v[44:47], v[128:131], v[168:171], v[44:47]
	v_mfma_f32_16x16x32_bf16 v[36:39], v[136:139], v[168:171], v[36:39]
	v_mfma_f32_16x16x32_bf16 v[28:31], v[128:131], v[176:179], v[28:31]
	v_mfma_f32_16x16x32_bf16 v[20:23], v[136:139], v[176:179], v[20:23]
	v_mfma_f32_16x16x32_bf16 v[12:15], v[128:131], v[184:187], v[12:15]
	v_mfma_f32_16x16x32_bf16 v[4:7], v[136:139], v[184:187], v[4:7]
	v_mfma_f32_16x16x32_bf16 v[60:63], v[132:135], v[164:167], v[60:63]
	v_mfma_f32_16x16x32_bf16 v[52:55], v[140:143], v[164:167], v[52:55]
	v_mfma_f32_16x16x32_bf16 v[44:47], v[132:135], v[172:175], v[44:47]
	v_mfma_f32_16x16x32_bf16 v[36:39], v[140:143], v[172:175], v[36:39]
	v_mfma_f32_16x16x32_bf16 v[28:31], v[132:135], v[180:183], v[28:31]
	v_mfma_f32_16x16x32_bf16 v[20:23], v[140:143], v[180:183], v[20:23]
	v_mfma_f32_16x16x32_bf16 v[12:15], v[132:135], v[188:191], v[12:15]
	v_mfma_f32_16x16x32_bf16 v[4:7], v[140:143], v[188:191], v[4:7]
	v_mfma_f32_16x16x32_bf16 v[56:59], v[144:147], v[160:163], v[56:59]
	v_mfma_f32_16x16x32_bf16 v[48:51], v[152:155], v[160:163], v[48:51]
	v_mfma_f32_16x16x32_bf16 v[40:43], v[144:147], v[168:171], v[40:43]
	v_mfma_f32_16x16x32_bf16 v[32:35], v[152:155], v[168:171], v[32:35]
	v_mfma_f32_16x16x32_bf16 v[24:27], v[144:147], v[176:179], v[24:27]
	v_mfma_f32_16x16x32_bf16 v[16:19], v[152:155], v[176:179], v[16:19]
	v_mfma_f32_16x16x32_bf16 v[8:11], v[144:147], v[184:187], v[8:11]
	v_mfma_f32_16x16x32_bf16 v[0:3], v[152:155], v[184:187], v[0:3]
	v_mfma_f32_16x16x32_bf16 v[56:59], v[148:151], v[164:167], v[56:59]
	v_mfma_f32_16x16x32_bf16 v[48:51], v[156:159], v[164:167], v[48:51]
	v_mfma_f32_16x16x32_bf16 v[40:43], v[148:151], v[172:175], v[40:43]
	v_mfma_f32_16x16x32_bf16 v[32:35], v[156:159], v[172:175], v[32:35]
	v_mfma_f32_16x16x32_bf16 v[24:27], v[148:151], v[180:183], v[24:27]
	v_mfma_f32_16x16x32_bf16 v[16:19], v[156:159], v[180:183], v[16:19]
	v_mfma_f32_16x16x32_bf16 v[8:11], v[148:151], v[188:191], v[8:11]
	v_mfma_f32_16x16x32_bf16 v[0:3], v[156:159], v[188:191], v[0:3]
	s_barrier
	s_setprio 0
	s_add_u32 s26, s26, 0x100
	s_addc_u32 s27, s27, 0
	s_add_u32 s59, s59, 0x100
	s_addc_u32 s60, s60, 0
	s_cmp_ge_i32 s61, s49
	s_cbranch_scc1 .LBB0_1365
.LBB0_1356:
	s_add_u32 s98, s26, 0xfff80000
	s_addc_u32 s99, s27, -1
	s_mov_b32 m0, s50
	s_nop 0
	global_load_lds_dwordx4 v198, s[98:99]
	s_mov_b32 m0, s51
	s_nop 0
	global_load_lds_dwordx4 v194, s[98:99]
	ds_read_b128 v[144:147], v223
	ds_read_b128 v[148:151], v223 offset:1024
	ds_read_b128 v[152:155], v223 offset:2048
	ds_read_b128 v[156:159], v223 offset:3072
	ds_read_b128 v[128:131], v224
	ds_read_b128 v[132:135], v224 offset:1024
	ds_read_b128 v[136:139], v224 offset:2048
	ds_read_b128 v[140:143], v224 offset:3072
	s_cmp_eq_u32 s52, s61
	s_cselect_b64 s[28:29], -1, 0
	s_cmp_lg_u32 s52, s61
	s_cselect_b64 s[34:35], -1, 0
	s_add_i32 m0, s40, 0xc000
	ds_read_b128 v[184:187], v225
	ds_read_b128 v[188:191], v225 offset:1024
	ds_read_b128 v[176:179], v225 offset:2048
	ds_read_b128 v[180:183], v225 offset:3072
	ds_read_b128 v[168:171], v225 offset:4096
	ds_read_b128 v[172:175], v225 offset:5120
	ds_read_b128 v[160:163], v225 offset:6144
	ds_read_b128 v[164:167], v225 offset:7168
	global_load_lds_dwordx4 v200, s[26:27]
	s_add_i32 m0, s40, 0xe000
	s_mov_b64 s[30:31], -1
	global_load_lds_dwordx4 v202, s[26:27]
	s_and_b64 vcc, exec, s[34:35]
	s_cbranch_vccz .LBB0_1358
	s_waitcnt vmcnt(8)
	s_mov_b64 s[30:31], 0

; #define PG8_STAGE(bufoff, gbase, voff) do { _Pragma("unroll") for (int _i = 0; _i < 2; ++_i) \
;         __builtin_amdgcn_global_load_lds((const unsigned*)((const char*)(gbase) + (voff)[_i]), (LAS unsigned*)(lds + (bufoff) + ldsw + _i * 8192), 16, 0, ((voff) == voffA ? AUXA : 0)); } while (0)
; #define PG8_LDA(dst, b, h) do { _Pragma("unroll") for (int m = 0; m < 4; ++m) _Pragma("unroll") for (int k = 0; k < 2; ++k) dst[m][k] = *(const LAS bf16x8*)(lds + PG8_SA(b, h) + aoff + m * 2048 + k * 1024); } while (0)
; #define PG8_MMA(ai, bj, At, Bt) do { __builtin_amdgcn_s_setprio(1); _Pragma("unroll") for (int m = 0; m < 4; ++m) _Pragma("unroll") for (int n = 0; n < 2; ++n) _Pragma("unroll") for (int k = 0; k < 2; ++k) \
;         acc[ai][bj][m][n] = __builtin_amdgcn_mfma_f32_16x16x32_bf16(Bt[n][k], At[m][k], acc[ai][bj][m][n], 0, 0, 0); __builtin_amdgcn_s_setprio(0); } while (0)
; #define PG8_WAIT_V(n) asm volatile("s_waitcnt vmcnt(" #n ")" ::: "memory")
; #define PG8_WAIT_L(n) asm volatile("s_waitcnt lgkmcnt(" #n ")" ::: "memory")
; #define PG8_BAR __builtin_amdgcn_s_barrier()
; #define PG8_SCHED __builtin_amdgcn_sched_barrier(0)
;     ...
;             if (Epi::NPRE != 0 && last) { E.pre(sv, cur, wr, fr); PG8_WAIT_V(16); } else { PG8_WAIT_V(8); }
;             PG8_WAIT_L(0); PG8_BAR; PG8_MMA(0, 0, At, B0); PG8_MMA(0, 1, At, B1); PG8_BAR; PG8_SCHED;
;             PG8_LDA(At, 0, 1); PG8_STAGE(PG8_SB(0, 0), b2, voffB); PG8_STAGE(PG8_SB(0, 1), b2 + hsB, voffB); PG8_STAGE(PG8_SA(0, 0), a2, voffA);
;             if (Epi::NPRE != 0 && last) { PG8_WAIT_V(16); } else { PG8_WAIT_V(8); }
;             PG8_WAIT_L(0); PG8_BAR; PG8_MMA(1, 0, At, B0); PG8_MMA(1, 1, At, B1); PG8_BAR; PG8_SCHED;
.LBB0_1360:
	s_add_u32 s30, s26, 0xfff80080
	s_addc_u32 s31, s27, -1
	s_waitcnt lgkmcnt(0)
	s_and_b64 s[28:29], s[28:29], exec
	s_cselect_b32 s31, s19, s31
	s_cselect_b32 s30, s21, s30
	s_cselect_b32 s29, s57, s60
	s_cselect_b32 s28, s58, s59
	s_setprio 1
	s_barrier
	v_mfma_f32_16x16x32_bf16 v[124:127], v[144:147], v[184:187], v[124:127]
	v_mfma_f32_16x16x32_bf16 v[116:119], v[152:155], v[184:187], v[116:119]
	v_mfma_f32_16x16x32_bf16 v[108:111], v[144:147], v[176:179], v[108:111]
	v_mfma_f32_16x16x32_bf16 v[100:103], v[152:155], v[176:179], v[100:103]
	v_mfma_f32_16x16x32_bf16 v[92:95], v[144:147], v[168:171], v[92:95]
	v_mfma_f32_16x16x32_bf16 v[84:87], v[152:155], v[168:171], v[84:87]
	v_mfma_f32_16x16x32_bf16 v[76:79], v[144:147], v[160:163], v[76:79]
	v_mfma_f32_16x16x32_bf16 v[68:71], v[152:155], v[160:163], v[68:71]
	v_mfma_f32_16x16x32_bf16 v[124:127], v[148:151], v[188:191], v[124:127]
	v_mfma_f32_16x16x32_bf16 v[116:119], v[156:159], v[188:191], v[116:119]
	v_mfma_f32_16x16x32_bf16 v[108:111], v[148:151], v[180:183], v[108:111]
	v_mfma_f32_16x16x32_bf16 v[100:103], v[156:159], v[180:183], v[100:103]
	v_mfma_f32_16x16x32_bf16 v[92:95], v[148:151], v[172:175], v[92:95]
	v_mfma_f32_16x16x32_bf16 v[84:87], v[156:159], v[172:175], v[84:87]
	v_mfma_f32_16x16x32_bf16 v[76:79], v[148:151], v[164:167], v[76:79]
	v_mfma_f32_16x16x32_bf16 v[68:71], v[156:159], v[164:167], v[68:71]
	v_mfma_f32_16x16x32_bf16 v[120:123], v[128:131], v[184:187], v[120:123]
	v_mfma_f32_16x16x32_bf16 v[112:115], v[136:139], v[184:187], v[112:115]
	v_mfma_f32_16x16x32_bf16 v[104:107], v[128:131], v[176:179], v[104:107]
	v_mfma_f32_16x16x32_bf16 v[96:99], v[136:139], v[176:179], v[96:99]
	v_mfma_f32_16x16x32_bf16 v[88:91], v[128:131], v[168:171], v[88:91]
	v_mfma_f32_16x16x32_bf16 v[80:83], v[136:139], v[168:171], v[80:83]
	v_mfma_f32_16x16x32_bf16 v[72:75], v[128:131], v[160:163], v[72:75]
	v_mfma_f32_16x16x32_bf16 v[64:67], v[136:139], v[160:163], v[64:67]
	v_mfma_f32_16x16x32_bf16 v[120:123], v[132:135], v[188:191], v[120:123]
	v_mfma_f32_16x16x32_bf16 v[112:115], v[140:143], v[188:191], v[112:115]
	v_mfma_f32_16x16x32_bf16 v[104:107], v[132:135], v[180:183], v[104:107]
	v_mfma_f32_16x16x32_bf16 v[96:99], v[140:143], v[180:183], v[96:99]
	v_mfma_f32_16x16x32_bf16 v[88:91], v[132:135], v[172:175], v[88:91]
	v_mfma_f32_16x16x32_bf16 v[80:83], v[140:143], v[172:175], v[80:83]
	v_mfma_f32_16x16x32_bf16 v[72:75], v[132:135], v[164:167], v[72:75]
	v_mfma_f32_16x16x32_bf16 v[64:67], v[140:143], v[164:167], v[64:67]
	s_barrier
	s_setprio 0
	s_add_u32 s98, s28, s14
	s_addc_u32 s99, s29, s15
	s_add_u32 s100, s30, s14
	s_addc_u32 s101, s31, s15
	s_mov_b32 m0, s41
	s_add_u32 s36, s28, 0x80000
	ds_read_b128 v[184:187], v225 offset:16384
	ds_read_b128 v[188:191], v225 offset:17408
	ds_read_b128 v[176:179], v225 offset:18432
	ds_read_b128 v[180:183], v225 offset:19456
	ds_read_b128 v[168:171], v225 offset:20480
	ds_read_b128 v[172:175], v225 offset:21504
	ds_read_b128 v[160:163], v225 offset:22528
	ds_read_b128 v[164:167], v225 offset:23552
	global_load_lds_dwordx4 v196, s[28:29]
	s_mov_b32 m0, s42
	s_addc_u32 s37, s29, 0
	global_load_lds_dwordx4 v192, s[28:29]
	s_mov_b32 m0, s43
	s_nop 0
	global_load_lds_dwordx4 v196, s[36:37]
	s_mov_b32 m0, s44
	s_nop 0
	global_load_lds_dwordx4 v192, s[36:37]
	s_mov_b64 s[36:37], -1
	s_and_b64 vcc, exec, s[34:35]
	s_cbranch_vccz .LBB0_1362
	s_waitcnt vmcnt(6)
	s_mov_b64 s[36:37], 0
.LBB0_1362:
	s_andn2_b64 vcc, exec, s[36:37]
	s_cbranch_vccnz .LBB0_1355
	s_waitcnt vmcnt(14)
	s_branch .LBB0_1355

; #define PG8_STAGE(bufoff, gbase, voff) do { _Pragma("unroll") for (int _i = 0; _i < 2; ++_i) \
;         __builtin_amdgcn_global_load_lds((const unsigned*)((const char*)(gbase) + (voff)[_i]), (LAS unsigned*)(lds + (bufoff) + ldsw + _i * 8192), 16, 0, ((voff) == voffA ? AUXA : 0)); } while (0)
; #define PG8_LDA(dst, b, h) do { _Pragma("unroll") for (int m = 0; m < 4; ++m) _Pragma("unroll") for (int k = 0; k < 2; ++k) dst[m][k] = *(const LAS bf16x8*)(lds + PG8_SA(b, h) + aoff + m * 2048 + k * 1024); } while (0)
; #define PG8_LDB(dst, b, h) do { _Pragma("unroll") for (int n = 0; n < 2; ++n) _Pragma("unroll") for (int k = 0; k < 2; ++k) dst[n][k] = *(const LAS bf16x8*)(lds + PG8_SB(b, h) + boff + n * 2048 + k * 1024); } while (0)
; #define PG8_MMA(ai, bj, At, Bt) do { __builtin_amdgcn_s_setprio(1); _Pragma("unroll") for (int m = 0; m < 4; ++m) _Pragma("unroll") for (int n = 0; n < 2; ++n) _Pragma("unroll") for (int k = 0; k < 2; ++k) \
;         acc[ai][bj][m][n] = __builtin_amdgcn_mfma_f32_16x16x32_bf16(Bt[n][k], At[m][k], acc[ai][bj][m][n], 0, 0, 0); __builtin_amdgcn_s_setprio(0); } while (0)
; #define PG8_WAIT_V(n) asm volatile("s_waitcnt vmcnt(" #n ")" ::: "memory")
; #define PG8_WAIT_L(n) asm volatile("s_waitcnt lgkmcnt(" #n ")" ::: "memory")
; #define PG8_BAR __builtin_amdgcn_s_barrier()
; #define PG8_SCHED __builtin_amdgcn_sched_barrier(0)
;     ...
;             const bool last = (t == nt - 2);
;             const char* a1 = cA + (size_t)(t + 1) * kstep;
;             const char* a2 = last ? nA : cA + (size_t)(t + 2) * kstep; const char* b2 = last ? nB : cB + (size_t)(t + 2) * kstep;
;             const char* a3 = a2 + kstep; const char* b3 = b2 + kstep;
;             PG8_LDB(B0, 0, 0); PG8_LDB(B1, 0, 1); PG8_SCHED; PG8_LDA(At, 0, 0); PG8_STAGE(PG8_SA(1, 1), a1 + hsA, voffA);
;             if (Epi::NPRE != 0 && last) { E.pre(sv, cur, wr, fr); PG8_WAIT_V(16); } else { PG8_WAIT_V(8); }
;             PG8_WAIT_L(0); PG8_BAR; PG8_MMA(0, 0, At, B0); PG8_MMA(0, 1, At, B1); PG8_BAR; PG8_SCHED;
;             PG8_LDA(At, 0, 1); PG8_STAGE(PG8_SB(0, 0), b2, voffB); PG8_STAGE(PG8_SB(0, 1), b2 + hsB, voffB); PG8_STAGE(PG8_SA(0, 0), a2, voffA);
;             if (Epi::NPRE != 0 && last) { PG8_WAIT_V(16); } else { PG8_WAIT_V(8); }
;             PG8_WAIT_L(0); PG8_BAR; PG8_MMA(1, 0, At, B0); PG8_MMA(1, 1, At, B1); PG8_BAR; PG8_SCHED;
.LBB0_1440:
	s_add_u32 s98, s16, 0xffea0000
	s_addc_u32 s99, s17, -1
	s_mov_b32 m0, s34
	s_nop 0
	global_load_lds_dwordx4 v134, s[98:99]
	s_mov_b32 m0, s35
	s_nop 0
	global_load_lds_dwordx4 v130, s[98:99]
	ds_read_b128 v[144:147], v159
	ds_read_b128 v[148:151], v159 offset:1024
	ds_read_b128 v[152:155], v159 offset:2048
	ds_read_b128 v[162:165], v159 offset:3072
	ds_read_b128 v[166:169], v160
	ds_read_b128 v[170:173], v160 offset:1024
	ds_read_b128 v[174:177], v160 offset:2048
	ds_read_b128 v[178:181], v160 offset:3072
	s_add_i32 s46, s18, 2
	s_add_u32 s19, s16, 0xffea0080
	s_addc_u32 s20, s17, -1
	s_cmp_eq_u32 s36, s18
	s_cselect_b32 s18, s14, s44
	s_cselect_b32 s21, s5, s20
	s_cselect_b32 s20, s4, s19
	s_cselect_b32 s19, s15, s45
	s_add_i32 m0, s26, 0xc000
	ds_read_b128 v[182:185], v161
	ds_read_b128 v[186:189], v161 offset:1024
	ds_read_b128 v[190:193], v161 offset:2048
	ds_read_b128 v[194:197], v161 offset:3072
	ds_read_b128 v[198:201], v161 offset:4096
	ds_read_b128 v[202:205], v161 offset:5120
	ds_read_b128 v[206:209], v161 offset:6144
	ds_read_b128 v[210:213], v161 offset:7168
	global_load_lds_dwordx4 v136, s[16:17]
	s_add_i32 m0, s26, 0xe000
	s_nop 0
	global_load_lds_dwordx4 v138, s[16:17]
	s_waitcnt vmcnt(8)
	s_waitcnt lgkmcnt(0)
	s_setprio 1
	s_barrier
	v_mfma_f32_16x16x32_bf16 v[124:127], v[144:147], v[182:185], v[124:127]
	v_mfma_f32_16x16x32_bf16 v[120:123], v[152:155], v[182:185], v[120:123]
	v_mfma_f32_16x16x32_bf16 v[116:119], v[144:147], v[190:193], v[116:119]
	v_mfma_f32_16x16x32_bf16 v[112:115], v[152:155], v[190:193], v[112:115]
	v_mfma_f32_16x16x32_bf16 v[104:107], v[144:147], v[198:201], v[104:107]
	v_mfma_f32_16x16x32_bf16 v[96:99], v[152:155], v[198:201], v[96:99]
	v_mfma_f32_16x16x32_bf16 v[88:91], v[144:147], v[206:209], v[88:91]
	v_mfma_f32_16x16x32_bf16 v[80:83], v[152:155], v[206:209], v[80:83]
	v_mfma_f32_16x16x32_bf16 v[124:127], v[148:151], v[186:189], v[124:127]
	v_mfma_f32_16x16x32_bf16 v[120:123], v[162:165], v[186:189], v[120:123]
	v_mfma_f32_16x16x32_bf16 v[116:119], v[148:151], v[194:197], v[116:119]
	v_mfma_f32_16x16x32_bf16 v[112:115], v[162:165], v[194:197], v[112:115]
	v_mfma_f32_16x16x32_bf16 v[104:107], v[148:151], v[202:205], v[104:107]
	v_mfma_f32_16x16x32_bf16 v[96:99], v[162:165], v[202:205], v[96:99]
	v_mfma_f32_16x16x32_bf16 v[88:91], v[148:151], v[210:213], v[88:91]
	v_mfma_f32_16x16x32_bf16 v[80:83], v[162:165], v[210:213], v[80:83]
	v_mfma_f32_16x16x32_bf16 v[108:111], v[166:169], v[182:185], v[108:111]
	v_mfma_f32_16x16x32_bf16 v[100:103], v[174:177], v[182:185], v[100:103]
	v_mfma_f32_16x16x32_bf16 v[92:95], v[166:169], v[190:193], v[92:95]
	v_mfma_f32_16x16x32_bf16 v[84:87], v[174:177], v[190:193], v[84:87]
	v_mfma_f32_16x16x32_bf16 v[76:79], v[166:169], v[198:201], v[76:79]
	v_mfma_f32_16x16x32_bf16 v[72:75], v[174:177], v[198:201], v[72:75]
	v_mfma_f32_16x16x32_bf16 v[68:71], v[166:169], v[206:209], v[68:71]
	v_mfma_f32_16x16x32_bf16 v[64:67], v[174:177], v[206:209], v[64:67]
	v_mfma_f32_16x16x32_bf16 v[108:111], v[170:173], v[186:189], v[108:111]
	v_mfma_f32_16x16x32_bf16 v[100:103], v[178:181], v[186:189], v[100:103]
	v_mfma_f32_16x16x32_bf16 v[92:95], v[170:173], v[194:197], v[92:95]
	v_mfma_f32_16x16x32_bf16 v[84:87], v[178:181], v[194:197], v[84:87]
	v_mfma_f32_16x16x32_bf16 v[76:79], v[170:173], v[202:205], v[76:79]
	v_mfma_f32_16x16x32_bf16 v[72:75], v[178:181], v[202:205], v[72:75]
	v_mfma_f32_16x16x32_bf16 v[68:71], v[170:173], v[210:213], v[68:71]
	v_mfma_f32_16x16x32_bf16 v[64:67], v[178:181], v[210:213], v[64:67]
	s_barrier
	s_setprio 0
	s_add_u32 s98, s18, s8
	s_addc_u32 s99, s19, s9
	s_add_u32 s100, s20, s8
	s_addc_u32 s101, s21, s9
	s_add_i32 s47, s38, s23
	s_mov_b32 m0, s47
	ds_read_b128 v[182:185], v161 offset:16384
	ds_read_b128 v[186:189], v161 offset:17408
	ds_read_b128 v[190:193], v161 offset:18432
	ds_read_b128 v[194:197], v161 offset:19456
	ds_read_b128 v[198:201], v161 offset:20480
	ds_read_b128 v[202:205], v161 offset:21504
	ds_read_b128 v[206:209], v161 offset:22528
	ds_read_b128 v[210:213], v161 offset:23552
	global_load_lds_dwordx4 v132, s[18:19]
	s_add_i32 m0, s47, 0x2000
	s_add_u32 s48, s18, 0x160000
	s_addc_u32 s49, s19, 0
	s_add_i32 s47, s39, s23
	global_load_lds_dwordx4 v128, s[18:19]
	s_mov_b32 m0, s47
	s_nop 0
	global_load_lds_dwordx4 v132, s[48:49]
	s_add_i32 m0, s47, 0x2000
	s_nop 0
	global_load_lds_dwordx4 v128, s[48:49]
	s_waitcnt vmcnt(6)
	s_waitcnt lgkmcnt(0)
	s_setprio 1
	s_barrier
	v_mfma_f32_16x16x32_bf16 v[60:63], v[144:147], v[182:185], v[60:63]
	v_mfma_f32_16x16x32_bf16 v[56:59], v[152:155], v[182:185], v[56:59]
	v_mfma_f32_16x16x32_bf16 v[52:55], v[144:147], v[190:193], v[52:55]
	v_mfma_f32_16x16x32_bf16 v[48:51], v[152:155], v[190:193], v[48:51]
	v_mfma_f32_16x16x32_bf16 v[40:43], v[144:147], v[198:201], v[40:43]
	v_mfma_f32_16x16x32_bf16 v[32:35], v[152:155], v[198:201], v[32:35]
	v_mfma_f32_16x16x32_bf16 v[24:27], v[144:147], v[206:209], v[24:27]
	v_mfma_f32_16x16x32_bf16 v[16:19], v[152:155], v[206:209], v[16:19]
	v_mfma_f32_16x16x32_bf16 v[60:63], v[148:151], v[186:189], v[60:63]
	v_mfma_f32_16x16x32_bf16 v[56:59], v[162:165], v[186:189], v[56:59]
	v_mfma_f32_16x16x32_bf16 v[52:55], v[148:151], v[194:197], v[52:55]
	v_mfma_f32_16x16x32_bf16 v[48:51], v[162:165], v[194:197], v[48:51]
	v_mfma_f32_16x16x32_bf16 v[40:43], v[148:151], v[202:205], v[40:43]
	v_mfma_f32_16x16x32_bf16 v[32:35], v[162:165], v[202:205], v[32:35]
	v_mfma_f32_16x16x32_bf16 v[24:27], v[148:151], v[210:213], v[24:27]
	v_mfma_f32_16x16x32_bf16 v[16:19], v[162:165], v[210:213], v[16:19]
	v_mfma_f32_16x16x32_bf16 v[44:47], v[166:169], v[182:185], v[44:47]
	v_mfma_f32_16x16x32_bf16 v[36:39], v[174:177], v[182:185], v[36:39]
	v_mfma_f32_16x16x32_bf16 v[28:31], v[166:169], v[190:193], v[28:31]
	v_mfma_f32_16x16x32_bf16 v[20:23], v[174:177], v[190:193], v[20:23]
	v_mfma_f32_16x16x32_bf16 v[12:15], v[166:169], v[198:201], v[12:15]
	v_mfma_f32_16x16x32_bf16 v[8:11], v[174:177], v[198:201], v[8:11]
	v_mfma_f32_16x16x32_bf16 v[4:7], v[166:169], v[206:209], v[4:7]
	v_mfma_f32_16x16x32_bf16 v[0:3], v[174:177], v[206:209], v[0:3]
	v_mfma_f32_16x16x32_bf16 v[44:47], v[170:173], v[186:189], v[44:47]
	v_mfma_f32_16x16x32_bf16 v[36:39], v[178:181], v[186:189], v[36:39]
	v_mfma_f32_16x16x32_bf16 v[28:31], v[170:173], v[194:197], v[28:31]
	v_mfma_f32_16x16x32_bf16 v[20:23], v[178:181], v[194:197], v[20:23]
	v_mfma_f32_16x16x32_bf16 v[12:15], v[170:173], v[202:205], v[12:15]
	v_mfma_f32_16x16x32_bf16 v[8:11], v[178:181], v[202:205], v[8:11]
	v_mfma_f32_16x16x32_bf16 v[4:7], v[170:173], v[210:213], v[4:7]
	v_mfma_f32_16x16x32_bf16 v[0:3], v[178:181], v[210:213], v[0:3]
	s_barrier
; #define PG8_STAGE(bufoff, gbase, voff) do { _Pragma("unroll") for (int _i = 0; _i < 2; ++_i) \
;         __builtin_amdgcn_global_load_lds((const unsigned*)((const char*)(gbase) + (voff)[_i]), (LAS unsigned*)(lds + (bufoff) + ldsw + _i * 8192), 16, 0, ((voff) == voffA ? AUXA : 0)); } while (0)
; #define PG8_LDA(dst, b, h) do { _Pragma("unroll") for (int m = 0; m < 4; ++m) _Pragma("unroll") for (int k = 0; k < 2; ++k) dst[m][k] = *(const LAS bf16x8*)(lds + PG8_SA(b, h) + aoff + m * 2048 + k * 1024); } while (0)
; #define PG8_LDB(dst, b, h) do { _Pragma("unroll") for (int n = 0; n < 2; ++n) _Pragma("unroll") for (int k = 0; k < 2; ++k) dst[n][k] = *(const LAS bf16x8*)(lds + PG8_SB(b, h) + boff + n * 2048 + k * 1024); } while (0)
; #define PG8_MMA(ai, bj, At, Bt) do { __builtin_amdgcn_s_setprio(1); _Pragma("unroll") for (int m = 0; m < 4; ++m) _Pragma("unroll") for (int n = 0; n < 2; ++n) _Pragma("unroll") for (int k = 0; k < 2; ++k) \
;         acc[ai][bj][m][n] = __builtin_amdgcn_mfma_f32_16x16x32_bf16(Bt[n][k], At[m][k], acc[ai][bj][m][n], 0, 0, 0); __builtin_amdgcn_s_setprio(0); } while (0)
; #define PG8_WAIT_V(n) asm volatile("s_waitcnt vmcnt(" #n ")" ::: "memory")
; #define PG8_WAIT_L(n) asm volatile("s_waitcnt lgkmcnt(" #n ")" ::: "memory")
; #define PG8_BAR __builtin_amdgcn_s_barrier()
; #define PG8_SCHED __builtin_amdgcn_sched_barrier(0)
;     ...
;             PG8_LDB(B0, 1, 0); PG8_LDB(B1, 1, 1); PG8_SCHED; PG8_LDA(At, 1, 0); PG8_STAGE(PG8_SA(0, 1), a2 + hsA, voffA);
;             PG8_WAIT_V(8); PG8_WAIT_L(0); PG8_BAR; PG8_MMA(0, 0, At, B0); PG8_MMA(0, 1, At, B1); PG8_BAR; PG8_SCHED;
;             PG8_LDA(At, 1, 1); PG8_STAGE(PG8_SB(1, 0), b3, voffB); PG8_STAGE(PG8_SB(1, 1), b3 + hsB, voffB); PG8_STAGE(PG8_SA(1, 0), a3, voffA);
	s_mov_b32 m0, s26
	s_nop 0
	global_load_lds_dwordx4 v134, s[20:21]
	s_mov_b32 m0, s27
	s_nop 0
	global_load_lds_dwordx4 v130, s[20:21]
	s_setprio 0
	s_add_i32 s47, 0, 0x18000
	s_add_i32 s48, 0, 0x1c000
	v_add_u32_e32 v162, s47, v157
	v_add_u32_e32 v178, s48, v157
	ds_read_b128 v[144:147], v162
	ds_read_b128 v[148:151], v162 offset:1024
	ds_read_b128 v[152:155], v162 offset:2048
	ds_read_b128 v[162:165], v162 offset:3072
	ds_read_b128 v[166:169], v178
	ds_read_b128 v[170:173], v178 offset:1024
	ds_read_b128 v[174:177], v178 offset:2048
	ds_read_b128 v[178:181], v178 offset:3072
	s_add_u32 s20, s20, 0x160000
	s_addc_u32 s21, s21, 0
	s_mov_b32 m0, s28
	ds_read_b128 v[182:185], v161 offset:32768
	ds_read_b128 v[186:189], v161 offset:33792
	ds_read_b128 v[190:193], v161 offset:34816
	ds_read_b128 v[194:197], v161 offset:35840
	ds_read_b128 v[198:201], v161 offset:36864
	ds_read_b128 v[202:205], v161 offset:37888
	ds_read_b128 v[206:209], v161 offset:38912
	ds_read_b128 v[210:213], v161 offset:39936
	global_load_lds_dwordx4 v134, s[20:21]
	s_mov_b32 m0, s29
	s_nop 0
	global_load_lds_dwordx4 v130, s[20:21]
	s_waitcnt vmcnt(8)
	s_waitcnt lgkmcnt(0)
	s_setprio 1
	s_barrier
	v_mfma_f32_16x16x32_bf16 v[124:127], v[144:147], v[182:185], v[124:127]
	v_mfma_f32_16x16x32_bf16 v[120:123], v[152:155], v[182:185], v[120:123]
	v_mfma_f32_16x16x32_bf16 v[116:119], v[144:147], v[190:193], v[116:119]
	v_mfma_f32_16x16x32_bf16 v[112:115], v[152:155], v[190:193], v[112:115]
	v_mfma_f32_16x16x32_bf16 v[104:107], v[144:147], v[198:201], v[104:107]
	v_mfma_f32_16x16x32_bf16 v[96:99], v[152:155], v[198:201], v[96:99]
	v_mfma_f32_16x16x32_bf16 v[88:91], v[144:147], v[206:209], v[88:91]
	v_mfma_f32_16x16x32_bf16 v[80:83], v[152:155], v[206:209], v[80:83]
	v_mfma_f32_16x16x32_bf16 v[124:127], v[148:151], v[186:189], v[124:127]
	v_mfma_f32_16x16x32_bf16 v[120:123], v[162:165], v[186:189], v[120:123]
	v_mfma_f32_16x16x32_bf16 v[116:119], v[148:151], v[194:197], v[116:119]
	v_mfma_f32_16x16x32_bf16 v[112:115], v[162:165], v[194:197], v[112:115]
	v_mfma_f32_16x16x32_bf16 v[104:107], v[148:151], v[202:205], v[104:107]
	v_mfma_f32_16x16x32_bf16 v[96:99], v[162:165], v[202:205], v[96:99]
	v_mfma_f32_16x16x32_bf16 v[88:91], v[148:151], v[210:213], v[88:91]
	v_mfma_f32_16x16x32_bf16 v[80:83], v[162:165], v[210:213], v[80:83]
	v_mfma_f32_16x16x32_bf16 v[108:111], v[166:169], v[182:185], v[108:111]
	v_mfma_f32_16x16x32_bf16 v[100:103], v[174:177], v[182:185], v[100:103]
	v_mfma_f32_16x16x32_bf16 v[92:95], v[166:169], v[190:193], v[92:95]
	v_mfma_f32_16x16x32_bf16 v[84:87], v[174:177], v[190:193], v[84:87]
	v_mfma_f32_16x16x32_bf16 v[76:79], v[166:169], v[198:201], v[76:79]
	v_mfma_f32_16x16x32_bf16 v[72:75], v[174:177], v[198:201], v[72:75]
	v_mfma_f32_16x16x32_bf16 v[68:71], v[166:169], v[206:209], v[68:71]
	v_mfma_f32_16x16x32_bf16 v[64:67], v[174:177], v[206:209], v[64:67]
	v_mfma_f32_16x16x32_bf16 v[108:111], v[170:173], v[186:189], v[108:111]
	v_mfma_f32_16x16x32_bf16 v[100:103], v[178:181], v[186:189], v[100:103]
	v_mfma_f32_16x16x32_bf16 v[92:95], v[170:173], v[194:197], v[92:95]
	v_mfma_f32_16x16x32_bf16 v[84:87], v[178:181], v[194:197], v[84:87]
	v_mfma_f32_16x16x32_bf16 v[76:79], v[170:173], v[202:205], v[76:79]
	v_mfma_f32_16x16x32_bf16 v[72:75], v[178:181], v[202:205], v[72:75]
	v_mfma_f32_16x16x32_bf16 v[68:71], v[170:173], v[210:213], v[68:71]
	v_mfma_f32_16x16x32_bf16 v[64:67], v[178:181], v[210:213], v[64:67]
	s_barrier
	s_setprio 0
	s_add_i32 s20, s47, s23
	s_mov_b32 m0, s20
	ds_read_b128 v[182:185], v161 offset:49152
	ds_read_b128 v[186:189], v161 offset:50176
	ds_read_b128 v[190:193], v161 offset:51200
	ds_read_b128 v[194:197], v161 offset:52224
	ds_read_b128 v[198:201], v161 offset:53248
	ds_read_b128 v[202:205], v161 offset:54272
	ds_read_b128 v[206:209], v161 offset:55296
	ds_read_b128 v[210:213], v161 offset:56320
	global_load_lds_dwordx4 v132, s[98:99]
	s_add_i32 m0, s20, 0x2000
	s_add_u32 s18, s18, 0x160080
	s_addc_u32 s19, s19, 0
	s_add_i32 s20, s48, s23
	global_load_lds_dwordx4 v128, s[98:99]
	s_mov_b32 m0, s20
	s_nop 0
	global_load_lds_dwordx4 v132, s[18:19]
	s_add_i32 m0, s20, 0x2000
	s_nop 0
	global_load_lds_dwordx4 v128, s[18:19]
	s_waitcnt vmcnt(6)
	s_waitcnt lgkmcnt(0)
	s_setprio 1
	s_barrier
; #define PG8_MMA(ai, bj, At, Bt) do { __builtin_amdgcn_s_setprio(1); _Pragma("unroll") for (int m = 0; m < 4; ++m) _Pragma("unroll") for (int n = 0; n < 2; ++n) _Pragma("unroll") for (int k = 0; k < 2; ++k) \
;         acc[ai][bj][m][n] = __builtin_amdgcn_mfma_f32_16x16x32_bf16(Bt[n][k], At[m][k], acc[ai][bj][m][n], 0, 0, 0); __builtin_amdgcn_s_setprio(0); } while (0)
; #define PG8_WAIT_V(n) asm volatile("s_waitcnt vmcnt(" #n ")" ::: "memory")
; #define PG8_WAIT_L(n) asm volatile("s_waitcnt lgkmcnt(" #n ")" ::: "memory")
; #define PG8_BAR __builtin_amdgcn_s_barrier()
; #define PG8_SCHED __builtin_amdgcn_sched_barrier(0)
;     ...
;             PG8_WAIT_V(8); PG8_WAIT_L(0); PG8_BAR; PG8_MMA(1, 0, At, B0); PG8_MMA(1, 1, At, B1); PG8_BAR; PG8_SCHED;
;         }
;     __device__ __forceinline__ void operator()(const Acc& acc, const Unit& u, int wr, int wc, int fr, int fq, const float (&sv8)[8]) const {
;     ...
;                 for (int bj = 0; bj < 2; ++bj) {
;                     const int col = colb + bj * 128;
;                     const f32x4 y0 = xr[m][bj][0] + acc[ai][bj][m][0] * scale, y1 = xr[m][bj][1] + acc[ai][bj][m][1] * scale;
	v_mfma_f32_16x16x32_bf16 v[60:63], v[144:147], v[182:185], v[60:63]
	v_mfma_f32_16x16x32_bf16 v[56:59], v[152:155], v[182:185], v[56:59]
	v_mfma_f32_16x16x32_bf16 v[52:55], v[144:147], v[190:193], v[52:55]
	v_mfma_f32_16x16x32_bf16 v[48:51], v[152:155], v[190:193], v[48:51]
	v_mfma_f32_16x16x32_bf16 v[40:43], v[144:147], v[198:201], v[40:43]
	v_mfma_f32_16x16x32_bf16 v[32:35], v[152:155], v[198:201], v[32:35]
	v_mfma_f32_16x16x32_bf16 v[24:27], v[144:147], v[206:209], v[24:27]
	v_mfma_f32_16x16x32_bf16 v[16:19], v[152:155], v[206:209], v[16:19]
	v_mfma_f32_16x16x32_bf16 v[60:63], v[148:151], v[186:189], v[60:63]
	v_mfma_f32_16x16x32_bf16 v[56:59], v[162:165], v[186:189], v[56:59]
	v_mfma_f32_16x16x32_bf16 v[52:55], v[148:151], v[194:197], v[52:55]
	v_mfma_f32_16x16x32_bf16 v[48:51], v[162:165], v[194:197], v[48:51]
	v_mfma_f32_16x16x32_bf16 v[40:43], v[148:151], v[202:205], v[40:43]
	v_mfma_f32_16x16x32_bf16 v[32:35], v[162:165], v[202:205], v[32:35]
	v_mfma_f32_16x16x32_bf16 v[24:27], v[148:151], v[210:213], v[24:27]
	v_mfma_f32_16x16x32_bf16 v[16:19], v[162:165], v[210:213], v[16:19]
	v_mfma_f32_16x16x32_bf16 v[44:47], v[166:169], v[182:185], v[44:47]
	v_mfma_f32_16x16x32_bf16 v[36:39], v[174:177], v[182:185], v[36:39]
	v_mfma_f32_16x16x32_bf16 v[28:31], v[166:169], v[190:193], v[28:31]
	v_mfma_f32_16x16x32_bf16 v[20:23], v[174:177], v[190:193], v[20:23]
	v_mfma_f32_16x16x32_bf16 v[12:15], v[166:169], v[198:201], v[12:15]
	v_mfma_f32_16x16x32_bf16 v[8:11], v[174:177], v[198:201], v[8:11]
	v_mfma_f32_16x16x32_bf16 v[4:7], v[166:169], v[206:209], v[4:7]
	v_mfma_f32_16x16x32_bf16 v[0:3], v[174:177], v[206:209], v[0:3]
	v_mfma_f32_16x16x32_bf16 v[44:47], v[170:173], v[186:189], v[44:47]
	v_mfma_f32_16x16x32_bf16 v[36:39], v[178:181], v[186:189], v[36:39]
	v_mfma_f32_16x16x32_bf16 v[28:31], v[170:173], v[194:197], v[28:31]
	v_mfma_f32_16x16x32_bf16 v[20:23], v[178:181], v[194:197], v[20:23]
	v_mfma_f32_16x16x32_bf16 v[12:15], v[170:173], v[202:205], v[12:15]
	v_mfma_f32_16x16x32_bf16 v[8:11], v[178:181], v[202:205], v[8:11]
	v_mfma_f32_16x16x32_bf16 v[4:7], v[170:173], v[210:213], v[4:7]
	v_mfma_f32_16x16x32_bf16 v[0:3], v[178:181], v[210:213], v[0:3]
	s_barrier
	s_setprio 0
	s_add_u32 s16, s16, 0x100
	s_addc_u32 s17, s17, 0
	s_add_u32 s44, s44, 0x100
	s_addc_u32 s45, s45, 0
	s_cmp_ge_i32 s46, s31
	s_mov_b32 s18, s46
	s_cbranch_scc0 .LBB0_1440
	v_pk_mul_f32 v[126:127], v[126:127], 0.5 op_sel_hi:[1,0]
	v_pk_mul_f32 v[146:147], v[124:125], 0.5 op_sel_hi:[1,0]
	v_pk_mul_f32 v[144:145], v[122:123], 0.5 op_sel_hi:[1,0]
	v_pk_mul_f32 v[124:125], v[120:121], 0.5 op_sel_hi:[1,0]
	v_pk_mul_f32 v[154:155], v[110:111], 0.5 op_sel_hi:[1,0]
	v_pk_mul_f32 v[152:153], v[108:109], 0.5 op_sel_hi:[1,0]
	v_pk_mul_f32 v[150:151], v[102:103], 0.5 op_sel_hi:[1,0]
	v_pk_mul_f32 v[148:149], v[100:101], 0.5 op_sel_hi:[1,0]
	v_pk_mul_f32 v[118:119], v[118:119], 0.5 op_sel_hi:[1,0]
	v_pk_mul_f32 v[116:117], v[116:117], 0.5 op_sel_hi:[1,0]
	v_pk_mul_f32 v[110:111], v[114:115], 0.5 op_sel_hi:[1,0]
	v_pk_mul_f32 v[108:109], v[112:113], 0.5 op_sel_hi:[1,0]
	v_pk_mul_f32 v[122:123], v[94:95], 0.5 op_sel_hi:[1,0]
	v_pk_mul_f32 v[120:121], v[92:93], 0.5 op_sel_hi:[1,0]
	v_pk_mul_f32 v[114:115], v[86:87], 0.5 op_sel_hi:[1,0]
	v_pk_mul_f32 v[112:113], v[84:85], 0.5 op_sel_hi:[1,0]
	v_pk_mul_f32 v[102:103], v[106:107], 0.5 op_sel_hi:[1,0]
	v_pk_mul_f32 v[100:101], v[104:105], 0.5 op_sel_hi:[1,0]
	v_pk_mul_f32 v[94:95], v[98:99], 0.5 op_sel_hi:[1,0]
	v_pk_mul_f32 v[92:93], v[96:97], 0.5 op_sel_hi:[1,0]
	v_pk_mul_f32 v[106:107], v[78:79], 0.5 op_sel_hi:[1,0]
	v_pk_mul_f32 v[104:105], v[76:77], 0.5 op_sel_hi:[1,0]
	v_pk_mul_f32 v[98:99], v[74:75], 0.5 op_sel_hi:[1,0]
	v_pk_mul_f32 v[96:97], v[72:73], 0.5 op_sel_hi:[1,0]
	v_pk_mul_f32 v[86:87], v[90:91], 0.5 op_sel_hi:[1,0]
	v_pk_mul_f32 v[84:85], v[88:89], 0.5 op_sel_hi:[1,0]
	v_pk_mul_f32 v[78:79], v[82:83], 0.5 op_sel_hi:[1,0]
	v_pk_mul_f32 v[76:77], v[80:81], 0.5 op_sel_hi:[1,0]
	v_pk_mul_f32 v[90:91], v[70:71], 0.5 op_sel_hi:[1,0]
	v_pk_mul_f32 v[88:89], v[68:69], 0.5 op_sel_hi:[1,0]
	v_pk_mul_f32 v[82:83], v[66:67], 0.5 op_sel_hi:[1,0]
	v_pk_mul_f32 v[80:81], v[64:65], 0.5 op_sel_hi:[1,0]
	v_pk_mul_f32 v[66:67], v[62:63], 0.5 op_sel_hi:[1,0]
	v_pk_mul_f32 v[64:65], v[60:61], 0.5 op_sel_hi:[1,0]
	v_pk_mul_f32 v[62:63], v[58:59], 0.5 op_sel_hi:[1,0]
	v_pk_mul_f32 v[60:61], v[56:57], 0.5 op_sel_hi:[1,0]
	v_pk_mul_f32 v[74:75], v[46:47], 0.5 op_sel_hi:[1,0]
	v_pk_mul_f32 v[72:73], v[44:45], 0.5 op_sel_hi:[1,0]
	v_pk_mul_f32 v[70:71], v[38:39], 0.5 op_sel_hi:[1,0]
	v_pk_mul_f32 v[68:69], v[36:37], 0.5 op_sel_hi:[1,0]
	v_pk_mul_f32 v[54:55], v[54:55], 0.5 op_sel_hi:[1,0]
	v_pk_mul_f32 v[52:53], v[52:53], 0.5 op_sel_hi:[1,0]
	v_pk_mul_f32 v[46:47], v[50:51], 0.5 op_sel_hi:[1,0]
	v_pk_mul_f32 v[44:45], v[48:49], 0.5 op_sel_hi:[1,0]
	v_pk_mul_f32 v[58:59], v[30:31], 0.5 op_sel_hi:[1,0]
	v_pk_mul_f32 v[56:57], v[28:29], 0.5 op_sel_hi:[1,0]
	v_pk_mul_f32 v[50:51], v[22:23], 0.5 op_sel_hi:[1,0]
	v_pk_mul_f32 v[48:49], v[20:21], 0.5 op_sel_hi:[1,0]
	v_pk_mul_f32 v[30:31], v[42:43], 0.5 op_sel_hi:[1,0]
	v_pk_mul_f32 v[28:29], v[40:41], 0.5 op_sel_hi:[1,0]
	v_pk_mul_f32 v[22:23], v[34:35], 0.5 op_sel_hi:[1,0]
	v_pk_mul_f32 v[20:21], v[32:33], 0.5 op_sel_hi:[1,0]
	v_pk_mul_f32 v[38:39], v[14:15], 0.5 op_sel_hi:[1,0]
	v_pk_mul_f32 v[36:37], v[12:13], 0.5 op_sel_hi:[1,0]
	v_pk_mul_f32 v[34:35], v[10:11], 0.5 op_sel_hi:[1,0]
	v_pk_mul_f32 v[32:33], v[8:9], 0.5 op_sel_hi:[1,0]
	v_pk_mul_f32 v[14:15], v[26:27], 0.5 op_sel_hi:[1,0]
	v_pk_mul_f32 v[12:13], v[24:25], 0.5 op_sel_hi:[1,0]
	v_pk_mul_f32 v[10:11], v[18:19], 0.5 op_sel_hi:[1,0]
	v_pk_mul_f32 v[8:9], v[16:17], 0.5 op_sel_hi:[1,0]
	v_pk_mul_f32 v[6:7], v[6:7], 0.5 op_sel_hi:[1,0]
	v_pk_mul_f32 v[4:5], v[4:5], 0.5 op_sel_hi:[1,0]
	v_pk_mul_f32 v[2:3], v[2:3], 0.5 op_sel_hi:[1,0]
	v_pk_mul_f32 v[0:1], v[0:1], 0.5 op_sel_hi:[1,0]
